# H3 pass and its grid barrier removed: V phase stores un-normalised bf16 h3 (x2*g_ple), P6 epilogue applies rsqrt(ssq/1024+eps) to the gate accumulator before the sigmoid
# speedup vs baseline: 1.0047x; 1.0040x over previous
; #define P5_LOAD(A, TAB, j0)                                                                \
;   _Pragma("unroll") for (int q = 0; q < 16; q++) {                                         \
;     A[q] = ((const uint4*)((TAB) + (size_t)widx[(j0) + q] * 1024))[lane];                  \
;   }
; __device__ __forceinline__ void phase5(const Params& p, char* smem, const bool store_x = true) {
;     ...
;     float2v o2[8];
; #pragma unroll
;     for (int i = 0; i < 8; i++) o2[i] = float2v{0.f, 0.f};
; #pragma unroll 1
;     for (int j0 = 0; j0 < 128; j0 += 32) {
;       P5_LOAD(A1, EV, j0 + 16)
;       P5_COMPUTE_V(A0, j0)
;       if (j0 + 32 < 128) { P5_LOAD(A0, EV, j0 + 32) }
;       P5_COMPUTE_V(A1, j0 + 16)
;     }
;     ...
;     unsigned hp[8];
; #pragma unroll
;     for (int i = 0; i < 4; i++) {
;       const float4 g = *(const float4*)(p.g_ple + lane * 16 + i * 4);
;       hp[2 * i] = pack2(x2[4 * i] * rs * g.x, x2[4 * i + 1] * rs * g.y);
;       hp[2 * i + 1] = pack2(x2[4 * i + 2] * rs * g.z, x2[4 * i + 3] * rs * g.w);
;     }
;     *(uint4*)(H3 + (size_t)tok * 1024 + lane * 16) = make_uint4(hp[0], hp[1], hp[2], hp[3]);
;     *(uint4*)(H3 + (size_t)tok * 1024 + lane * 16 + 8) = make_uint4(hp[4], hp[5], hp[6], hp[7]);
.Lp5v_start:
	v_mbcnt_lo_u32_b32 v0, -1, 0
	v_mbcnt_hi_u32_b32 v0, -1, v0
	v_accvgpr_read_b32 v4, a129
	s_and_b32 s0, s96, 7
	s_lshr_b32 s1, s96, 3
	v_and_b32_e32 v1, 7, v0
	v_lshrrev_b32_e32 v2, 3, v0
	v_lshlrev_b32_e32 v3, 1, v2
	v_lshl_add_u32 v3, v1, 4, v3
	v_lshlrev_b32_e32 v3, 2, v3
	v_lshlrev_b32_e32 v1, 4, v1
	v_lshlrev_b32_e32 v2, 6, v2
	v_readfirstlane_b32 s8, v4
	s_lshl_b32 s17, s8, 13
	v_add_u32_e32 v2, s17, v2
	s_lshl_b32 s10, s1, 2
	s_add_u32 s8, s8, s10
	s_lshr_b32 s9, s82, 1
	s_lshl_b32 s10, s0, 21
	s_add_u32 s2, s80, 0xbf35000
	s_addc_u32 s3, s81, 0
	s_add_u32 s2, s2, s10
	s_addc_u32 s3, s3, 0
	s_add_u32 s4, s80, 0x3bb5000
	s_addc_u32 s5, s81, 0
	s_lshl_b32 s10, s0, 9
	s_add_u32 s6, s78, s10
	s_addc_u32 s7, s79, 0
	s_movk_i32 s13, 0x41ff
	s_mov_b32 s14, 0xff00ff00
	s_mov_b32 s15, 0xff00ff00
	s_mov_b32 s16, 0
	s_mov_b32 s19, 0
	v_lshlrev_b32_e32 v9, 4, v0
	v_mov_b32_e32 v59, s5
	v_add_co_u32_e32 v58, vcc, s4, v9
	s_nop 1
	v_addc_co_u32_e32 v59, vcc, 0, v59, vcc
	s_mul_i32 s20, s9, 1
	s_mul_i32 s21, s9, 2
	s_mul_i32 s22, s9, 3
	s_mul_i32 s23, s9, 4
	s_mul_i32 s24, s9, 5
	s_mul_i32 s25, s9, 6
	s_mul_i32 s26, s9, 7
	s_mul_i32 s27, s9, 8
	v_readlane_b32 s28, v254, 33
	v_readlane_b32 s29, v254, 34
	s_lshl_b32 s10, s0, 9
	s_add_u32 s28, s28, s10
	s_addc_u32 s29, s29, 0
	global_load_dwordx2 v[56:57], v3, s[28:29]
	v_lshrrev_b32_e32 v9, 1, v3
	s_lshl_b32 s10, s0, 8
	s_add_u32 s36, s80, 0x8e35000
	s_addc_u32 s37, s81, 0
	s_add_u32 s36, s36, s10
	s_addc_u32 s37, s37, 0
	s_min_u32 s10, s8, s13
	s_lshl_b32 s18, s10, 10
	s_add_u32 s11, s16, 0
	s_and_b32 s11, s11, 7
	s_lshl_b32 s11, s11, 10
	s_add_u32 s11, s11, s17
	s_mov_b32 m0, s11
	v_lshl_add_u64 v[4:5], v[58:59], 0, s[18:19]
	global_load_lds_dwordx4 v[4:5], off
	s_add_u32 s10, s8, s20
	s_min_u32 s10, s10, s13
	s_lshl_b32 s18, s10, 10
	s_add_u32 s11, s16, 1
	s_and_b32 s11, s11, 7
	s_lshl_b32 s11, s11, 10
	s_add_u32 s11, s11, s17
	s_mov_b32 m0, s11
	v_lshl_add_u64 v[4:5], v[58:59], 0, s[18:19]
	global_load_lds_dwordx4 v[4:5], off
	s_add_u32 s10, s8, s21
	s_min_u32 s10, s10, s13
	s_lshl_b32 s18, s10, 10
	s_add_u32 s11, s16, 2
	s_and_b32 s11, s11, 7
	s_lshl_b32 s11, s11, 10
	s_add_u32 s11, s11, s17
	s_mov_b32 m0, s11
	v_lshl_add_u64 v[4:5], v[58:59], 0, s[18:19]
	global_load_lds_dwordx4 v[4:5], off
	s_add_u32 s10, s8, s22
	s_min_u32 s10, s10, s13
	s_lshl_b32 s18, s10, 10
	s_add_u32 s11, s16, 3
	s_and_b32 s11, s11, 7
	s_lshl_b32 s11, s11, 10
	s_add_u32 s11, s11, s17
	s_mov_b32 m0, s11
	v_lshl_add_u64 v[4:5], v[58:59], 0, s[18:19]
	global_load_lds_dwordx4 v[4:5], off
	s_add_u32 s10, s8, s23
	s_min_u32 s10, s10, s13
	s_lshl_b32 s18, s10, 10
	s_add_u32 s11, s16, 4
	s_and_b32 s11, s11, 7
	s_lshl_b32 s11, s11, 10
	s_add_u32 s11, s11, s17
	s_mov_b32 m0, s11
	v_lshl_add_u64 v[4:5], v[58:59], 0, s[18:19]
	global_load_lds_dwordx4 v[4:5], off
	s_add_u32 s10, s8, s24
	s_min_u32 s10, s10, s13
	s_lshl_b32 s18, s10, 10
	s_add_u32 s11, s16, 5
	s_and_b32 s11, s11, 7
	s_lshl_b32 s11, s11, 10
	s_add_u32 s11, s11, s17
	s_mov_b32 m0, s11
	v_lshl_add_u64 v[4:5], v[58:59], 0, s[18:19]
	global_load_lds_dwordx4 v[4:5], off
	s_waitcnt vmcnt(0)
	s_add_u32 s11, s16, 0
	s_and_b32 s11, s11, 7
	s_lshl_b32 s11, s11, 10
	v_add_u32_e32 v8, s11, v2
	ds_read_b128 v[10:13], v8 offset:0
	ds_read_b128 v[14:17], v8 offset:16
	ds_read_b128 v[18:21], v8 offset:32
	ds_read_b128 v[22:25], v8 offset:48
	s_min_u32 s10, s8, s13
	s_lshl_b32 s11, s10, 12
	v_add_u32_e32 v6, s11, v3
	global_load_dwordx2 v[50:51], v6, s[6:7]
	s_waitcnt lgkmcnt(0)
	v_add_u32_e32 v10, v10, v1
	global_load_dwordx4 v[60:63], v10, s[2:3]
	v_add_u32_e32 v11, v11, v1
	global_load_dwordx4 v[64:67], v11, s[2:3]
	v_add_u32_e32 v12, v12, v1
	global_load_dwordx4 v[68:71], v12, s[2:3]
	v_add_u32_e32 v13, v13, v1
	global_load_dwordx4 v[72:75], v13, s[2:3]
	v_add_u32_e32 v14, v14, v1
	global_load_dwordx4 v[76:79], v14, s[2:3]
	v_add_u32_e32 v15, v15, v1
	global_load_dwordx4 v[80:83], v15, s[2:3]
	v_add_u32_e32 v16, v16, v1
	global_load_dwordx4 v[84:87], v16, s[2:3]
	v_add_u32_e32 v17, v17, v1
	global_load_dwordx4 v[88:91], v17, s[2:3]
	v_add_u32_e32 v18, v18, v1
	global_load_dwordx4 v[92:95], v18, s[2:3]
	v_add_u32_e32 v19, v19, v1
	global_load_dwordx4 v[96:99], v19, s[2:3]
	v_add_u32_e32 v20, v20, v1
	global_load_dwordx4 v[100:103], v20, s[2:3]
	v_add_u32_e32 v21, v21, v1
	global_load_dwordx4 v[104:107], v21, s[2:3]
	v_add_u32_e32 v22, v22, v1
	global_load_dwordx4 v[108:111], v22, s[2:3]
	v_add_u32_e32 v23, v23, v1
	global_load_dwordx4 v[112:115], v23, s[2:3]
	v_add_u32_e32 v24, v24, v1
	global_load_dwordx4 v[116:119], v24, s[2:3]
	v_add_u32_e32 v25, v25, v1
	global_load_dwordx4 v[120:123], v25, s[2:3]
	global_load_dword v252, v6, s[6:7]
	global_load_dword v252, v6, s[6:7]
	global_load_dword v252, v6, s[6:7]
	global_load_dword v252, v6, s[6:7]
	s_add_u32 s11, s16, 1
	s_and_b32 s11, s11, 7
	s_lshl_b32 s11, s11, 10
	v_add_u32_e32 v8, s11, v2
	ds_read_b128 v[10:13], v8 offset:0
	ds_read_b128 v[14:17], v8 offset:16
	ds_read_b128 v[18:21], v8 offset:32
	ds_read_b128 v[22:25], v8 offset:48
	s_add_u32 s10, s8, s20
	s_min_u32 s10, s10, s13
	s_lshl_b32 s11, s10, 12
	v_add_u32_e32 v6, s11, v3
	global_load_dwordx2 v[52:53], v6, s[6:7]
	s_waitcnt lgkmcnt(0)
	v_add_u32_e32 v10, v10, v1
	global_load_dwordx4 v[124:127], v10, s[2:3]
	v_add_u32_e32 v11, v11, v1
	global_load_dwordx4 v[128:131], v11, s[2:3]
	v_add_u32_e32 v12, v12, v1
	global_load_dwordx4 v[132:135], v12, s[2:3]
	v_add_u32_e32 v13, v13, v1
	global_load_dwordx4 v[136:139], v13, s[2:3]
	v_add_u32_e32 v14, v14, v1
	global_load_dwordx4 v[140:143], v14, s[2:3]
	v_add_u32_e32 v15, v15, v1
	global_load_dwordx4 v[144:147], v15, s[2:3]
	v_add_u32_e32 v16, v16, v1
	global_load_dwordx4 v[148:151], v16, s[2:3]
	v_add_u32_e32 v17, v17, v1
	global_load_dwordx4 v[152:155], v17, s[2:3]
	v_add_u32_e32 v18, v18, v1
	global_load_dwordx4 v[156:159], v18, s[2:3]
	v_add_u32_e32 v19, v19, v1
	global_load_dwordx4 v[160:163], v19, s[2:3]
	v_add_u32_e32 v20, v20, v1
	global_load_dwordx4 v[164:167], v20, s[2:3]
	v_add_u32_e32 v21, v21, v1
	global_load_dwordx4 v[168:171], v21, s[2:3]
	v_add_u32_e32 v22, v22, v1
	global_load_dwordx4 v[172:175], v22, s[2:3]
	v_add_u32_e32 v23, v23, v1
	global_load_dwordx4 v[176:179], v23, s[2:3]
	v_add_u32_e32 v24, v24, v1
	global_load_dwordx4 v[180:183], v24, s[2:3]
	v_add_u32_e32 v25, v25, v1
	global_load_dwordx4 v[184:187], v25, s[2:3]
	global_load_dword v252, v6, s[6:7]
	global_load_dword v252, v6, s[6:7]
	global_load_dword v252, v6, s[6:7]
; #define P5_LOAD(A, TAB, j0)                                                                \
;   _Pragma("unroll") for (int q = 0; q < 16; q++) {                                         \
;     A[q] = ((const uint4*)((TAB) + (size_t)widx[(j0) + q] * 1024))[lane];                  \
;   }
; __device__ __forceinline__ void phase5(const Params& p, char* smem, const bool store_x = true) {
;     ...
; #pragma unroll 1
;     for (int j0 = 0; j0 < 128; j0 += 32) {
;       P5_LOAD(A1, EV, j0 + 16)
;       P5_COMPUTE_V(A0, j0)
;       if (j0 + 32 < 128) { P5_LOAD(A0, EV, j0 + 32) }
;       P5_COMPUTE_V(A1, j0 + 16)
;     }
.Lp5v_loop:
	s_add_u32 s10, s8, s25
	s_min_u32 s10, s10, s13
	s_lshl_b32 s18, s10, 10
	s_add_u32 s11, s16, 6
	s_and_b32 s11, s11, 7
	s_lshl_b32 s11, s11, 10
	s_add_u32 s11, s11, s17
	s_mov_b32 m0, s11
	v_lshl_add_u64 v[4:5], v[58:59], 0, s[18:19]
	global_load_lds_dwordx4 v[4:5], off
	s_add_u32 s11, s16, 2
	s_and_b32 s11, s11, 7
	s_lshl_b32 s11, s11, 10
	v_add_u32_e32 v8, s11, v2
	ds_read_b128 v[10:13], v8 offset:0
	ds_read_b128 v[14:17], v8 offset:16
	ds_read_b128 v[18:21], v8 offset:32
	ds_read_b128 v[22:25], v8 offset:48
	s_add_u32 s10, s8, s21
	s_min_u32 s10, s10, s13
	s_lshl_b32 s11, s10, 12
	v_add_u32_e32 v6, s11, v3
	global_load_dwordx2 v[54:55], v6, s[6:7]
	s_waitcnt lgkmcnt(0)
	v_add_u32_e32 v10, v10, v1
	global_load_dwordx4 v[188:191], v10, s[2:3]
	v_add_u32_e32 v11, v11, v1
	global_load_dwordx4 v[192:195], v11, s[2:3]
	v_add_u32_e32 v12, v12, v1
	global_load_dwordx4 v[196:199], v12, s[2:3]
	v_add_u32_e32 v13, v13, v1
	global_load_dwordx4 v[200:203], v13, s[2:3]
	v_add_u32_e32 v14, v14, v1
	global_load_dwordx4 v[204:207], v14, s[2:3]
	v_add_u32_e32 v15, v15, v1
	global_load_dwordx4 v[208:211], v15, s[2:3]
	v_add_u32_e32 v16, v16, v1
	global_load_dwordx4 v[212:215], v16, s[2:3]
	v_add_u32_e32 v17, v17, v1
	global_load_dwordx4 v[216:219], v17, s[2:3]
	v_add_u32_e32 v18, v18, v1
	global_load_dwordx4 v[220:223], v18, s[2:3]
	v_add_u32_e32 v19, v19, v1
	global_load_dwordx4 v[224:227], v19, s[2:3]
	v_add_u32_e32 v20, v20, v1
	global_load_dwordx4 v[228:231], v20, s[2:3]
	v_add_u32_e32 v21, v21, v1
	global_load_dwordx4 v[232:235], v21, s[2:3]
	v_add_u32_e32 v22, v22, v1
	global_load_dwordx4 v[236:239], v22, s[2:3]
	v_add_u32_e32 v23, v23, v1
	global_load_dwordx4 v[240:243], v23, s[2:3]
	v_add_u32_e32 v24, v24, v1
	global_load_dwordx4 v[244:247], v24, s[2:3]
	v_add_u32_e32 v25, v25, v1
	global_load_dwordx4 v[248:251], v25, s[2:3]
	s_add_u32 s11, s16, 0
	s_and_b32 s11, s11, 7
	s_lshl_b32 s11, s11, 10
	v_add_u32_e32 v8, s11, v2
	ds_read_b128 v[10:13], v8 offset:512
	ds_read_b128 v[14:17], v8 offset:528
	ds_read_b128 v[18:21], v8 offset:544
	ds_read_b128 v[22:25], v8 offset:560
	s_mov_b32 s12, s8
	s_waitcnt vmcnt(42) lgkmcnt(0)
	s_cmp_lt_u32 s12, 0x4200
	s_cbranch_scc0 .Lp5v_skip0
	v_cvt_pk_f32_fp8_e32 v[42:43], v60
	v_cvt_pk_f32_fp8_sdwa v[44:45], v60 src0_sel:WORD_1
	v_pk_mul_f32 v[26:27], v[42:43], v[10:11] op_sel_hi:[1,0]
	v_pk_mul_f32 v[28:29], v[44:45], v[10:11] op_sel_hi:[1,0]
	v_cvt_pk_f32_fp8_e32 v[46:47], v61
	v_cvt_pk_f32_fp8_sdwa v[48:49], v61 src0_sel:WORD_1
	v_pk_mul_f32 v[30:31], v[46:47], v[10:11] op_sel_hi:[1,0]
	v_pk_mul_f32 v[32:33], v[48:49], v[10:11] op_sel_hi:[1,0]
	v_cvt_pk_f32_fp8_e32 v[42:43], v62
	v_cvt_pk_f32_fp8_sdwa v[44:45], v62 src0_sel:WORD_1
	v_pk_mul_f32 v[34:35], v[42:43], v[10:11] op_sel_hi:[1,0]
	v_pk_mul_f32 v[36:37], v[44:45], v[10:11] op_sel_hi:[1,0]
	v_cvt_pk_f32_fp8_e32 v[46:47], v63
	v_cvt_pk_f32_fp8_sdwa v[48:49], v63 src0_sel:WORD_1
	v_pk_mul_f32 v[38:39], v[46:47], v[10:11] op_sel_hi:[1,0]
	v_pk_mul_f32 v[40:41], v[48:49], v[10:11] op_sel_hi:[1,0]
	v_cvt_pk_f32_fp8_e32 v[42:43], v64
	v_cvt_pk_f32_fp8_sdwa v[44:45], v64 src0_sel:WORD_1
	v_pk_fma_f32 v[26:27], v[42:43], v[10:11], v[26:27] op_sel:[0,1,0] op_sel_hi:[1,1,1]
	v_pk_fma_f32 v[28:29], v[44:45], v[10:11], v[28:29] op_sel:[0,1,0] op_sel_hi:[1,1,1]
	v_cvt_pk_f32_fp8_e32 v[46:47], v65
	v_cvt_pk_f32_fp8_sdwa v[48:49], v65 src0_sel:WORD_1
	v_pk_fma_f32 v[30:31], v[46:47], v[10:11], v[30:31] op_sel:[0,1,0] op_sel_hi:[1,1,1]
	v_pk_fma_f32 v[32:33], v[48:49], v[10:11], v[32:33] op_sel:[0,1,0] op_sel_hi:[1,1,1]
	v_cvt_pk_f32_fp8_e32 v[42:43], v66
	v_cvt_pk_f32_fp8_sdwa v[44:45], v66 src0_sel:WORD_1
	v_pk_fma_f32 v[34:35], v[42:43], v[10:11], v[34:35] op_sel:[0,1,0] op_sel_hi:[1,1,1]
	v_pk_fma_f32 v[36:37], v[44:45], v[10:11], v[36:37] op_sel:[0,1,0] op_sel_hi:[1,1,1]
	v_cvt_pk_f32_fp8_e32 v[46:47], v67
	v_cvt_pk_f32_fp8_sdwa v[48:49], v67 src0_sel:WORD_1
	v_pk_fma_f32 v[38:39], v[46:47], v[10:11], v[38:39] op_sel:[0,1,0] op_sel_hi:[1,1,1]
	v_pk_fma_f32 v[40:41], v[48:49], v[10:11], v[40:41] op_sel:[0,1,0] op_sel_hi:[1,1,1]
	v_cvt_pk_f32_fp8_e32 v[42:43], v68
	v_cvt_pk_f32_fp8_sdwa v[44:45], v68 src0_sel:WORD_1
	v_pk_fma_f32 v[26:27], v[42:43], v[12:13], v[26:27] op_sel_hi:[1,0,1]
	v_pk_fma_f32 v[28:29], v[44:45], v[12:13], v[28:29] op_sel_hi:[1,0,1]
	v_cvt_pk_f32_fp8_e32 v[46:47], v69
	v_cvt_pk_f32_fp8_sdwa v[48:49], v69 src0_sel:WORD_1
	v_pk_fma_f32 v[30:31], v[46:47], v[12:13], v[30:31] op_sel_hi:[1,0,1]
	v_pk_fma_f32 v[32:33], v[48:49], v[12:13], v[32:33] op_sel_hi:[1,0,1]
	v_cvt_pk_f32_fp8_e32 v[42:43], v70
	v_cvt_pk_f32_fp8_sdwa v[44:45], v70 src0_sel:WORD_1
	v_pk_fma_f32 v[34:35], v[42:43], v[12:13], v[34:35] op_sel_hi:[1,0,1]
	v_pk_fma_f32 v[36:37], v[44:45], v[12:13], v[36:37] op_sel_hi:[1,0,1]
	v_cvt_pk_f32_fp8_e32 v[46:47], v71
	v_cvt_pk_f32_fp8_sdwa v[48:49], v71 src0_sel:WORD_1
	v_pk_fma_f32 v[38:39], v[46:47], v[12:13], v[38:39] op_sel_hi:[1,0,1]
	v_pk_fma_f32 v[40:41], v[48:49], v[12:13], v[40:41] op_sel_hi:[1,0,1]
	v_cvt_pk_f32_fp8_e32 v[42:43], v72
	v_cvt_pk_f32_fp8_sdwa v[44:45], v72 src0_sel:WORD_1
	v_pk_fma_f32 v[26:27], v[42:43], v[12:13], v[26:27] op_sel:[0,1,0] op_sel_hi:[1,1,1]
	v_pk_fma_f32 v[28:29], v[44:45], v[12:13], v[28:29] op_sel:[0,1,0] op_sel_hi:[1,1,1]
	v_cvt_pk_f32_fp8_e32 v[46:47], v73
	v_cvt_pk_f32_fp8_sdwa v[48:49], v73 src0_sel:WORD_1
	v_pk_fma_f32 v[30:31], v[46:47], v[12:13], v[30:31] op_sel:[0,1,0] op_sel_hi:[1,1,1]
	v_pk_fma_f32 v[32:33], v[48:49], v[12:13], v[32:33] op_sel:[0,1,0] op_sel_hi:[1,1,1]
	v_cvt_pk_f32_fp8_e32 v[42:43], v74
	v_cvt_pk_f32_fp8_sdwa v[44:45], v74 src0_sel:WORD_1
	v_pk_fma_f32 v[34:35], v[42:43], v[12:13], v[34:35] op_sel:[0,1,0] op_sel_hi:[1,1,1]
	v_pk_fma_f32 v[36:37], v[44:45], v[12:13], v[36:37] op_sel:[0,1,0] op_sel_hi:[1,1,1]
	v_cvt_pk_f32_fp8_e32 v[46:47], v75
	v_cvt_pk_f32_fp8_sdwa v[48:49], v75 src0_sel:WORD_1
	v_pk_fma_f32 v[38:39], v[46:47], v[12:13], v[38:39] op_sel:[0,1,0] op_sel_hi:[1,1,1]
	v_pk_fma_f32 v[40:41], v[48:49], v[12:13], v[40:41] op_sel:[0,1,0] op_sel_hi:[1,1,1]
	v_cvt_pk_f32_fp8_e32 v[42:43], v76
	v_cvt_pk_f32_fp8_sdwa v[44:45], v76 src0_sel:WORD_1
	v_pk_fma_f32 v[26:27], v[42:43], v[14:15], v[26:27] op_sel_hi:[1,0,1]
	v_pk_fma_f32 v[28:29], v[44:45], v[14:15], v[28:29] op_sel_hi:[1,0,1]
	v_cvt_pk_f32_fp8_e32 v[46:47], v77
	v_cvt_pk_f32_fp8_sdwa v[48:49], v77 src0_sel:WORD_1
	v_pk_fma_f32 v[30:31], v[46:47], v[14:15], v[30:31] op_sel_hi:[1,0,1]
	v_pk_fma_f32 v[32:33], v[48:49], v[14:15], v[32:33] op_sel_hi:[1,0,1]
	v_cvt_pk_f32_fp8_e32 v[42:43], v78
	v_cvt_pk_f32_fp8_sdwa v[44:45], v78 src0_sel:WORD_1
	v_pk_fma_f32 v[34:35], v[42:43], v[14:15], v[34:35] op_sel_hi:[1,0,1]
	v_pk_fma_f32 v[36:37], v[44:45], v[14:15], v[36:37] op_sel_hi:[1,0,1]
	v_cvt_pk_f32_fp8_e32 v[46:47], v79
	v_cvt_pk_f32_fp8_sdwa v[48:49], v79 src0_sel:WORD_1
	v_pk_fma_f32 v[38:39], v[46:47], v[14:15], v[38:39] op_sel_hi:[1,0,1]
	v_pk_fma_f32 v[40:41], v[48:49], v[14:15], v[40:41] op_sel_hi:[1,0,1]
	v_cvt_pk_f32_fp8_e32 v[42:43], v80
	v_cvt_pk_f32_fp8_sdwa v[44:45], v80 src0_sel:WORD_1
	v_pk_fma_f32 v[26:27], v[42:43], v[14:15], v[26:27] op_sel:[0,1,0] op_sel_hi:[1,1,1]
	v_pk_fma_f32 v[28:29], v[44:45], v[14:15], v[28:29] op_sel:[0,1,0] op_sel_hi:[1,1,1]
	v_cvt_pk_f32_fp8_e32 v[46:47], v81
	v_cvt_pk_f32_fp8_sdwa v[48:49], v81 src0_sel:WORD_1
	v_pk_fma_f32 v[30:31], v[46:47], v[14:15], v[30:31] op_sel:[0,1,0] op_sel_hi:[1,1,1]
	v_pk_fma_f32 v[32:33], v[48:49], v[14:15], v[32:33] op_sel:[0,1,0] op_sel_hi:[1,1,1]
	v_cvt_pk_f32_fp8_e32 v[42:43], v82
	v_cvt_pk_f32_fp8_sdwa v[44:45], v82 src0_sel:WORD_1
	v_pk_fma_f32 v[34:35], v[42:43], v[14:15], v[34:35] op_sel:[0,1,0] op_sel_hi:[1,1,1]
	v_pk_fma_f32 v[36:37], v[44:45], v[14:15], v[36:37] op_sel:[0,1,0] op_sel_hi:[1,1,1]
	v_cvt_pk_f32_fp8_e32 v[46:47], v83
	v_cvt_pk_f32_fp8_sdwa v[48:49], v83 src0_sel:WORD_1
	v_pk_fma_f32 v[38:39], v[46:47], v[14:15], v[38:39] op_sel:[0,1,0] op_sel_hi:[1,1,1]
	v_pk_fma_f32 v[40:41], v[48:49], v[14:15], v[40:41] op_sel:[0,1,0] op_sel_hi:[1,1,1]
	v_cvt_pk_f32_fp8_e32 v[42:43], v84
	v_cvt_pk_f32_fp8_sdwa v[44:45], v84 src0_sel:WORD_1
	v_pk_fma_f32 v[26:27], v[42:43], v[16:17], v[26:27] op_sel_hi:[1,0,1]
	v_pk_fma_f32 v[28:29], v[44:45], v[16:17], v[28:29] op_sel_hi:[1,0,1]
	v_cvt_pk_f32_fp8_e32 v[46:47], v85
	v_cvt_pk_f32_fp8_sdwa v[48:49], v85 src0_sel:WORD_1
	v_pk_fma_f32 v[30:31], v[46:47], v[16:17], v[30:31] op_sel_hi:[1,0,1]
	v_pk_fma_f32 v[32:33], v[48:49], v[16:17], v[32:33] op_sel_hi:[1,0,1]
	v_cvt_pk_f32_fp8_e32 v[42:43], v86
	v_cvt_pk_f32_fp8_sdwa v[44:45], v86 src0_sel:WORD_1
	v_pk_fma_f32 v[34:35], v[42:43], v[16:17], v[34:35] op_sel_hi:[1,0,1]
	v_pk_fma_f32 v[36:37], v[44:45], v[16:17], v[36:37] op_sel_hi:[1,0,1]
	v_cvt_pk_f32_fp8_e32 v[46:47], v87
	v_cvt_pk_f32_fp8_sdwa v[48:49], v87 src0_sel:WORD_1
	v_pk_fma_f32 v[38:39], v[46:47], v[16:17], v[38:39] op_sel_hi:[1,0,1]
	v_pk_fma_f32 v[40:41], v[48:49], v[16:17], v[40:41] op_sel_hi:[1,0,1]
	v_cvt_pk_f32_fp8_e32 v[42:43], v88
	v_cvt_pk_f32_fp8_sdwa v[44:45], v88 src0_sel:WORD_1
	v_pk_fma_f32 v[26:27], v[42:43], v[16:17], v[26:27] op_sel:[0,1,0] op_sel_hi:[1,1,1]
	v_pk_fma_f32 v[28:29], v[44:45], v[16:17], v[28:29] op_sel:[0,1,0] op_sel_hi:[1,1,1]
	v_cvt_pk_f32_fp8_e32 v[46:47], v89
	v_cvt_pk_f32_fp8_sdwa v[48:49], v89 src0_sel:WORD_1
	v_pk_fma_f32 v[30:31], v[46:47], v[16:17], v[30:31] op_sel:[0,1,0] op_sel_hi:[1,1,1]
	v_pk_fma_f32 v[32:33], v[48:49], v[16:17], v[32:33] op_sel:[0,1,0] op_sel_hi:[1,1,1]
	v_cvt_pk_f32_fp8_e32 v[42:43], v90
	v_cvt_pk_f32_fp8_sdwa v[44:45], v90 src0_sel:WORD_1
	v_pk_fma_f32 v[34:35], v[42:43], v[16:17], v[34:35] op_sel:[0,1,0] op_sel_hi:[1,1,1]
	v_pk_fma_f32 v[36:37], v[44:45], v[16:17], v[36:37] op_sel:[0,1,0] op_sel_hi:[1,1,1]
	v_cvt_pk_f32_fp8_e32 v[46:47], v91
	v_cvt_pk_f32_fp8_sdwa v[48:49], v91 src0_sel:WORD_1
	v_pk_fma_f32 v[38:39], v[46:47], v[16:17], v[38:39] op_sel:[0,1,0] op_sel_hi:[1,1,1]
	v_pk_fma_f32 v[40:41], v[48:49], v[16:17], v[40:41] op_sel:[0,1,0] op_sel_hi:[1,1,1]
	v_cvt_pk_f32_fp8_e32 v[42:43], v92
	v_cvt_pk_f32_fp8_sdwa v[44:45], v92 src0_sel:WORD_1
	v_pk_fma_f32 v[26:27], v[42:43], v[18:19], v[26:27] op_sel_hi:[1,0,1]
	v_pk_fma_f32 v[28:29], v[44:45], v[18:19], v[28:29] op_sel_hi:[1,0,1]
	v_cvt_pk_f32_fp8_e32 v[46:47], v93
	v_cvt_pk_f32_fp8_sdwa v[48:49], v93 src0_sel:WORD_1
	v_pk_fma_f32 v[30:31], v[46:47], v[18:19], v[30:31] op_sel_hi:[1,0,1]
	v_pk_fma_f32 v[32:33], v[48:49], v[18:19], v[32:33] op_sel_hi:[1,0,1]
	v_cvt_pk_f32_fp8_e32 v[42:43], v94
	v_cvt_pk_f32_fp8_sdwa v[44:45], v94 src0_sel:WORD_1
	v_pk_fma_f32 v[34:35], v[42:43], v[18:19], v[34:35] op_sel_hi:[1,0,1]
	v_pk_fma_f32 v[36:37], v[44:45], v[18:19], v[36:37] op_sel_hi:[1,0,1]
	v_cvt_pk_f32_fp8_e32 v[46:47], v95
	v_cvt_pk_f32_fp8_sdwa v[48:49], v95 src0_sel:WORD_1
	v_pk_fma_f32 v[38:39], v[46:47], v[18:19], v[38:39] op_sel_hi:[1,0,1]
	v_pk_fma_f32 v[40:41], v[48:49], v[18:19], v[40:41] op_sel_hi:[1,0,1]
	v_cvt_pk_f32_fp8_e32 v[42:43], v96
	v_cvt_pk_f32_fp8_sdwa v[44:45], v96 src0_sel:WORD_1
	v_pk_fma_f32 v[26:27], v[42:43], v[18:19], v[26:27] op_sel:[0,1,0] op_sel_hi:[1,1,1]
	v_pk_fma_f32 v[28:29], v[44:45], v[18:19], v[28:29] op_sel:[0,1,0] op_sel_hi:[1,1,1]
	v_cvt_pk_f32_fp8_e32 v[46:47], v97
	v_cvt_pk_f32_fp8_sdwa v[48:49], v97 src0_sel:WORD_1
	v_pk_fma_f32 v[30:31], v[46:47], v[18:19], v[30:31] op_sel:[0,1,0] op_sel_hi:[1,1,1]
	v_pk_fma_f32 v[32:33], v[48:49], v[18:19], v[32:33] op_sel:[0,1,0] op_sel_hi:[1,1,1]
	v_cvt_pk_f32_fp8_e32 v[42:43], v98
	v_cvt_pk_f32_fp8_sdwa v[44:45], v98 src0_sel:WORD_1
	v_pk_fma_f32 v[34:35], v[42:43], v[18:19], v[34:35] op_sel:[0,1,0] op_sel_hi:[1,1,1]
	v_pk_fma_f32 v[36:37], v[44:45], v[18:19], v[36:37] op_sel:[0,1,0] op_sel_hi:[1,1,1]
	v_cvt_pk_f32_fp8_e32 v[46:47], v99
	v_cvt_pk_f32_fp8_sdwa v[48:49], v99 src0_sel:WORD_1
	v_pk_fma_f32 v[38:39], v[46:47], v[18:19], v[38:39] op_sel:[0,1,0] op_sel_hi:[1,1,1]
	v_pk_fma_f32 v[40:41], v[48:49], v[18:19], v[40:41] op_sel:[0,1,0] op_sel_hi:[1,1,1]
	v_cvt_pk_f32_fp8_e32 v[42:43], v100
	v_cvt_pk_f32_fp8_sdwa v[44:45], v100 src0_sel:WORD_1
	v_pk_fma_f32 v[26:27], v[42:43], v[20:21], v[26:27] op_sel_hi:[1,0,1]
	v_pk_fma_f32 v[28:29], v[44:45], v[20:21], v[28:29] op_sel_hi:[1,0,1]
	v_cvt_pk_f32_fp8_e32 v[46:47], v101
	v_cvt_pk_f32_fp8_sdwa v[48:49], v101 src0_sel:WORD_1
	v_pk_fma_f32 v[30:31], v[46:47], v[20:21], v[30:31] op_sel_hi:[1,0,1]
	v_pk_fma_f32 v[32:33], v[48:49], v[20:21], v[32:33] op_sel_hi:[1,0,1]
	v_cvt_pk_f32_fp8_e32 v[42:43], v102
	v_cvt_pk_f32_fp8_sdwa v[44:45], v102 src0_sel:WORD_1
	v_pk_fma_f32 v[34:35], v[42:43], v[20:21], v[34:35] op_sel_hi:[1,0,1]
	v_pk_fma_f32 v[36:37], v[44:45], v[20:21], v[36:37] op_sel_hi:[1,0,1]
	v_cvt_pk_f32_fp8_e32 v[46:47], v103
	v_cvt_pk_f32_fp8_sdwa v[48:49], v103 src0_sel:WORD_1
	v_pk_fma_f32 v[38:39], v[46:47], v[20:21], v[38:39] op_sel_hi:[1,0,1]
	v_pk_fma_f32 v[40:41], v[48:49], v[20:21], v[40:41] op_sel_hi:[1,0,1]
	v_cvt_pk_f32_fp8_e32 v[42:43], v104
	v_cvt_pk_f32_fp8_sdwa v[44:45], v104 src0_sel:WORD_1
	v_pk_fma_f32 v[26:27], v[42:43], v[20:21], v[26:27] op_sel:[0,1,0] op_sel_hi:[1,1,1]
	v_pk_fma_f32 v[28:29], v[44:45], v[20:21], v[28:29] op_sel:[0,1,0] op_sel_hi:[1,1,1]
	v_cvt_pk_f32_fp8_e32 v[46:47], v105
	v_cvt_pk_f32_fp8_sdwa v[48:49], v105 src0_sel:WORD_1
	v_pk_fma_f32 v[30:31], v[46:47], v[20:21], v[30:31] op_sel:[0,1,0] op_sel_hi:[1,1,1]
	v_pk_fma_f32 v[32:33], v[48:49], v[20:21], v[32:33] op_sel:[0,1,0] op_sel_hi:[1,1,1]
	v_cvt_pk_f32_fp8_e32 v[42:43], v106
	v_cvt_pk_f32_fp8_sdwa v[44:45], v106 src0_sel:WORD_1
	v_pk_fma_f32 v[34:35], v[42:43], v[20:21], v[34:35] op_sel:[0,1,0] op_sel_hi:[1,1,1]
	v_pk_fma_f32 v[36:37], v[44:45], v[20:21], v[36:37] op_sel:[0,1,0] op_sel_hi:[1,1,1]
	v_cvt_pk_f32_fp8_e32 v[46:47], v107
	v_cvt_pk_f32_fp8_sdwa v[48:49], v107 src0_sel:WORD_1
	v_pk_fma_f32 v[38:39], v[46:47], v[20:21], v[38:39] op_sel:[0,1,0] op_sel_hi:[1,1,1]
	v_pk_fma_f32 v[40:41], v[48:49], v[20:21], v[40:41] op_sel:[0,1,0] op_sel_hi:[1,1,1]
	v_cvt_pk_f32_fp8_e32 v[42:43], v108
	v_cvt_pk_f32_fp8_sdwa v[44:45], v108 src0_sel:WORD_1
	v_pk_fma_f32 v[26:27], v[42:43], v[22:23], v[26:27] op_sel_hi:[1,0,1]
	v_pk_fma_f32 v[28:29], v[44:45], v[22:23], v[28:29] op_sel_hi:[1,0,1]
	v_cvt_pk_f32_fp8_e32 v[46:47], v109
	v_cvt_pk_f32_fp8_sdwa v[48:49], v109 src0_sel:WORD_1
	v_pk_fma_f32 v[30:31], v[46:47], v[22:23], v[30:31] op_sel_hi:[1,0,1]
	v_pk_fma_f32 v[32:33], v[48:49], v[22:23], v[32:33] op_sel_hi:[1,0,1]
	v_cvt_pk_f32_fp8_e32 v[42:43], v110
	v_cvt_pk_f32_fp8_sdwa v[44:45], v110 src0_sel:WORD_1
	v_pk_fma_f32 v[34:35], v[42:43], v[22:23], v[34:35] op_sel_hi:[1,0,1]
	v_pk_fma_f32 v[36:37], v[44:45], v[22:23], v[36:37] op_sel_hi:[1,0,1]
	v_cvt_pk_f32_fp8_e32 v[46:47], v111
	v_cvt_pk_f32_fp8_sdwa v[48:49], v111 src0_sel:WORD_1
	v_pk_fma_f32 v[38:39], v[46:47], v[22:23], v[38:39] op_sel_hi:[1,0,1]
	v_pk_fma_f32 v[40:41], v[48:49], v[22:23], v[40:41] op_sel_hi:[1,0,1]
	v_cvt_pk_f32_fp8_e32 v[42:43], v112
	v_cvt_pk_f32_fp8_sdwa v[44:45], v112 src0_sel:WORD_1
	v_pk_fma_f32 v[26:27], v[42:43], v[22:23], v[26:27] op_sel:[0,1,0] op_sel_hi:[1,1,1]
	v_pk_fma_f32 v[28:29], v[44:45], v[22:23], v[28:29] op_sel:[0,1,0] op_sel_hi:[1,1,1]
	v_cvt_pk_f32_fp8_e32 v[46:47], v113
	v_cvt_pk_f32_fp8_sdwa v[48:49], v113 src0_sel:WORD_1
	v_pk_fma_f32 v[30:31], v[46:47], v[22:23], v[30:31] op_sel:[0,1,0] op_sel_hi:[1,1,1]
	v_pk_fma_f32 v[32:33], v[48:49], v[22:23], v[32:33] op_sel:[0,1,0] op_sel_hi:[1,1,1]
	v_cvt_pk_f32_fp8_e32 v[42:43], v114
	v_cvt_pk_f32_fp8_sdwa v[44:45], v114 src0_sel:WORD_1
	v_pk_fma_f32 v[34:35], v[42:43], v[22:23], v[34:35] op_sel:[0,1,0] op_sel_hi:[1,1,1]
	v_pk_fma_f32 v[36:37], v[44:45], v[22:23], v[36:37] op_sel:[0,1,0] op_sel_hi:[1,1,1]
	v_cvt_pk_f32_fp8_e32 v[46:47], v115
	v_cvt_pk_f32_fp8_sdwa v[48:49], v115 src0_sel:WORD_1
	v_pk_fma_f32 v[38:39], v[46:47], v[22:23], v[38:39] op_sel:[0,1,0] op_sel_hi:[1,1,1]
	v_pk_fma_f32 v[40:41], v[48:49], v[22:23], v[40:41] op_sel:[0,1,0] op_sel_hi:[1,1,1]
	v_cvt_pk_f32_fp8_e32 v[42:43], v116
	v_cvt_pk_f32_fp8_sdwa v[44:45], v116 src0_sel:WORD_1
	v_pk_fma_f32 v[26:27], v[42:43], v[24:25], v[26:27] op_sel_hi:[1,0,1]
	v_pk_fma_f32 v[28:29], v[44:45], v[24:25], v[28:29] op_sel_hi:[1,0,1]
	v_cvt_pk_f32_fp8_e32 v[46:47], v117
	v_cvt_pk_f32_fp8_sdwa v[48:49], v117 src0_sel:WORD_1
	v_pk_fma_f32 v[30:31], v[46:47], v[24:25], v[30:31] op_sel_hi:[1,0,1]
	v_pk_fma_f32 v[32:33], v[48:49], v[24:25], v[32:33] op_sel_hi:[1,0,1]
	v_cvt_pk_f32_fp8_e32 v[42:43], v118
	v_cvt_pk_f32_fp8_sdwa v[44:45], v118 src0_sel:WORD_1
	v_pk_fma_f32 v[34:35], v[42:43], v[24:25], v[34:35] op_sel_hi:[1,0,1]
	v_pk_fma_f32 v[36:37], v[44:45], v[24:25], v[36:37] op_sel_hi:[1,0,1]
	v_cvt_pk_f32_fp8_e32 v[46:47], v119
	v_cvt_pk_f32_fp8_sdwa v[48:49], v119 src0_sel:WORD_1
	v_pk_fma_f32 v[38:39], v[46:47], v[24:25], v[38:39] op_sel_hi:[1,0,1]
	v_pk_fma_f32 v[40:41], v[48:49], v[24:25], v[40:41] op_sel_hi:[1,0,1]
	v_cvt_pk_f32_fp8_e32 v[42:43], v120
; __device__ __forceinline__ float wsum(float v) { v = dpp_row_sum16(v); v += __shfl_xor(v, 16); v += __shfl_xor(v, 32); return v; }
; __device__ __forceinline__ void phase5(const Params& p, char* smem, const bool store_x = true) {
;     ...
;     float x2[16];
; #pragma unroll
;     for (int i = 0; i < 4; i++) {
;       const float4 xv = i == 0 ? xv0 : i == 1 ? xv1 : i == 2 ? xv2 : xv3;
;       x2[4 * i] = xv.x + o2[2 * i].x; x2[4 * i + 1] = xv.y + o2[2 * i].y; x2[4 * i + 2] = xv.z + o2[2 * i + 1].x; x2[4 * i + 3] = xv.w + o2[2 * i + 1].y;
;     }
;     float ss = 0.f;
; #pragma unroll
;     for (int i = 0; i < 16; i++) ss += x2[i] * x2[i];
;     ss = wsum(ss);
;     const float rs = rsqrtf(ss * (1.f / 1024.f) + EPSF);
;     if (store_x) {
; #pragma unroll
;       for (int i = 0; i < 4; i++) *(float4*)(xr + i * 4) = make_float4(x2[4 * i], x2[4 * i + 1], x2[4 * i + 2], x2[4 * i + 3]);
;     }
;     unsigned hp[8];
; #pragma unroll
;     for (int i = 0; i < 4; i++) {
;       const float4 g = *(const float4*)(p.g_ple + lane * 16 + i * 4);
;       hp[2 * i] = pack2(x2[4 * i] * rs * g.x, x2[4 * i + 1] * rs * g.y);
;       hp[2 * i + 1] = pack2(x2[4 * i + 2] * rs * g.z, x2[4 * i + 3] * rs * g.w);
;     }
;     *(uint4*)(H3 + (size_t)tok * 1024 + lane * 16) = make_uint4(hp[0], hp[1], hp[2], hp[3]);
;     *(uint4*)(H3 + (size_t)tok * 1024 + lane * 16 + 8) = make_uint4(hp[4], hp[5], hp[6], hp[7]);
	v_cvt_pk_f32_fp8_sdwa v[44:45], v120 src0_sel:WORD_1
	v_pk_fma_f32 v[26:27], v[42:43], v[24:25], v[26:27] op_sel:[0,1,0] op_sel_hi:[1,1,1]
	v_pk_fma_f32 v[28:29], v[44:45], v[24:25], v[28:29] op_sel:[0,1,0] op_sel_hi:[1,1,1]
	v_cvt_pk_f32_fp8_e32 v[46:47], v121
	v_cvt_pk_f32_fp8_sdwa v[48:49], v121 src0_sel:WORD_1
	v_pk_fma_f32 v[30:31], v[46:47], v[24:25], v[30:31] op_sel:[0,1,0] op_sel_hi:[1,1,1]
	v_pk_fma_f32 v[32:33], v[48:49], v[24:25], v[32:33] op_sel:[0,1,0] op_sel_hi:[1,1,1]
	v_cvt_pk_f32_fp8_e32 v[42:43], v122
	v_cvt_pk_f32_fp8_sdwa v[44:45], v122 src0_sel:WORD_1
	v_pk_fma_f32 v[34:35], v[42:43], v[24:25], v[34:35] op_sel:[0,1,0] op_sel_hi:[1,1,1]
	v_pk_fma_f32 v[36:37], v[44:45], v[24:25], v[36:37] op_sel:[0,1,0] op_sel_hi:[1,1,1]
	v_cvt_pk_f32_fp8_e32 v[46:47], v123
	v_cvt_pk_f32_fp8_sdwa v[48:49], v123 src0_sel:WORD_1
	v_pk_fma_f32 v[38:39], v[46:47], v[24:25], v[38:39] op_sel:[0,1,0] op_sel_hi:[1,1,1]
	v_pk_fma_f32 v[40:41], v[48:49], v[24:25], v[40:41] op_sel:[0,1,0] op_sel_hi:[1,1,1]
	s_nop 1
	v_permlane32_swap_b32_e32 v26, v34
	v_permlane32_swap_b32_e32 v27, v35
	v_permlane32_swap_b32_e32 v28, v36
	v_permlane32_swap_b32_e32 v29, v37
	v_permlane32_swap_b32_e32 v30, v38
	v_permlane32_swap_b32_e32 v31, v39
	v_permlane32_swap_b32_e32 v32, v40
	v_permlane32_swap_b32_e32 v33, v41
	v_add_f32_e32 v26, v26, v34
	v_add_f32_e32 v27, v27, v35
	v_add_f32_e32 v28, v28, v36
	v_add_f32_e32 v29, v29, v37
	v_add_f32_e32 v30, v30, v38
	v_add_f32_e32 v31, v31, v39
	v_add_f32_e32 v32, v32, v40
	v_add_f32_e32 v33, v33, v41
	s_nop 1
	v_permlane16_swap_b32_e32 v26, v30
	v_permlane16_swap_b32_e32 v27, v31
	v_permlane16_swap_b32_e32 v28, v32
	v_permlane16_swap_b32_e32 v29, v33
	v_add_f32_e32 v26, v26, v30
	v_add_f32_e32 v27, v27, v31
	v_add_f32_e32 v28, v28, v32
	v_add_f32_e32 v29, v29, v33
	s_lshl_b32 s11, s12, 12
	v_add_u32_e32 v6, s11, v3
	v_add_f32_dpp v42, v26, v26 row_ror:8 row_mask:0xf bank_mask:0xf
	v_add_f32_dpp v43, v28, v28 row_ror:8 row_mask:0xf bank_mask:0xf
	v_add_f32_dpp v44, v27, v27 row_ror:8 row_mask:0xf bank_mask:0xf
	v_add_f32_dpp v45, v29, v29 row_ror:8 row_mask:0xf bank_mask:0xf
	v_cndmask_b32_e64 v46, v42, v43, s[14:15]
	v_cndmask_b32_e64 v47, v44, v45, s[14:15]
	v_add_f32_e32 v46, v50, v46
	v_add_f32_e32 v47, v51, v47
	global_store_dwordx2 v6, v[46:47], s[6:7]
	v_pk_mul_f32 v[42:43], v[46:47], v[56:57]
	s_lshl_b32 s11, s12, 11
	v_add_u32_e32 v8, s11, v9
	v_cvt_pk_bf16_f32 v42, v42, v43
	global_store_dword v8, v42, s[36:37]
	v_mul_f32_e32 v48, v46, v46
	v_fmac_f32_e32 v48, v47, v47
	s_lshl_b32 s11, s12, 2
	s_add_u32 s11, s11, 0x1100000
	v_mov_b32_e32 v7, s11
	v_add_f32_dpp v48, v48, v48 quad_perm:[1,0,3,2] row_mask:0xf bank_mask:0xf
	s_nop 1
	v_add_f32_dpp v48, v48, v48 quad_perm:[2,3,0,1] row_mask:0xf bank_mask:0xf
	s_nop 1
	v_add_f32_dpp v48, v48, v48 row_half_mirror row_mask:0xf bank_mask:0xf
	s_nop 1
	v_add_f32_dpp v48, v48, v48 row_mirror row_mask:0xf bank_mask:0xf
	s_nop 1
	v_add_f32_dpp v48, v48, v48 row_bcast:15 row_mask:0xa bank_mask:0xf
	s_nop 1
	v_add_f32_dpp v48, v48, v48 row_bcast:31 row_mask:0xc bank_mask:0xf
	s_nop 1
	s_mov_b32 exec_lo, 0
	s_brev_b32 exec_hi, 1
	global_atomic_add_f32 v7, v48, s[4:5]
	s_mov_b64 exec, -1
.Lp5v_skip0:
	s_add_u32 s10, s8, s26
	s_min_u32 s10, s10, s13
	s_lshl_b32 s18, s10, 10
	s_add_u32 s11, s16, 7
	s_and_b32 s11, s11, 7
	s_lshl_b32 s11, s11, 10
	s_add_u32 s11, s11, s17
	s_mov_b32 m0, s11
	v_lshl_add_u64 v[4:5], v[58:59], 0, s[18:19]
	global_load_lds_dwordx4 v[4:5], off
	s_add_u32 s11, s16, 3
	s_and_b32 s11, s11, 7
	s_lshl_b32 s11, s11, 10
	v_add_u32_e32 v8, s11, v2
	ds_read_b128 v[10:13], v8 offset:0
	ds_read_b128 v[14:17], v8 offset:16
	ds_read_b128 v[18:21], v8 offset:32
	ds_read_b128 v[22:25], v8 offset:48
	s_add_u32 s10, s8, s22
	s_min_u32 s10, s10, s13
	s_lshl_b32 s11, s10, 12
	v_add_u32_e32 v6, s11, v3
	global_load_dwordx2 v[50:51], v6, s[6:7]
	s_waitcnt lgkmcnt(0)
	v_add_u32_e32 v10, v10, v1
	global_load_dwordx4 v[60:63], v10, s[2:3]
	v_add_u32_e32 v11, v11, v1
	global_load_dwordx4 v[64:67], v11, s[2:3]
	v_add_u32_e32 v12, v12, v1
	global_load_dwordx4 v[68:71], v12, s[2:3]
	v_add_u32_e32 v13, v13, v1
	global_load_dwordx4 v[72:75], v13, s[2:3]
	v_add_u32_e32 v14, v14, v1
	global_load_dwordx4 v[76:79], v14, s[2:3]
	v_add_u32_e32 v15, v15, v1
	global_load_dwordx4 v[80:83], v15, s[2:3]
	v_add_u32_e32 v16, v16, v1
	global_load_dwordx4 v[84:87], v16, s[2:3]
	v_add_u32_e32 v17, v17, v1
	global_load_dwordx4 v[88:91], v17, s[2:3]
	v_add_u32_e32 v18, v18, v1
	global_load_dwordx4 v[92:95], v18, s[2:3]
	v_add_u32_e32 v19, v19, v1
	global_load_dwordx4 v[96:99], v19, s[2:3]
	v_add_u32_e32 v20, v20, v1
	global_load_dwordx4 v[100:103], v20, s[2:3]
	v_add_u32_e32 v21, v21, v1
	global_load_dwordx4 v[104:107], v21, s[2:3]
	v_add_u32_e32 v22, v22, v1
	global_load_dwordx4 v[108:111], v22, s[2:3]
	v_add_u32_e32 v23, v23, v1
	global_load_dwordx4 v[112:115], v23, s[2:3]
	v_add_u32_e32 v24, v24, v1
	global_load_dwordx4 v[116:119], v24, s[2:3]
	v_add_u32_e32 v25, v25, v1
	global_load_dwordx4 v[120:123], v25, s[2:3]
	s_add_u32 s11, s16, 1
	s_and_b32 s11, s11, 7
	s_lshl_b32 s11, s11, 10
	v_add_u32_e32 v8, s11, v2
	ds_read_b128 v[10:13], v8 offset:512
	ds_read_b128 v[14:17], v8 offset:528
	ds_read_b128 v[18:21], v8 offset:544
	ds_read_b128 v[22:25], v8 offset:560
	s_add_u32 s12, s8, s20
	s_waitcnt vmcnt(42) lgkmcnt(0)
	s_cmp_lt_u32 s12, 0x4200
	s_cbranch_scc0 .Lp5v_skip1
	v_cvt_pk_f32_fp8_e32 v[42:43], v124
	v_cvt_pk_f32_fp8_sdwa v[44:45], v124 src0_sel:WORD_1
	v_pk_mul_f32 v[26:27], v[42:43], v[10:11] op_sel_hi:[1,0]
	v_pk_mul_f32 v[28:29], v[44:45], v[10:11] op_sel_hi:[1,0]
	v_cvt_pk_f32_fp8_e32 v[46:47], v125
	v_cvt_pk_f32_fp8_sdwa v[48:49], v125 src0_sel:WORD_1
	v_pk_mul_f32 v[30:31], v[46:47], v[10:11] op_sel_hi:[1,0]
	v_pk_mul_f32 v[32:33], v[48:49], v[10:11] op_sel_hi:[1,0]
	v_cvt_pk_f32_fp8_e32 v[42:43], v126
	v_cvt_pk_f32_fp8_sdwa v[44:45], v126 src0_sel:WORD_1
	v_pk_mul_f32 v[34:35], v[42:43], v[10:11] op_sel_hi:[1,0]
	v_pk_mul_f32 v[36:37], v[44:45], v[10:11] op_sel_hi:[1,0]
	v_cvt_pk_f32_fp8_e32 v[46:47], v127
	v_cvt_pk_f32_fp8_sdwa v[48:49], v127 src0_sel:WORD_1
	v_pk_mul_f32 v[38:39], v[46:47], v[10:11] op_sel_hi:[1,0]
	v_pk_mul_f32 v[40:41], v[48:49], v[10:11] op_sel_hi:[1,0]
	v_cvt_pk_f32_fp8_e32 v[42:43], v128
	v_cvt_pk_f32_fp8_sdwa v[44:45], v128 src0_sel:WORD_1
	v_pk_fma_f32 v[26:27], v[42:43], v[10:11], v[26:27] op_sel:[0,1,0] op_sel_hi:[1,1,1]
	v_pk_fma_f32 v[28:29], v[44:45], v[10:11], v[28:29] op_sel:[0,1,0] op_sel_hi:[1,1,1]
	v_cvt_pk_f32_fp8_e32 v[46:47], v129
	v_cvt_pk_f32_fp8_sdwa v[48:49], v129 src0_sel:WORD_1
	v_pk_fma_f32 v[30:31], v[46:47], v[10:11], v[30:31] op_sel:[0,1,0] op_sel_hi:[1,1,1]
	v_pk_fma_f32 v[32:33], v[48:49], v[10:11], v[32:33] op_sel:[0,1,0] op_sel_hi:[1,1,1]
	v_cvt_pk_f32_fp8_e32 v[42:43], v130
	v_cvt_pk_f32_fp8_sdwa v[44:45], v130 src0_sel:WORD_1
	v_pk_fma_f32 v[34:35], v[42:43], v[10:11], v[34:35] op_sel:[0,1,0] op_sel_hi:[1,1,1]
	v_pk_fma_f32 v[36:37], v[44:45], v[10:11], v[36:37] op_sel:[0,1,0] op_sel_hi:[1,1,1]
	v_cvt_pk_f32_fp8_e32 v[46:47], v131
	v_cvt_pk_f32_fp8_sdwa v[48:49], v131 src0_sel:WORD_1
	v_pk_fma_f32 v[38:39], v[46:47], v[10:11], v[38:39] op_sel:[0,1,0] op_sel_hi:[1,1,1]
	v_pk_fma_f32 v[40:41], v[48:49], v[10:11], v[40:41] op_sel:[0,1,0] op_sel_hi:[1,1,1]
	v_cvt_pk_f32_fp8_e32 v[42:43], v132
	v_cvt_pk_f32_fp8_sdwa v[44:45], v132 src0_sel:WORD_1
	v_pk_fma_f32 v[26:27], v[42:43], v[12:13], v[26:27] op_sel_hi:[1,0,1]
	v_pk_fma_f32 v[28:29], v[44:45], v[12:13], v[28:29] op_sel_hi:[1,0,1]
	v_cvt_pk_f32_fp8_e32 v[46:47], v133
	v_cvt_pk_f32_fp8_sdwa v[48:49], v133 src0_sel:WORD_1
	v_pk_fma_f32 v[30:31], v[46:47], v[12:13], v[30:31] op_sel_hi:[1,0,1]
	v_pk_fma_f32 v[32:33], v[48:49], v[12:13], v[32:33] op_sel_hi:[1,0,1]
	v_cvt_pk_f32_fp8_e32 v[42:43], v134
	v_cvt_pk_f32_fp8_sdwa v[44:45], v134 src0_sel:WORD_1
	v_pk_fma_f32 v[34:35], v[42:43], v[12:13], v[34:35] op_sel_hi:[1,0,1]
	v_pk_fma_f32 v[36:37], v[44:45], v[12:13], v[36:37] op_sel_hi:[1,0,1]
	v_cvt_pk_f32_fp8_e32 v[46:47], v135
	v_cvt_pk_f32_fp8_sdwa v[48:49], v135 src0_sel:WORD_1
	v_pk_fma_f32 v[38:39], v[46:47], v[12:13], v[38:39] op_sel_hi:[1,0,1]
	v_pk_fma_f32 v[40:41], v[48:49], v[12:13], v[40:41] op_sel_hi:[1,0,1]
	v_cvt_pk_f32_fp8_e32 v[42:43], v136
	v_cvt_pk_f32_fp8_sdwa v[44:45], v136 src0_sel:WORD_1
	v_pk_fma_f32 v[26:27], v[42:43], v[12:13], v[26:27] op_sel:[0,1,0] op_sel_hi:[1,1,1]
	v_pk_fma_f32 v[28:29], v[44:45], v[12:13], v[28:29] op_sel:[0,1,0] op_sel_hi:[1,1,1]
	v_cvt_pk_f32_fp8_e32 v[46:47], v137
	v_cvt_pk_f32_fp8_sdwa v[48:49], v137 src0_sel:WORD_1
	v_pk_fma_f32 v[30:31], v[46:47], v[12:13], v[30:31] op_sel:[0,1,0] op_sel_hi:[1,1,1]
	v_pk_fma_f32 v[32:33], v[48:49], v[12:13], v[32:33] op_sel:[0,1,0] op_sel_hi:[1,1,1]
	v_cvt_pk_f32_fp8_e32 v[42:43], v138
	v_cvt_pk_f32_fp8_sdwa v[44:45], v138 src0_sel:WORD_1
	v_pk_fma_f32 v[34:35], v[42:43], v[12:13], v[34:35] op_sel:[0,1,0] op_sel_hi:[1,1,1]
	v_pk_fma_f32 v[36:37], v[44:45], v[12:13], v[36:37] op_sel:[0,1,0] op_sel_hi:[1,1,1]
	v_cvt_pk_f32_fp8_e32 v[46:47], v139
	v_cvt_pk_f32_fp8_sdwa v[48:49], v139 src0_sel:WORD_1
	v_pk_fma_f32 v[38:39], v[46:47], v[12:13], v[38:39] op_sel:[0,1,0] op_sel_hi:[1,1,1]
	v_pk_fma_f32 v[40:41], v[48:49], v[12:13], v[40:41] op_sel:[0,1,0] op_sel_hi:[1,1,1]
	v_cvt_pk_f32_fp8_e32 v[42:43], v140
	v_cvt_pk_f32_fp8_sdwa v[44:45], v140 src0_sel:WORD_1
	v_pk_fma_f32 v[26:27], v[42:43], v[14:15], v[26:27] op_sel_hi:[1,0,1]
	v_pk_fma_f32 v[28:29], v[44:45], v[14:15], v[28:29] op_sel_hi:[1,0,1]
	v_cvt_pk_f32_fp8_e32 v[46:47], v141
	v_cvt_pk_f32_fp8_sdwa v[48:49], v141 src0_sel:WORD_1
	v_pk_fma_f32 v[30:31], v[46:47], v[14:15], v[30:31] op_sel_hi:[1,0,1]
	v_pk_fma_f32 v[32:33], v[48:49], v[14:15], v[32:33] op_sel_hi:[1,0,1]
	v_cvt_pk_f32_fp8_e32 v[42:43], v142
	v_cvt_pk_f32_fp8_sdwa v[44:45], v142 src0_sel:WORD_1
	v_pk_fma_f32 v[34:35], v[42:43], v[14:15], v[34:35] op_sel_hi:[1,0,1]
	v_pk_fma_f32 v[36:37], v[44:45], v[14:15], v[36:37] op_sel_hi:[1,0,1]
	v_cvt_pk_f32_fp8_e32 v[46:47], v143
	v_cvt_pk_f32_fp8_sdwa v[48:49], v143 src0_sel:WORD_1
	v_pk_fma_f32 v[38:39], v[46:47], v[14:15], v[38:39] op_sel_hi:[1,0,1]
	v_pk_fma_f32 v[40:41], v[48:49], v[14:15], v[40:41] op_sel_hi:[1,0,1]
	v_cvt_pk_f32_fp8_e32 v[42:43], v144
	v_cvt_pk_f32_fp8_sdwa v[44:45], v144 src0_sel:WORD_1
	v_pk_fma_f32 v[26:27], v[42:43], v[14:15], v[26:27] op_sel:[0,1,0] op_sel_hi:[1,1,1]
	v_pk_fma_f32 v[28:29], v[44:45], v[14:15], v[28:29] op_sel:[0,1,0] op_sel_hi:[1,1,1]
	v_cvt_pk_f32_fp8_e32 v[46:47], v145
	v_cvt_pk_f32_fp8_sdwa v[48:49], v145 src0_sel:WORD_1
	v_pk_fma_f32 v[30:31], v[46:47], v[14:15], v[30:31] op_sel:[0,1,0] op_sel_hi:[1,1,1]
	v_pk_fma_f32 v[32:33], v[48:49], v[14:15], v[32:33] op_sel:[0,1,0] op_sel_hi:[1,1,1]
	v_cvt_pk_f32_fp8_e32 v[42:43], v146
	v_cvt_pk_f32_fp8_sdwa v[44:45], v146 src0_sel:WORD_1
	v_pk_fma_f32 v[34:35], v[42:43], v[14:15], v[34:35] op_sel:[0,1,0] op_sel_hi:[1,1,1]
	v_pk_fma_f32 v[36:37], v[44:45], v[14:15], v[36:37] op_sel:[0,1,0] op_sel_hi:[1,1,1]
	v_cvt_pk_f32_fp8_e32 v[46:47], v147
	v_cvt_pk_f32_fp8_sdwa v[48:49], v147 src0_sel:WORD_1
	v_pk_fma_f32 v[38:39], v[46:47], v[14:15], v[38:39] op_sel:[0,1,0] op_sel_hi:[1,1,1]
	v_pk_fma_f32 v[40:41], v[48:49], v[14:15], v[40:41] op_sel:[0,1,0] op_sel_hi:[1,1,1]
	v_cvt_pk_f32_fp8_e32 v[42:43], v148
	v_cvt_pk_f32_fp8_sdwa v[44:45], v148 src0_sel:WORD_1
	v_pk_fma_f32 v[26:27], v[42:43], v[16:17], v[26:27] op_sel_hi:[1,0,1]
	v_pk_fma_f32 v[28:29], v[44:45], v[16:17], v[28:29] op_sel_hi:[1,0,1]
	v_cvt_pk_f32_fp8_e32 v[46:47], v149
	v_cvt_pk_f32_fp8_sdwa v[48:49], v149 src0_sel:WORD_1
	v_pk_fma_f32 v[30:31], v[46:47], v[16:17], v[30:31] op_sel_hi:[1,0,1]
	v_pk_fma_f32 v[32:33], v[48:49], v[16:17], v[32:33] op_sel_hi:[1,0,1]
	v_cvt_pk_f32_fp8_e32 v[42:43], v150
	v_cvt_pk_f32_fp8_sdwa v[44:45], v150 src0_sel:WORD_1
	v_pk_fma_f32 v[34:35], v[42:43], v[16:17], v[34:35] op_sel_hi:[1,0,1]
	v_pk_fma_f32 v[36:37], v[44:45], v[16:17], v[36:37] op_sel_hi:[1,0,1]
	v_cvt_pk_f32_fp8_e32 v[46:47], v151
	v_cvt_pk_f32_fp8_sdwa v[48:49], v151 src0_sel:WORD_1
	v_pk_fma_f32 v[38:39], v[46:47], v[16:17], v[38:39] op_sel_hi:[1,0,1]
	v_pk_fma_f32 v[40:41], v[48:49], v[16:17], v[40:41] op_sel_hi:[1,0,1]
	v_cvt_pk_f32_fp8_e32 v[42:43], v152
	v_cvt_pk_f32_fp8_sdwa v[44:45], v152 src0_sel:WORD_1
	v_pk_fma_f32 v[26:27], v[42:43], v[16:17], v[26:27] op_sel:[0,1,0] op_sel_hi:[1,1,1]
	v_pk_fma_f32 v[28:29], v[44:45], v[16:17], v[28:29] op_sel:[0,1,0] op_sel_hi:[1,1,1]
	v_cvt_pk_f32_fp8_e32 v[46:47], v153
	v_cvt_pk_f32_fp8_sdwa v[48:49], v153 src0_sel:WORD_1
	v_pk_fma_f32 v[30:31], v[46:47], v[16:17], v[30:31] op_sel:[0,1,0] op_sel_hi:[1,1,1]
	v_pk_fma_f32 v[32:33], v[48:49], v[16:17], v[32:33] op_sel:[0,1,0] op_sel_hi:[1,1,1]
	v_cvt_pk_f32_fp8_e32 v[42:43], v154
	v_cvt_pk_f32_fp8_sdwa v[44:45], v154 src0_sel:WORD_1
	v_pk_fma_f32 v[34:35], v[42:43], v[16:17], v[34:35] op_sel:[0,1,0] op_sel_hi:[1,1,1]
	v_pk_fma_f32 v[36:37], v[44:45], v[16:17], v[36:37] op_sel:[0,1,0] op_sel_hi:[1,1,1]
	v_cvt_pk_f32_fp8_e32 v[46:47], v155
	v_cvt_pk_f32_fp8_sdwa v[48:49], v155 src0_sel:WORD_1
	v_pk_fma_f32 v[38:39], v[46:47], v[16:17], v[38:39] op_sel:[0,1,0] op_sel_hi:[1,1,1]
	v_pk_fma_f32 v[40:41], v[48:49], v[16:17], v[40:41] op_sel:[0,1,0] op_sel_hi:[1,1,1]
	v_cvt_pk_f32_fp8_e32 v[42:43], v156
	v_cvt_pk_f32_fp8_sdwa v[44:45], v156 src0_sel:WORD_1
	v_pk_fma_f32 v[26:27], v[42:43], v[18:19], v[26:27] op_sel_hi:[1,0,1]
	v_pk_fma_f32 v[28:29], v[44:45], v[18:19], v[28:29] op_sel_hi:[1,0,1]
	v_cvt_pk_f32_fp8_e32 v[46:47], v157
	v_cvt_pk_f32_fp8_sdwa v[48:49], v157 src0_sel:WORD_1
	v_pk_fma_f32 v[30:31], v[46:47], v[18:19], v[30:31] op_sel_hi:[1,0,1]
	v_pk_fma_f32 v[32:33], v[48:49], v[18:19], v[32:33] op_sel_hi:[1,0,1]
	v_cvt_pk_f32_fp8_e32 v[42:43], v158
	v_cvt_pk_f32_fp8_sdwa v[44:45], v158 src0_sel:WORD_1
	v_pk_fma_f32 v[34:35], v[42:43], v[18:19], v[34:35] op_sel_hi:[1,0,1]
	v_pk_fma_f32 v[36:37], v[44:45], v[18:19], v[36:37] op_sel_hi:[1,0,1]
	v_cvt_pk_f32_fp8_e32 v[46:47], v159
	v_cvt_pk_f32_fp8_sdwa v[48:49], v159 src0_sel:WORD_1
	v_pk_fma_f32 v[38:39], v[46:47], v[18:19], v[38:39] op_sel_hi:[1,0,1]
	v_pk_fma_f32 v[40:41], v[48:49], v[18:19], v[40:41] op_sel_hi:[1,0,1]
	v_cvt_pk_f32_fp8_e32 v[42:43], v160
	v_cvt_pk_f32_fp8_sdwa v[44:45], v160 src0_sel:WORD_1
	v_pk_fma_f32 v[26:27], v[42:43], v[18:19], v[26:27] op_sel:[0,1,0] op_sel_hi:[1,1,1]
	v_pk_fma_f32 v[28:29], v[44:45], v[18:19], v[28:29] op_sel:[0,1,0] op_sel_hi:[1,1,1]
	v_cvt_pk_f32_fp8_e32 v[46:47], v161
	v_cvt_pk_f32_fp8_sdwa v[48:49], v161 src0_sel:WORD_1
	v_pk_fma_f32 v[30:31], v[46:47], v[18:19], v[30:31] op_sel:[0,1,0] op_sel_hi:[1,1,1]
	v_pk_fma_f32 v[32:33], v[48:49], v[18:19], v[32:33] op_sel:[0,1,0] op_sel_hi:[1,1,1]
	v_cvt_pk_f32_fp8_e32 v[42:43], v162
	v_cvt_pk_f32_fp8_sdwa v[44:45], v162 src0_sel:WORD_1
	v_pk_fma_f32 v[34:35], v[42:43], v[18:19], v[34:35] op_sel:[0,1,0] op_sel_hi:[1,1,1]
	v_pk_fma_f32 v[36:37], v[44:45], v[18:19], v[36:37] op_sel:[0,1,0] op_sel_hi:[1,1,1]
	v_cvt_pk_f32_fp8_e32 v[46:47], v163
	v_cvt_pk_f32_fp8_sdwa v[48:49], v163 src0_sel:WORD_1
	v_pk_fma_f32 v[38:39], v[46:47], v[18:19], v[38:39] op_sel:[0,1,0] op_sel_hi:[1,1,1]
	v_pk_fma_f32 v[40:41], v[48:49], v[18:19], v[40:41] op_sel:[0,1,0] op_sel_hi:[1,1,1]
	v_cvt_pk_f32_fp8_e32 v[42:43], v164
	v_cvt_pk_f32_fp8_sdwa v[44:45], v164 src0_sel:WORD_1
	v_pk_fma_f32 v[26:27], v[42:43], v[20:21], v[26:27] op_sel_hi:[1,0,1]
	v_pk_fma_f32 v[28:29], v[44:45], v[20:21], v[28:29] op_sel_hi:[1,0,1]
	v_cvt_pk_f32_fp8_e32 v[46:47], v165
	v_cvt_pk_f32_fp8_sdwa v[48:49], v165 src0_sel:WORD_1
	v_pk_fma_f32 v[30:31], v[46:47], v[20:21], v[30:31] op_sel_hi:[1,0,1]
	v_pk_fma_f32 v[32:33], v[48:49], v[20:21], v[32:33] op_sel_hi:[1,0,1]
	v_cvt_pk_f32_fp8_e32 v[42:43], v166
	v_cvt_pk_f32_fp8_sdwa v[44:45], v166 src0_sel:WORD_1
	v_pk_fma_f32 v[34:35], v[42:43], v[20:21], v[34:35] op_sel_hi:[1,0,1]
	v_pk_fma_f32 v[36:37], v[44:45], v[20:21], v[36:37] op_sel_hi:[1,0,1]
	v_cvt_pk_f32_fp8_e32 v[46:47], v167
	v_cvt_pk_f32_fp8_sdwa v[48:49], v167 src0_sel:WORD_1
	v_pk_fma_f32 v[38:39], v[46:47], v[20:21], v[38:39] op_sel_hi:[1,0,1]
	v_pk_fma_f32 v[40:41], v[48:49], v[20:21], v[40:41] op_sel_hi:[1,0,1]
	v_cvt_pk_f32_fp8_e32 v[42:43], v168
	v_cvt_pk_f32_fp8_sdwa v[44:45], v168 src0_sel:WORD_1
	v_pk_fma_f32 v[26:27], v[42:43], v[20:21], v[26:27] op_sel:[0,1,0] op_sel_hi:[1,1,1]
	v_pk_fma_f32 v[28:29], v[44:45], v[20:21], v[28:29] op_sel:[0,1,0] op_sel_hi:[1,1,1]
	v_cvt_pk_f32_fp8_e32 v[46:47], v169
	v_cvt_pk_f32_fp8_sdwa v[48:49], v169 src0_sel:WORD_1
	v_pk_fma_f32 v[30:31], v[46:47], v[20:21], v[30:31] op_sel:[0,1,0] op_sel_hi:[1,1,1]
	v_pk_fma_f32 v[32:33], v[48:49], v[20:21], v[32:33] op_sel:[0,1,0] op_sel_hi:[1,1,1]
; __device__ __forceinline__ float wsum(float v) { v = dpp_row_sum16(v); v += __shfl_xor(v, 16); v += __shfl_xor(v, 32); return v; }
; __device__ __forceinline__ void phase5(const Params& p, char* smem, const bool store_x = true) {
;     ...
;     float x2[16];
; #pragma unroll
;     for (int i = 0; i < 4; i++) {
;       const float4 xv = i == 0 ? xv0 : i == 1 ? xv1 : i == 2 ? xv2 : xv3;
;       x2[4 * i] = xv.x + o2[2 * i].x; x2[4 * i + 1] = xv.y + o2[2 * i].y; x2[4 * i + 2] = xv.z + o2[2 * i + 1].x; x2[4 * i + 3] = xv.w + o2[2 * i + 1].y;
;     }
;     float ss = 0.f;
; #pragma unroll
;     for (int i = 0; i < 16; i++) ss += x2[i] * x2[i];
;     ss = wsum(ss);
;     const float rs = rsqrtf(ss * (1.f / 1024.f) + EPSF);
;     if (store_x) {
; #pragma unroll
;       for (int i = 0; i < 4; i++) *(float4*)(xr + i * 4) = make_float4(x2[4 * i], x2[4 * i + 1], x2[4 * i + 2], x2[4 * i + 3]);
;     }
;     unsigned hp[8];
; #pragma unroll
;     for (int i = 0; i < 4; i++) {
;       const float4 g = *(const float4*)(p.g_ple + lane * 16 + i * 4);
;       hp[2 * i] = pack2(x2[4 * i] * rs * g.x, x2[4 * i + 1] * rs * g.y);
;       hp[2 * i + 1] = pack2(x2[4 * i + 2] * rs * g.z, x2[4 * i + 3] * rs * g.w);
;     }
;     *(uint4*)(H3 + (size_t)tok * 1024 + lane * 16) = make_uint4(hp[0], hp[1], hp[2], hp[3]);
;     *(uint4*)(H3 + (size_t)tok * 1024 + lane * 16 + 8) = make_uint4(hp[4], hp[5], hp[6], hp[7]);
	v_cvt_pk_f32_fp8_e32 v[42:43], v170
	v_cvt_pk_f32_fp8_sdwa v[44:45], v170 src0_sel:WORD_1
	v_pk_fma_f32 v[34:35], v[42:43], v[20:21], v[34:35] op_sel:[0,1,0] op_sel_hi:[1,1,1]
	v_pk_fma_f32 v[36:37], v[44:45], v[20:21], v[36:37] op_sel:[0,1,0] op_sel_hi:[1,1,1]
	v_cvt_pk_f32_fp8_e32 v[46:47], v171
	v_cvt_pk_f32_fp8_sdwa v[48:49], v171 src0_sel:WORD_1
	v_pk_fma_f32 v[38:39], v[46:47], v[20:21], v[38:39] op_sel:[0,1,0] op_sel_hi:[1,1,1]
	v_pk_fma_f32 v[40:41], v[48:49], v[20:21], v[40:41] op_sel:[0,1,0] op_sel_hi:[1,1,1]
	v_cvt_pk_f32_fp8_e32 v[42:43], v172
	v_cvt_pk_f32_fp8_sdwa v[44:45], v172 src0_sel:WORD_1
	v_pk_fma_f32 v[26:27], v[42:43], v[22:23], v[26:27] op_sel_hi:[1,0,1]
	v_pk_fma_f32 v[28:29], v[44:45], v[22:23], v[28:29] op_sel_hi:[1,0,1]
	v_cvt_pk_f32_fp8_e32 v[46:47], v173
	v_cvt_pk_f32_fp8_sdwa v[48:49], v173 src0_sel:WORD_1
	v_pk_fma_f32 v[30:31], v[46:47], v[22:23], v[30:31] op_sel_hi:[1,0,1]
	v_pk_fma_f32 v[32:33], v[48:49], v[22:23], v[32:33] op_sel_hi:[1,0,1]
	v_cvt_pk_f32_fp8_e32 v[42:43], v174
	v_cvt_pk_f32_fp8_sdwa v[44:45], v174 src0_sel:WORD_1
	v_pk_fma_f32 v[34:35], v[42:43], v[22:23], v[34:35] op_sel_hi:[1,0,1]
	v_pk_fma_f32 v[36:37], v[44:45], v[22:23], v[36:37] op_sel_hi:[1,0,1]
	v_cvt_pk_f32_fp8_e32 v[46:47], v175
	v_cvt_pk_f32_fp8_sdwa v[48:49], v175 src0_sel:WORD_1
	v_pk_fma_f32 v[38:39], v[46:47], v[22:23], v[38:39] op_sel_hi:[1,0,1]
	v_pk_fma_f32 v[40:41], v[48:49], v[22:23], v[40:41] op_sel_hi:[1,0,1]
	v_cvt_pk_f32_fp8_e32 v[42:43], v176
	v_cvt_pk_f32_fp8_sdwa v[44:45], v176 src0_sel:WORD_1
	v_pk_fma_f32 v[26:27], v[42:43], v[22:23], v[26:27] op_sel:[0,1,0] op_sel_hi:[1,1,1]
	v_pk_fma_f32 v[28:29], v[44:45], v[22:23], v[28:29] op_sel:[0,1,0] op_sel_hi:[1,1,1]
	v_cvt_pk_f32_fp8_e32 v[46:47], v177
	v_cvt_pk_f32_fp8_sdwa v[48:49], v177 src0_sel:WORD_1
	v_pk_fma_f32 v[30:31], v[46:47], v[22:23], v[30:31] op_sel:[0,1,0] op_sel_hi:[1,1,1]
	v_pk_fma_f32 v[32:33], v[48:49], v[22:23], v[32:33] op_sel:[0,1,0] op_sel_hi:[1,1,1]
	v_cvt_pk_f32_fp8_e32 v[42:43], v178
	v_cvt_pk_f32_fp8_sdwa v[44:45], v178 src0_sel:WORD_1
	v_pk_fma_f32 v[34:35], v[42:43], v[22:23], v[34:35] op_sel:[0,1,0] op_sel_hi:[1,1,1]
	v_pk_fma_f32 v[36:37], v[44:45], v[22:23], v[36:37] op_sel:[0,1,0] op_sel_hi:[1,1,1]
	v_cvt_pk_f32_fp8_e32 v[46:47], v179
	v_cvt_pk_f32_fp8_sdwa v[48:49], v179 src0_sel:WORD_1
	v_pk_fma_f32 v[38:39], v[46:47], v[22:23], v[38:39] op_sel:[0,1,0] op_sel_hi:[1,1,1]
	v_pk_fma_f32 v[40:41], v[48:49], v[22:23], v[40:41] op_sel:[0,1,0] op_sel_hi:[1,1,1]
	v_cvt_pk_f32_fp8_e32 v[42:43], v180
	v_cvt_pk_f32_fp8_sdwa v[44:45], v180 src0_sel:WORD_1
	v_pk_fma_f32 v[26:27], v[42:43], v[24:25], v[26:27] op_sel_hi:[1,0,1]
	v_pk_fma_f32 v[28:29], v[44:45], v[24:25], v[28:29] op_sel_hi:[1,0,1]
	v_cvt_pk_f32_fp8_e32 v[46:47], v181
	v_cvt_pk_f32_fp8_sdwa v[48:49], v181 src0_sel:WORD_1
	v_pk_fma_f32 v[30:31], v[46:47], v[24:25], v[30:31] op_sel_hi:[1,0,1]
	v_pk_fma_f32 v[32:33], v[48:49], v[24:25], v[32:33] op_sel_hi:[1,0,1]
	v_cvt_pk_f32_fp8_e32 v[42:43], v182
	v_cvt_pk_f32_fp8_sdwa v[44:45], v182 src0_sel:WORD_1
	v_pk_fma_f32 v[34:35], v[42:43], v[24:25], v[34:35] op_sel_hi:[1,0,1]
	v_pk_fma_f32 v[36:37], v[44:45], v[24:25], v[36:37] op_sel_hi:[1,0,1]
	v_cvt_pk_f32_fp8_e32 v[46:47], v183
	v_cvt_pk_f32_fp8_sdwa v[48:49], v183 src0_sel:WORD_1
	v_pk_fma_f32 v[38:39], v[46:47], v[24:25], v[38:39] op_sel_hi:[1,0,1]
	v_pk_fma_f32 v[40:41], v[48:49], v[24:25], v[40:41] op_sel_hi:[1,0,1]
	v_cvt_pk_f32_fp8_e32 v[42:43], v184
	v_cvt_pk_f32_fp8_sdwa v[44:45], v184 src0_sel:WORD_1
	v_pk_fma_f32 v[26:27], v[42:43], v[24:25], v[26:27] op_sel:[0,1,0] op_sel_hi:[1,1,1]
	v_pk_fma_f32 v[28:29], v[44:45], v[24:25], v[28:29] op_sel:[0,1,0] op_sel_hi:[1,1,1]
	v_cvt_pk_f32_fp8_e32 v[46:47], v185
	v_cvt_pk_f32_fp8_sdwa v[48:49], v185 src0_sel:WORD_1
	v_pk_fma_f32 v[30:31], v[46:47], v[24:25], v[30:31] op_sel:[0,1,0] op_sel_hi:[1,1,1]
	v_pk_fma_f32 v[32:33], v[48:49], v[24:25], v[32:33] op_sel:[0,1,0] op_sel_hi:[1,1,1]
	v_cvt_pk_f32_fp8_e32 v[42:43], v186
	v_cvt_pk_f32_fp8_sdwa v[44:45], v186 src0_sel:WORD_1
	v_pk_fma_f32 v[34:35], v[42:43], v[24:25], v[34:35] op_sel:[0,1,0] op_sel_hi:[1,1,1]
	v_pk_fma_f32 v[36:37], v[44:45], v[24:25], v[36:37] op_sel:[0,1,0] op_sel_hi:[1,1,1]
	v_cvt_pk_f32_fp8_e32 v[46:47], v187
	v_cvt_pk_f32_fp8_sdwa v[48:49], v187 src0_sel:WORD_1
	v_pk_fma_f32 v[38:39], v[46:47], v[24:25], v[38:39] op_sel:[0,1,0] op_sel_hi:[1,1,1]
	v_pk_fma_f32 v[40:41], v[48:49], v[24:25], v[40:41] op_sel:[0,1,0] op_sel_hi:[1,1,1]
	s_nop 1
	v_permlane32_swap_b32_e32 v26, v34
	v_permlane32_swap_b32_e32 v27, v35
	v_permlane32_swap_b32_e32 v28, v36
	v_permlane32_swap_b32_e32 v29, v37
	v_permlane32_swap_b32_e32 v30, v38
	v_permlane32_swap_b32_e32 v31, v39
	v_permlane32_swap_b32_e32 v32, v40
	v_permlane32_swap_b32_e32 v33, v41
	v_add_f32_e32 v26, v26, v34
	v_add_f32_e32 v27, v27, v35
	v_add_f32_e32 v28, v28, v36
	v_add_f32_e32 v29, v29, v37
	v_add_f32_e32 v30, v30, v38
	v_add_f32_e32 v31, v31, v39
	v_add_f32_e32 v32, v32, v40
	v_add_f32_e32 v33, v33, v41
	s_nop 1
	v_permlane16_swap_b32_e32 v26, v30
	v_permlane16_swap_b32_e32 v27, v31
	v_permlane16_swap_b32_e32 v28, v32
	v_permlane16_swap_b32_e32 v29, v33
	v_add_f32_e32 v26, v26, v30
	v_add_f32_e32 v27, v27, v31
	v_add_f32_e32 v28, v28, v32
	v_add_f32_e32 v29, v29, v33
	s_lshl_b32 s11, s12, 12
	v_add_u32_e32 v6, s11, v3
	v_add_f32_dpp v42, v26, v26 row_ror:8 row_mask:0xf bank_mask:0xf
	v_add_f32_dpp v43, v28, v28 row_ror:8 row_mask:0xf bank_mask:0xf
	v_add_f32_dpp v44, v27, v27 row_ror:8 row_mask:0xf bank_mask:0xf
	v_add_f32_dpp v45, v29, v29 row_ror:8 row_mask:0xf bank_mask:0xf
	v_cndmask_b32_e64 v46, v42, v43, s[14:15]
	v_cndmask_b32_e64 v47, v44, v45, s[14:15]
	v_add_f32_e32 v46, v52, v46
	v_add_f32_e32 v47, v53, v47
	global_store_dwordx2 v6, v[46:47], s[6:7]
	v_pk_mul_f32 v[42:43], v[46:47], v[56:57]
	s_lshl_b32 s11, s12, 11
	v_add_u32_e32 v8, s11, v9
	v_cvt_pk_bf16_f32 v42, v42, v43
	global_store_dword v8, v42, s[36:37]
	v_mul_f32_e32 v48, v46, v46
	v_fmac_f32_e32 v48, v47, v47
	s_lshl_b32 s11, s12, 2
	s_add_u32 s11, s11, 0x1100000
	v_mov_b32_e32 v7, s11
	v_add_f32_dpp v48, v48, v48 quad_perm:[1,0,3,2] row_mask:0xf bank_mask:0xf
	s_nop 1
	v_add_f32_dpp v48, v48, v48 quad_perm:[2,3,0,1] row_mask:0xf bank_mask:0xf
	s_nop 1
	v_add_f32_dpp v48, v48, v48 row_half_mirror row_mask:0xf bank_mask:0xf
	s_nop 1
	v_add_f32_dpp v48, v48, v48 row_mirror row_mask:0xf bank_mask:0xf
	s_nop 1
	v_add_f32_dpp v48, v48, v48 row_bcast:15 row_mask:0xa bank_mask:0xf
	s_nop 1
	v_add_f32_dpp v48, v48, v48 row_bcast:31 row_mask:0xc bank_mask:0xf
	s_nop 1
	s_mov_b32 exec_lo, 0
	s_brev_b32 exec_hi, 1
	global_atomic_add_f32 v7, v48, s[4:5]
	s_mov_b64 exec, -1
; #define P5_LOAD(A, TAB, j0)                                                                \
;   _Pragma("unroll") for (int q = 0; q < 16; q++) {                                         \
;     A[q] = ((const uint4*)((TAB) + (size_t)widx[(j0) + q] * 1024))[lane];                  \
;   }
; __device__ __forceinline__ void phase5(const Params& p, char* smem, const bool store_x = true) {
;     ...
; #pragma unroll 1
;     for (int j0 = 0; j0 < 128; j0 += 32) {
;       P5_LOAD(A1, EV, j0 + 16)
;       P5_COMPUTE_V(A0, j0)
;       if (j0 + 32 < 128) { P5_LOAD(A0, EV, j0 + 32) }
;       P5_COMPUTE_V(A1, j0 + 16)
;     }
.Lp5v_skip1:
	s_add_u32 s10, s8, s27
	s_min_u32 s10, s10, s13
	s_lshl_b32 s18, s10, 10
	s_add_u32 s11, s16, 8
	s_and_b32 s11, s11, 7
	s_lshl_b32 s11, s11, 10
	s_add_u32 s11, s11, s17
	s_mov_b32 m0, s11
	v_lshl_add_u64 v[4:5], v[58:59], 0, s[18:19]
	global_load_lds_dwordx4 v[4:5], off
	s_add_u32 s11, s16, 4
	s_and_b32 s11, s11, 7
	s_lshl_b32 s11, s11, 10
	v_add_u32_e32 v8, s11, v2
	ds_read_b128 v[10:13], v8 offset:0
	ds_read_b128 v[14:17], v8 offset:16
	ds_read_b128 v[18:21], v8 offset:32
	ds_read_b128 v[22:25], v8 offset:48
	s_add_u32 s10, s8, s23
	s_min_u32 s10, s10, s13
	s_lshl_b32 s11, s10, 12
	v_add_u32_e32 v6, s11, v3
	global_load_dwordx2 v[52:53], v6, s[6:7]
	s_waitcnt lgkmcnt(0)
	v_add_u32_e32 v10, v10, v1
	global_load_dwordx4 v[124:127], v10, s[2:3]
	v_add_u32_e32 v11, v11, v1
	global_load_dwordx4 v[128:131], v11, s[2:3]
	v_add_u32_e32 v12, v12, v1
	global_load_dwordx4 v[132:135], v12, s[2:3]
	v_add_u32_e32 v13, v13, v1
	global_load_dwordx4 v[136:139], v13, s[2:3]
	v_add_u32_e32 v14, v14, v1
	global_load_dwordx4 v[140:143], v14, s[2:3]
	v_add_u32_e32 v15, v15, v1
	global_load_dwordx4 v[144:147], v15, s[2:3]
	v_add_u32_e32 v16, v16, v1
	global_load_dwordx4 v[148:151], v16, s[2:3]
	v_add_u32_e32 v17, v17, v1
	global_load_dwordx4 v[152:155], v17, s[2:3]
	v_add_u32_e32 v18, v18, v1
	global_load_dwordx4 v[156:159], v18, s[2:3]
	v_add_u32_e32 v19, v19, v1
	global_load_dwordx4 v[160:163], v19, s[2:3]
	v_add_u32_e32 v20, v20, v1
	global_load_dwordx4 v[164:167], v20, s[2:3]
	v_add_u32_e32 v21, v21, v1
	global_load_dwordx4 v[168:171], v21, s[2:3]
	v_add_u32_e32 v22, v22, v1
	global_load_dwordx4 v[172:175], v22, s[2:3]
	v_add_u32_e32 v23, v23, v1
	global_load_dwordx4 v[176:179], v23, s[2:3]
	v_add_u32_e32 v24, v24, v1
	global_load_dwordx4 v[180:183], v24, s[2:3]
	v_add_u32_e32 v25, v25, v1
	global_load_dwordx4 v[184:187], v25, s[2:3]
	s_add_u32 s11, s16, 2
	s_and_b32 s11, s11, 7
	s_lshl_b32 s11, s11, 10
	v_add_u32_e32 v8, s11, v2
	ds_read_b128 v[10:13], v8 offset:512
	ds_read_b128 v[14:17], v8 offset:528
	ds_read_b128 v[18:21], v8 offset:544
	ds_read_b128 v[22:25], v8 offset:560
	s_add_u32 s12, s8, s21
	s_waitcnt vmcnt(42) lgkmcnt(0)
	s_cmp_lt_u32 s12, 0x4200
	s_cbranch_scc0 .Lp5v_skip2
	v_cvt_pk_f32_fp8_e32 v[42:43], v188
	v_cvt_pk_f32_fp8_sdwa v[44:45], v188 src0_sel:WORD_1
	v_pk_mul_f32 v[26:27], v[42:43], v[10:11] op_sel_hi:[1,0]
	v_pk_mul_f32 v[28:29], v[44:45], v[10:11] op_sel_hi:[1,0]
	v_cvt_pk_f32_fp8_e32 v[46:47], v189
	v_cvt_pk_f32_fp8_sdwa v[48:49], v189 src0_sel:WORD_1
	v_pk_mul_f32 v[30:31], v[46:47], v[10:11] op_sel_hi:[1,0]
	v_pk_mul_f32 v[32:33], v[48:49], v[10:11] op_sel_hi:[1,0]
	v_cvt_pk_f32_fp8_e32 v[42:43], v190
	v_cvt_pk_f32_fp8_sdwa v[44:45], v190 src0_sel:WORD_1
	v_pk_mul_f32 v[34:35], v[42:43], v[10:11] op_sel_hi:[1,0]
	v_pk_mul_f32 v[36:37], v[44:45], v[10:11] op_sel_hi:[1,0]
	v_cvt_pk_f32_fp8_e32 v[46:47], v191
	v_cvt_pk_f32_fp8_sdwa v[48:49], v191 src0_sel:WORD_1
	v_pk_mul_f32 v[38:39], v[46:47], v[10:11] op_sel_hi:[1,0]
	v_pk_mul_f32 v[40:41], v[48:49], v[10:11] op_sel_hi:[1,0]
	v_cvt_pk_f32_fp8_e32 v[42:43], v192
	v_cvt_pk_f32_fp8_sdwa v[44:45], v192 src0_sel:WORD_1
	v_pk_fma_f32 v[26:27], v[42:43], v[10:11], v[26:27] op_sel:[0,1,0] op_sel_hi:[1,1,1]
	v_pk_fma_f32 v[28:29], v[44:45], v[10:11], v[28:29] op_sel:[0,1,0] op_sel_hi:[1,1,1]
	v_cvt_pk_f32_fp8_e32 v[46:47], v193
	v_cvt_pk_f32_fp8_sdwa v[48:49], v193 src0_sel:WORD_1
	v_pk_fma_f32 v[30:31], v[46:47], v[10:11], v[30:31] op_sel:[0,1,0] op_sel_hi:[1,1,1]
	v_pk_fma_f32 v[32:33], v[48:49], v[10:11], v[32:33] op_sel:[0,1,0] op_sel_hi:[1,1,1]
	v_cvt_pk_f32_fp8_e32 v[42:43], v194
	v_cvt_pk_f32_fp8_sdwa v[44:45], v194 src0_sel:WORD_1
	v_pk_fma_f32 v[34:35], v[42:43], v[10:11], v[34:35] op_sel:[0,1,0] op_sel_hi:[1,1,1]
	v_pk_fma_f32 v[36:37], v[44:45], v[10:11], v[36:37] op_sel:[0,1,0] op_sel_hi:[1,1,1]
	v_cvt_pk_f32_fp8_e32 v[46:47], v195
	v_cvt_pk_f32_fp8_sdwa v[48:49], v195 src0_sel:WORD_1
	v_pk_fma_f32 v[38:39], v[46:47], v[10:11], v[38:39] op_sel:[0,1,0] op_sel_hi:[1,1,1]
	v_pk_fma_f32 v[40:41], v[48:49], v[10:11], v[40:41] op_sel:[0,1,0] op_sel_hi:[1,1,1]
	v_cvt_pk_f32_fp8_e32 v[42:43], v196
	v_cvt_pk_f32_fp8_sdwa v[44:45], v196 src0_sel:WORD_1
	v_pk_fma_f32 v[26:27], v[42:43], v[12:13], v[26:27] op_sel_hi:[1,0,1]
	v_pk_fma_f32 v[28:29], v[44:45], v[12:13], v[28:29] op_sel_hi:[1,0,1]
	v_cvt_pk_f32_fp8_e32 v[46:47], v197
	v_cvt_pk_f32_fp8_sdwa v[48:49], v197 src0_sel:WORD_1
	v_pk_fma_f32 v[30:31], v[46:47], v[12:13], v[30:31] op_sel_hi:[1,0,1]
	v_pk_fma_f32 v[32:33], v[48:49], v[12:13], v[32:33] op_sel_hi:[1,0,1]
	v_cvt_pk_f32_fp8_e32 v[42:43], v198
	v_cvt_pk_f32_fp8_sdwa v[44:45], v198 src0_sel:WORD_1
	v_pk_fma_f32 v[34:35], v[42:43], v[12:13], v[34:35] op_sel_hi:[1,0,1]
	v_pk_fma_f32 v[36:37], v[44:45], v[12:13], v[36:37] op_sel_hi:[1,0,1]
	v_cvt_pk_f32_fp8_e32 v[46:47], v199
	v_cvt_pk_f32_fp8_sdwa v[48:49], v199 src0_sel:WORD_1
	v_pk_fma_f32 v[38:39], v[46:47], v[12:13], v[38:39] op_sel_hi:[1,0,1]
	v_pk_fma_f32 v[40:41], v[48:49], v[12:13], v[40:41] op_sel_hi:[1,0,1]
	v_cvt_pk_f32_fp8_e32 v[42:43], v200
	v_cvt_pk_f32_fp8_sdwa v[44:45], v200 src0_sel:WORD_1
	v_pk_fma_f32 v[26:27], v[42:43], v[12:13], v[26:27] op_sel:[0,1,0] op_sel_hi:[1,1,1]
	v_pk_fma_f32 v[28:29], v[44:45], v[12:13], v[28:29] op_sel:[0,1,0] op_sel_hi:[1,1,1]
	v_cvt_pk_f32_fp8_e32 v[46:47], v201
	v_cvt_pk_f32_fp8_sdwa v[48:49], v201 src0_sel:WORD_1
	v_pk_fma_f32 v[30:31], v[46:47], v[12:13], v[30:31] op_sel:[0,1,0] op_sel_hi:[1,1,1]
	v_pk_fma_f32 v[32:33], v[48:49], v[12:13], v[32:33] op_sel:[0,1,0] op_sel_hi:[1,1,1]
	v_cvt_pk_f32_fp8_e32 v[42:43], v202
	v_cvt_pk_f32_fp8_sdwa v[44:45], v202 src0_sel:WORD_1
	v_pk_fma_f32 v[34:35], v[42:43], v[12:13], v[34:35] op_sel:[0,1,0] op_sel_hi:[1,1,1]
	v_pk_fma_f32 v[36:37], v[44:45], v[12:13], v[36:37] op_sel:[0,1,0] op_sel_hi:[1,1,1]
	v_cvt_pk_f32_fp8_e32 v[46:47], v203
	v_cvt_pk_f32_fp8_sdwa v[48:49], v203 src0_sel:WORD_1
	v_pk_fma_f32 v[38:39], v[46:47], v[12:13], v[38:39] op_sel:[0,1,0] op_sel_hi:[1,1,1]
	v_pk_fma_f32 v[40:41], v[48:49], v[12:13], v[40:41] op_sel:[0,1,0] op_sel_hi:[1,1,1]
	v_cvt_pk_f32_fp8_e32 v[42:43], v204
	v_cvt_pk_f32_fp8_sdwa v[44:45], v204 src0_sel:WORD_1
	v_pk_fma_f32 v[26:27], v[42:43], v[14:15], v[26:27] op_sel_hi:[1,0,1]
	v_pk_fma_f32 v[28:29], v[44:45], v[14:15], v[28:29] op_sel_hi:[1,0,1]
	v_cvt_pk_f32_fp8_e32 v[46:47], v205
	v_cvt_pk_f32_fp8_sdwa v[48:49], v205 src0_sel:WORD_1
	v_pk_fma_f32 v[30:31], v[46:47], v[14:15], v[30:31] op_sel_hi:[1,0,1]
	v_pk_fma_f32 v[32:33], v[48:49], v[14:15], v[32:33] op_sel_hi:[1,0,1]
	v_cvt_pk_f32_fp8_e32 v[42:43], v206
	v_cvt_pk_f32_fp8_sdwa v[44:45], v206 src0_sel:WORD_1
	v_pk_fma_f32 v[34:35], v[42:43], v[14:15], v[34:35] op_sel_hi:[1,0,1]
	v_pk_fma_f32 v[36:37], v[44:45], v[14:15], v[36:37] op_sel_hi:[1,0,1]
	v_cvt_pk_f32_fp8_e32 v[46:47], v207
	v_cvt_pk_f32_fp8_sdwa v[48:49], v207 src0_sel:WORD_1
	v_pk_fma_f32 v[38:39], v[46:47], v[14:15], v[38:39] op_sel_hi:[1,0,1]
	v_pk_fma_f32 v[40:41], v[48:49], v[14:15], v[40:41] op_sel_hi:[1,0,1]
	v_cvt_pk_f32_fp8_e32 v[42:43], v208
	v_cvt_pk_f32_fp8_sdwa v[44:45], v208 src0_sel:WORD_1
	v_pk_fma_f32 v[26:27], v[42:43], v[14:15], v[26:27] op_sel:[0,1,0] op_sel_hi:[1,1,1]
	v_pk_fma_f32 v[28:29], v[44:45], v[14:15], v[28:29] op_sel:[0,1,0] op_sel_hi:[1,1,1]
	v_cvt_pk_f32_fp8_e32 v[46:47], v209
	v_cvt_pk_f32_fp8_sdwa v[48:49], v209 src0_sel:WORD_1
	v_pk_fma_f32 v[30:31], v[46:47], v[14:15], v[30:31] op_sel:[0,1,0] op_sel_hi:[1,1,1]
	v_pk_fma_f32 v[32:33], v[48:49], v[14:15], v[32:33] op_sel:[0,1,0] op_sel_hi:[1,1,1]
	v_cvt_pk_f32_fp8_e32 v[42:43], v210
	v_cvt_pk_f32_fp8_sdwa v[44:45], v210 src0_sel:WORD_1
	v_pk_fma_f32 v[34:35], v[42:43], v[14:15], v[34:35] op_sel:[0,1,0] op_sel_hi:[1,1,1]
	v_pk_fma_f32 v[36:37], v[44:45], v[14:15], v[36:37] op_sel:[0,1,0] op_sel_hi:[1,1,1]
	v_cvt_pk_f32_fp8_e32 v[46:47], v211
	v_cvt_pk_f32_fp8_sdwa v[48:49], v211 src0_sel:WORD_1
	v_pk_fma_f32 v[38:39], v[46:47], v[14:15], v[38:39] op_sel:[0,1,0] op_sel_hi:[1,1,1]
	v_pk_fma_f32 v[40:41], v[48:49], v[14:15], v[40:41] op_sel:[0,1,0] op_sel_hi:[1,1,1]
	v_cvt_pk_f32_fp8_e32 v[42:43], v212
	v_cvt_pk_f32_fp8_sdwa v[44:45], v212 src0_sel:WORD_1
	v_pk_fma_f32 v[26:27], v[42:43], v[16:17], v[26:27] op_sel_hi:[1,0,1]
	v_pk_fma_f32 v[28:29], v[44:45], v[16:17], v[28:29] op_sel_hi:[1,0,1]
	v_cvt_pk_f32_fp8_e32 v[46:47], v213
	v_cvt_pk_f32_fp8_sdwa v[48:49], v213 src0_sel:WORD_1
	v_pk_fma_f32 v[30:31], v[46:47], v[16:17], v[30:31] op_sel_hi:[1,0,1]
	v_pk_fma_f32 v[32:33], v[48:49], v[16:17], v[32:33] op_sel_hi:[1,0,1]
	v_cvt_pk_f32_fp8_e32 v[42:43], v214
	v_cvt_pk_f32_fp8_sdwa v[44:45], v214 src0_sel:WORD_1
	v_pk_fma_f32 v[34:35], v[42:43], v[16:17], v[34:35] op_sel_hi:[1,0,1]
	v_pk_fma_f32 v[36:37], v[44:45], v[16:17], v[36:37] op_sel_hi:[1,0,1]
	v_cvt_pk_f32_fp8_e32 v[46:47], v215
	v_cvt_pk_f32_fp8_sdwa v[48:49], v215 src0_sel:WORD_1
	v_pk_fma_f32 v[38:39], v[46:47], v[16:17], v[38:39] op_sel_hi:[1,0,1]
	v_pk_fma_f32 v[40:41], v[48:49], v[16:17], v[40:41] op_sel_hi:[1,0,1]
	v_cvt_pk_f32_fp8_e32 v[42:43], v216
	v_cvt_pk_f32_fp8_sdwa v[44:45], v216 src0_sel:WORD_1
	v_pk_fma_f32 v[26:27], v[42:43], v[16:17], v[26:27] op_sel:[0,1,0] op_sel_hi:[1,1,1]
	v_pk_fma_f32 v[28:29], v[44:45], v[16:17], v[28:29] op_sel:[0,1,0] op_sel_hi:[1,1,1]
	v_cvt_pk_f32_fp8_e32 v[46:47], v217
	v_cvt_pk_f32_fp8_sdwa v[48:49], v217 src0_sel:WORD_1
	v_pk_fma_f32 v[30:31], v[46:47], v[16:17], v[30:31] op_sel:[0,1,0] op_sel_hi:[1,1,1]
	v_pk_fma_f32 v[32:33], v[48:49], v[16:17], v[32:33] op_sel:[0,1,0] op_sel_hi:[1,1,1]
	v_cvt_pk_f32_fp8_e32 v[42:43], v218
	v_cvt_pk_f32_fp8_sdwa v[44:45], v218 src0_sel:WORD_1
	v_pk_fma_f32 v[34:35], v[42:43], v[16:17], v[34:35] op_sel:[0,1,0] op_sel_hi:[1,1,1]
	v_pk_fma_f32 v[36:37], v[44:45], v[16:17], v[36:37] op_sel:[0,1,0] op_sel_hi:[1,1,1]
	v_cvt_pk_f32_fp8_e32 v[46:47], v219
	v_cvt_pk_f32_fp8_sdwa v[48:49], v219 src0_sel:WORD_1
	v_pk_fma_f32 v[38:39], v[46:47], v[16:17], v[38:39] op_sel:[0,1,0] op_sel_hi:[1,1,1]
	v_pk_fma_f32 v[40:41], v[48:49], v[16:17], v[40:41] op_sel:[0,1,0] op_sel_hi:[1,1,1]
	v_cvt_pk_f32_fp8_e32 v[42:43], v220
	v_cvt_pk_f32_fp8_sdwa v[44:45], v220 src0_sel:WORD_1
	v_pk_fma_f32 v[26:27], v[42:43], v[18:19], v[26:27] op_sel_hi:[1,0,1]
	v_pk_fma_f32 v[28:29], v[44:45], v[18:19], v[28:29] op_sel_hi:[1,0,1]
	v_cvt_pk_f32_fp8_e32 v[46:47], v221
	v_cvt_pk_f32_fp8_sdwa v[48:49], v221 src0_sel:WORD_1
	v_pk_fma_f32 v[30:31], v[46:47], v[18:19], v[30:31] op_sel_hi:[1,0,1]
	v_pk_fma_f32 v[32:33], v[48:49], v[18:19], v[32:33] op_sel_hi:[1,0,1]
	v_cvt_pk_f32_fp8_e32 v[42:43], v222
	v_cvt_pk_f32_fp8_sdwa v[44:45], v222 src0_sel:WORD_1
	v_pk_fma_f32 v[34:35], v[42:43], v[18:19], v[34:35] op_sel_hi:[1,0,1]
	v_pk_fma_f32 v[36:37], v[44:45], v[18:19], v[36:37] op_sel_hi:[1,0,1]
	v_cvt_pk_f32_fp8_e32 v[46:47], v223
	v_cvt_pk_f32_fp8_sdwa v[48:49], v223 src0_sel:WORD_1
	v_pk_fma_f32 v[38:39], v[46:47], v[18:19], v[38:39] op_sel_hi:[1,0,1]
	v_pk_fma_f32 v[40:41], v[48:49], v[18:19], v[40:41] op_sel_hi:[1,0,1]
	v_cvt_pk_f32_fp8_e32 v[42:43], v224
	v_cvt_pk_f32_fp8_sdwa v[44:45], v224 src0_sel:WORD_1
	v_pk_fma_f32 v[26:27], v[42:43], v[18:19], v[26:27] op_sel:[0,1,0] op_sel_hi:[1,1,1]
	v_pk_fma_f32 v[28:29], v[44:45], v[18:19], v[28:29] op_sel:[0,1,0] op_sel_hi:[1,1,1]
	v_cvt_pk_f32_fp8_e32 v[46:47], v225
	v_cvt_pk_f32_fp8_sdwa v[48:49], v225 src0_sel:WORD_1
	v_pk_fma_f32 v[30:31], v[46:47], v[18:19], v[30:31] op_sel:[0,1,0] op_sel_hi:[1,1,1]
	v_pk_fma_f32 v[32:33], v[48:49], v[18:19], v[32:33] op_sel:[0,1,0] op_sel_hi:[1,1,1]
	v_cvt_pk_f32_fp8_e32 v[42:43], v226
	v_cvt_pk_f32_fp8_sdwa v[44:45], v226 src0_sel:WORD_1
	v_pk_fma_f32 v[34:35], v[42:43], v[18:19], v[34:35] op_sel:[0,1,0] op_sel_hi:[1,1,1]
	v_pk_fma_f32 v[36:37], v[44:45], v[18:19], v[36:37] op_sel:[0,1,0] op_sel_hi:[1,1,1]
	v_cvt_pk_f32_fp8_e32 v[46:47], v227
	v_cvt_pk_f32_fp8_sdwa v[48:49], v227 src0_sel:WORD_1
	v_pk_fma_f32 v[38:39], v[46:47], v[18:19], v[38:39] op_sel:[0,1,0] op_sel_hi:[1,1,1]
	v_pk_fma_f32 v[40:41], v[48:49], v[18:19], v[40:41] op_sel:[0,1,0] op_sel_hi:[1,1,1]
	v_cvt_pk_f32_fp8_e32 v[42:43], v228
	v_cvt_pk_f32_fp8_sdwa v[44:45], v228 src0_sel:WORD_1
	v_pk_fma_f32 v[26:27], v[42:43], v[20:21], v[26:27] op_sel_hi:[1,0,1]
	v_pk_fma_f32 v[28:29], v[44:45], v[20:21], v[28:29] op_sel_hi:[1,0,1]
	v_cvt_pk_f32_fp8_e32 v[46:47], v229
	v_cvt_pk_f32_fp8_sdwa v[48:49], v229 src0_sel:WORD_1
	v_pk_fma_f32 v[30:31], v[46:47], v[20:21], v[30:31] op_sel_hi:[1,0,1]
	v_pk_fma_f32 v[32:33], v[48:49], v[20:21], v[32:33] op_sel_hi:[1,0,1]
	v_cvt_pk_f32_fp8_e32 v[42:43], v230
	v_cvt_pk_f32_fp8_sdwa v[44:45], v230 src0_sel:WORD_1
	v_pk_fma_f32 v[34:35], v[42:43], v[20:21], v[34:35] op_sel_hi:[1,0,1]
	v_pk_fma_f32 v[36:37], v[44:45], v[20:21], v[36:37] op_sel_hi:[1,0,1]
	v_cvt_pk_f32_fp8_e32 v[46:47], v231
	v_cvt_pk_f32_fp8_sdwa v[48:49], v231 src0_sel:WORD_1
	v_pk_fma_f32 v[38:39], v[46:47], v[20:21], v[38:39] op_sel_hi:[1,0,1]
	v_pk_fma_f32 v[40:41], v[48:49], v[20:21], v[40:41] op_sel_hi:[1,0,1]
	v_cvt_pk_f32_fp8_e32 v[42:43], v232
	v_cvt_pk_f32_fp8_sdwa v[44:45], v232 src0_sel:WORD_1
	v_pk_fma_f32 v[26:27], v[42:43], v[20:21], v[26:27] op_sel:[0,1,0] op_sel_hi:[1,1,1]
	v_pk_fma_f32 v[28:29], v[44:45], v[20:21], v[28:29] op_sel:[0,1,0] op_sel_hi:[1,1,1]
	v_cvt_pk_f32_fp8_e32 v[46:47], v233
	v_cvt_pk_f32_fp8_sdwa v[48:49], v233 src0_sel:WORD_1
	v_pk_fma_f32 v[30:31], v[46:47], v[20:21], v[30:31] op_sel:[0,1,0] op_sel_hi:[1,1,1]
	v_pk_fma_f32 v[32:33], v[48:49], v[20:21], v[32:33] op_sel:[0,1,0] op_sel_hi:[1,1,1]
	v_cvt_pk_f32_fp8_e32 v[42:43], v234
	v_cvt_pk_f32_fp8_sdwa v[44:45], v234 src0_sel:WORD_1
	v_pk_fma_f32 v[34:35], v[42:43], v[20:21], v[34:35] op_sel:[0,1,0] op_sel_hi:[1,1,1]
	v_pk_fma_f32 v[36:37], v[44:45], v[20:21], v[36:37] op_sel:[0,1,0] op_sel_hi:[1,1,1]
	v_cvt_pk_f32_fp8_e32 v[46:47], v235
	v_cvt_pk_f32_fp8_sdwa v[48:49], v235 src0_sel:WORD_1
	v_pk_fma_f32 v[38:39], v[46:47], v[20:21], v[38:39] op_sel:[0,1,0] op_sel_hi:[1,1,1]
	v_pk_fma_f32 v[40:41], v[48:49], v[20:21], v[40:41] op_sel:[0,1,0] op_sel_hi:[1,1,1]
	v_cvt_pk_f32_fp8_e32 v[42:43], v236
	v_cvt_pk_f32_fp8_sdwa v[44:45], v236 src0_sel:WORD_1
	v_pk_fma_f32 v[26:27], v[42:43], v[22:23], v[26:27] op_sel_hi:[1,0,1]
	v_pk_fma_f32 v[28:29], v[44:45], v[22:23], v[28:29] op_sel_hi:[1,0,1]
	v_cvt_pk_f32_fp8_e32 v[46:47], v237
	v_cvt_pk_f32_fp8_sdwa v[48:49], v237 src0_sel:WORD_1
	v_pk_fma_f32 v[30:31], v[46:47], v[22:23], v[30:31] op_sel_hi:[1,0,1]
	v_pk_fma_f32 v[32:33], v[48:49], v[22:23], v[32:33] op_sel_hi:[1,0,1]
	v_cvt_pk_f32_fp8_e32 v[42:43], v238
	v_cvt_pk_f32_fp8_sdwa v[44:45], v238 src0_sel:WORD_1
	v_pk_fma_f32 v[34:35], v[42:43], v[22:23], v[34:35] op_sel_hi:[1,0,1]
	v_pk_fma_f32 v[36:37], v[44:45], v[22:23], v[36:37] op_sel_hi:[1,0,1]
	v_cvt_pk_f32_fp8_e32 v[46:47], v239
	v_cvt_pk_f32_fp8_sdwa v[48:49], v239 src0_sel:WORD_1
	v_pk_fma_f32 v[38:39], v[46:47], v[22:23], v[38:39] op_sel_hi:[1,0,1]
	v_pk_fma_f32 v[40:41], v[48:49], v[22:23], v[40:41] op_sel_hi:[1,0,1]
	v_cvt_pk_f32_fp8_e32 v[42:43], v240
	v_cvt_pk_f32_fp8_sdwa v[44:45], v240 src0_sel:WORD_1
	v_pk_fma_f32 v[26:27], v[42:43], v[22:23], v[26:27] op_sel:[0,1,0] op_sel_hi:[1,1,1]
	v_pk_fma_f32 v[28:29], v[44:45], v[22:23], v[28:29] op_sel:[0,1,0] op_sel_hi:[1,1,1]
	v_cvt_pk_f32_fp8_e32 v[46:47], v241
	v_cvt_pk_f32_fp8_sdwa v[48:49], v241 src0_sel:WORD_1
	v_pk_fma_f32 v[30:31], v[46:47], v[22:23], v[30:31] op_sel:[0,1,0] op_sel_hi:[1,1,1]
	v_pk_fma_f32 v[32:33], v[48:49], v[22:23], v[32:33] op_sel:[0,1,0] op_sel_hi:[1,1,1]
	v_cvt_pk_f32_fp8_e32 v[42:43], v242
	v_cvt_pk_f32_fp8_sdwa v[44:45], v242 src0_sel:WORD_1
	v_pk_fma_f32 v[34:35], v[42:43], v[22:23], v[34:35] op_sel:[0,1,0] op_sel_hi:[1,1,1]
	v_pk_fma_f32 v[36:37], v[44:45], v[22:23], v[36:37] op_sel:[0,1,0] op_sel_hi:[1,1,1]
	v_cvt_pk_f32_fp8_e32 v[46:47], v243
	v_cvt_pk_f32_fp8_sdwa v[48:49], v243 src0_sel:WORD_1
; __device__ __forceinline__ void phase5(const Params& p, char* smem, const bool store_x = true) {
;     ...
;     float x2[16];
; #pragma unroll
;     for (int i = 0; i < 4; i++) {
;       const float4 xv = i == 0 ? xv0 : i == 1 ? xv1 : i == 2 ? xv2 : xv3;
;       x2[4 * i] = xv.x + o2[2 * i].x; x2[4 * i + 1] = xv.y + o2[2 * i].y; x2[4 * i + 2] = xv.z + o2[2 * i + 1].x; x2[4 * i + 3] = xv.w + o2[2 * i + 1].y;
;     }
;     float ss = 0.f;
; #pragma unroll
;     for (int i = 0; i < 16; i++) ss += x2[i] * x2[i];
;     ss = wsum(ss);
;     const float rs = rsqrtf(ss * (1.f / 1024.f) + EPSF);
;     if (store_x) {
; #pragma unroll
;       for (int i = 0; i < 4; i++) *(float4*)(xr + i * 4) = make_float4(x2[4 * i], x2[4 * i + 1], x2[4 * i + 2], x2[4 * i + 3]);
;     }
;     unsigned hp[8];
; #pragma unroll
;     for (int i = 0; i < 4; i++) {
;       const float4 g = *(const float4*)(p.g_ple + lane * 16 + i * 4);
;       hp[2 * i] = pack2(x2[4 * i] * rs * g.x, x2[4 * i + 1] * rs * g.y);
;       hp[2 * i + 1] = pack2(x2[4 * i + 2] * rs * g.z, x2[4 * i + 3] * rs * g.w);
;     }
;     *(uint4*)(H3 + (size_t)tok * 1024 + lane * 16) = make_uint4(hp[0], hp[1], hp[2], hp[3]);
;     *(uint4*)(H3 + (size_t)tok * 1024 + lane * 16 + 8) = make_uint4(hp[4], hp[5], hp[6], hp[7]);
; __device__ __forceinline__ void xcd_barrier(const XcdBarrier& b) {
;     asm volatile("s_waitcnt vmcnt(0)" ::: "memory");
;     __syncthreads();
;     if (threadIdx.x == 0) {
;         unsigned* bar = b.bar;
;         __builtin_amdgcn_s_waitcnt(0);
;         unsigned nloc = b.st[0], nx = b.st[1];
;         if (nloc == 0u) { xcd_barrier_complete(bar, b.x, nloc, nx); b.st[0] = nloc; b.st[1] = nx; }
;         const unsigned old = xb_add(&bar[XB_XSUB(b.x)], 1u);
;         const unsigned gen = old / nloc;
;         if (old + 1u == (gen + 1u) * nloc) {
;             __builtin_amdgcn_fence(__ATOMIC_RELEASE, "agent");
;             asm volatile("s_waitcnt vmcnt(0)" ::: "memory");
;             const unsigned og = xb_add(&bar[XB_TOP], 1u);
;             const unsigned tg = og / nx;
;             if (og + 1u == (tg + 1u) * nx) xb_add(&bar[XB_TOPGEN], 1u);
;             else XB_SPIN(xb_ld(&bar[XB_TOPGEN]) == tg, bar);
;             __builtin_amdgcn_fence(__ATOMIC_ACQUIRE, "agent");
;             xb_add(&bar[XB_XGEN(b.x)], 1u);
;             asm volatile("s_waitcnt vmcnt(0)" ::: "memory");
;         } else {
	v_pk_fma_f32 v[38:39], v[46:47], v[22:23], v[38:39] op_sel:[0,1,0] op_sel_hi:[1,1,1]
	v_pk_fma_f32 v[40:41], v[48:49], v[22:23], v[40:41] op_sel:[0,1,0] op_sel_hi:[1,1,1]
	v_cvt_pk_f32_fp8_e32 v[42:43], v244
	v_cvt_pk_f32_fp8_sdwa v[44:45], v244 src0_sel:WORD_1
	v_pk_fma_f32 v[26:27], v[42:43], v[24:25], v[26:27] op_sel_hi:[1,0,1]
	v_pk_fma_f32 v[28:29], v[44:45], v[24:25], v[28:29] op_sel_hi:[1,0,1]
	v_cvt_pk_f32_fp8_e32 v[46:47], v245
	v_cvt_pk_f32_fp8_sdwa v[48:49], v245 src0_sel:WORD_1
	v_pk_fma_f32 v[30:31], v[46:47], v[24:25], v[30:31] op_sel_hi:[1,0,1]
	v_pk_fma_f32 v[32:33], v[48:49], v[24:25], v[32:33] op_sel_hi:[1,0,1]
	v_cvt_pk_f32_fp8_e32 v[42:43], v246
	v_cvt_pk_f32_fp8_sdwa v[44:45], v246 src0_sel:WORD_1
	v_pk_fma_f32 v[34:35], v[42:43], v[24:25], v[34:35] op_sel_hi:[1,0,1]
	v_pk_fma_f32 v[36:37], v[44:45], v[24:25], v[36:37] op_sel_hi:[1,0,1]
	v_cvt_pk_f32_fp8_e32 v[46:47], v247
	v_cvt_pk_f32_fp8_sdwa v[48:49], v247 src0_sel:WORD_1
	v_pk_fma_f32 v[38:39], v[46:47], v[24:25], v[38:39] op_sel_hi:[1,0,1]
	v_pk_fma_f32 v[40:41], v[48:49], v[24:25], v[40:41] op_sel_hi:[1,0,1]
	v_cvt_pk_f32_fp8_e32 v[42:43], v248
	v_cvt_pk_f32_fp8_sdwa v[44:45], v248 src0_sel:WORD_1
	v_pk_fma_f32 v[26:27], v[42:43], v[24:25], v[26:27] op_sel:[0,1,0] op_sel_hi:[1,1,1]
	v_pk_fma_f32 v[28:29], v[44:45], v[24:25], v[28:29] op_sel:[0,1,0] op_sel_hi:[1,1,1]
	v_cvt_pk_f32_fp8_e32 v[46:47], v249
	v_cvt_pk_f32_fp8_sdwa v[48:49], v249 src0_sel:WORD_1
	v_pk_fma_f32 v[30:31], v[46:47], v[24:25], v[30:31] op_sel:[0,1,0] op_sel_hi:[1,1,1]
	v_pk_fma_f32 v[32:33], v[48:49], v[24:25], v[32:33] op_sel:[0,1,0] op_sel_hi:[1,1,1]
	v_cvt_pk_f32_fp8_e32 v[42:43], v250
	v_cvt_pk_f32_fp8_sdwa v[44:45], v250 src0_sel:WORD_1
	v_pk_fma_f32 v[34:35], v[42:43], v[24:25], v[34:35] op_sel:[0,1,0] op_sel_hi:[1,1,1]
	v_pk_fma_f32 v[36:37], v[44:45], v[24:25], v[36:37] op_sel:[0,1,0] op_sel_hi:[1,1,1]
	v_cvt_pk_f32_fp8_e32 v[46:47], v251
	v_cvt_pk_f32_fp8_sdwa v[48:49], v251 src0_sel:WORD_1
	v_pk_fma_f32 v[38:39], v[46:47], v[24:25], v[38:39] op_sel:[0,1,0] op_sel_hi:[1,1,1]
	v_pk_fma_f32 v[40:41], v[48:49], v[24:25], v[40:41] op_sel:[0,1,0] op_sel_hi:[1,1,1]
	s_nop 1
	v_permlane32_swap_b32_e32 v26, v34
	v_permlane32_swap_b32_e32 v27, v35
	v_permlane32_swap_b32_e32 v28, v36
	v_permlane32_swap_b32_e32 v29, v37
	v_permlane32_swap_b32_e32 v30, v38
	v_permlane32_swap_b32_e32 v31, v39
	v_permlane32_swap_b32_e32 v32, v40
	v_permlane32_swap_b32_e32 v33, v41
	v_add_f32_e32 v26, v26, v34
	v_add_f32_e32 v27, v27, v35
	v_add_f32_e32 v28, v28, v36
	v_add_f32_e32 v29, v29, v37
	v_add_f32_e32 v30, v30, v38
	v_add_f32_e32 v31, v31, v39
	v_add_f32_e32 v32, v32, v40
	v_add_f32_e32 v33, v33, v41
	s_nop 1
	v_permlane16_swap_b32_e32 v26, v30
	v_permlane16_swap_b32_e32 v27, v31
	v_permlane16_swap_b32_e32 v28, v32
	v_permlane16_swap_b32_e32 v29, v33
	v_add_f32_e32 v26, v26, v30
	v_add_f32_e32 v27, v27, v31
	v_add_f32_e32 v28, v28, v32
	v_add_f32_e32 v29, v29, v33
	s_lshl_b32 s11, s12, 12
	v_add_u32_e32 v6, s11, v3
	v_add_f32_dpp v42, v26, v26 row_ror:8 row_mask:0xf bank_mask:0xf
	v_add_f32_dpp v43, v28, v28 row_ror:8 row_mask:0xf bank_mask:0xf
	v_add_f32_dpp v44, v27, v27 row_ror:8 row_mask:0xf bank_mask:0xf
	v_add_f32_dpp v45, v29, v29 row_ror:8 row_mask:0xf bank_mask:0xf
	v_cndmask_b32_e64 v46, v42, v43, s[14:15]
	v_cndmask_b32_e64 v47, v44, v45, s[14:15]
	v_add_f32_e32 v46, v54, v46
	v_add_f32_e32 v47, v55, v47
	global_store_dwordx2 v6, v[46:47], s[6:7]
	v_pk_mul_f32 v[42:43], v[46:47], v[56:57]
	s_lshl_b32 s11, s12, 11
	v_add_u32_e32 v8, s11, v9
	v_cvt_pk_bf16_f32 v42, v42, v43
	global_store_dword v8, v42, s[36:37]
	v_mul_f32_e32 v48, v46, v46
	v_fmac_f32_e32 v48, v47, v47
	s_lshl_b32 s11, s12, 2
	s_add_u32 s11, s11, 0x1100000
	v_mov_b32_e32 v7, s11
	v_add_f32_dpp v48, v48, v48 quad_perm:[1,0,3,2] row_mask:0xf bank_mask:0xf
	s_nop 1
	v_add_f32_dpp v48, v48, v48 quad_perm:[2,3,0,1] row_mask:0xf bank_mask:0xf
	s_nop 1
	v_add_f32_dpp v48, v48, v48 row_half_mirror row_mask:0xf bank_mask:0xf
	s_nop 1
	v_add_f32_dpp v48, v48, v48 row_mirror row_mask:0xf bank_mask:0xf
	s_nop 1
	v_add_f32_dpp v48, v48, v48 row_bcast:15 row_mask:0xa bank_mask:0xf
	s_nop 1
	v_add_f32_dpp v48, v48, v48 row_bcast:31 row_mask:0xc bank_mask:0xf
	s_nop 1
	s_mov_b32 exec_lo, 0
	s_brev_b32 exec_hi, 1
	global_atomic_add_f32 v7, v48, s[4:5]
	s_mov_b64 exec, -1
.Lp5v_skip2:
	s_add_u32 s8, s8, s22
	s_add_u32 s16, s16, 3
	s_cmp_lt_u32 s8, 0x4200
	s_cbranch_scc1 .Lp5v_loop
	s_waitcnt vmcnt(0)
	s_add_u32 s2, s80, 0x8e35000
	s_addc_u32 s3, s81, 0

; __device__ __forceinline__ float bflo(unsigned u) { return __uint_as_float(u << 16); }
; __device__ __forceinline__ float bfhi(unsigned u) { return __uint_as_float(u & 0xffff0000u); }
; __device__ __forceinline__ float sigmoidf_(float x) { return __builtin_amdgcn_rcpf(1.f + __expf(-x)); }
; __device__ __forceinline__ int rowmap(int e, int lane) { return (e & 3) + 8 * (e >> 2) + 4 * (lane >> 5); }
; __device__ __forceinline__ void phase6(const Params& p, char* smem) {
;     ...
; #pragma unroll
;     for (int i = 0; i < 2; i++)
; #pragma unroll
;       for (int e = 0; e < 16; e++) {
;         const int row = m0 + wm * 64 + i * 32 + rowmap(e, lane);
;         float sq = 0.f;
; #pragma unroll
;         for (int j = 0; j < 2; j++) {
;           const int col = n0 + wn * 64 + j * 32 + (lane & 31);
;           float* xp = X + (size_t)row * 1024 + col;
;           float v = *xp + ((e & 1) ? bfhi(pe[i][j][e >> 1]) : bflo(pe[i][j][e >> 1])) * sigmoidf_(acc1[i][j][e]);
.LBB0_1588:
	s_nop 7
	v_accvgpr_read_b32 v112, a0
	v_accvgpr_read_b32 v113, a1
	v_accvgpr_read_b32 v114, a2
	v_accvgpr_read_b32 v115, a3
	v_accvgpr_read_b32 v116, a4
	v_accvgpr_read_b32 v117, a5
	v_accvgpr_read_b32 v118, a6
	v_accvgpr_read_b32 v119, a7
	v_accvgpr_read_b32 v120, a8
	v_accvgpr_read_b32 v121, a9
	v_accvgpr_read_b32 v122, a10
	v_accvgpr_read_b32 v123, a11
	v_accvgpr_read_b32 v124, a12
	v_accvgpr_read_b32 v125, a13
	v_accvgpr_read_b32 v126, a14
	v_accvgpr_read_b32 v127, a15
	v_accvgpr_read_b32 v96, a32
	v_accvgpr_read_b32 v97, a33
	v_accvgpr_read_b32 v98, a34
	v_accvgpr_read_b32 v99, a35
	v_accvgpr_read_b32 v100, a36
	v_accvgpr_read_b32 v101, a37
	v_accvgpr_read_b32 v102, a38
	v_accvgpr_read_b32 v103, a39
	v_accvgpr_read_b32 v104, a40
	v_accvgpr_read_b32 v105, a41
	v_accvgpr_read_b32 v106, a42
	v_accvgpr_read_b32 v107, a43
	v_accvgpr_read_b32 v108, a44
	v_accvgpr_read_b32 v109, a45
	v_accvgpr_read_b32 v110, a46
	v_accvgpr_read_b32 v111, a47
	v_accvgpr_read_b32 v80, a48
	v_accvgpr_read_b32 v81, a49
	v_accvgpr_read_b32 v82, a50
	v_accvgpr_read_b32 v83, a51
	v_accvgpr_read_b32 v84, a52
	v_accvgpr_read_b32 v85, a53
	v_accvgpr_read_b32 v86, a54
	v_accvgpr_read_b32 v87, a55
	v_accvgpr_read_b32 v88, a56
	v_accvgpr_read_b32 v89, a57
	v_accvgpr_read_b32 v90, a58
	v_accvgpr_read_b32 v91, a59
	v_accvgpr_read_b32 v92, a60
	v_accvgpr_read_b32 v93, a61
	v_accvgpr_read_b32 v94, a62
	v_accvgpr_read_b32 v95, a63
	v_accvgpr_read_b32 v64, a16
	v_accvgpr_read_b32 v65, a17
	v_accvgpr_read_b32 v66, a18
	v_accvgpr_read_b32 v67, a19
	v_accvgpr_read_b32 v68, a20
	v_accvgpr_read_b32 v69, a21
	v_accvgpr_read_b32 v70, a22
	v_accvgpr_read_b32 v71, a23
	v_accvgpr_read_b32 v72, a24
	v_accvgpr_read_b32 v73, a25
	v_accvgpr_read_b32 v74, a26
	v_accvgpr_read_b32 v75, a27
	v_accvgpr_read_b32 v76, a28
	v_accvgpr_read_b32 v77, a29
	v_accvgpr_read_b32 v78, a30
	v_accvgpr_read_b32 v79, a31
	v_add_u32_e32 v206, s8, v215
	v_or_b32_e32 v130, s38, v217
	v_or_b32_e32 v206, v206, v236
	s_add_u32 s98, s80, 0x4cb5000
	s_addc_u32 s99, s81, 0
	v_lshlrev_b32_e32 v154, 2, v206
	global_load_dwordx4 v[238:241], v154, s[98:99]
	global_load_dwordx4 v[242:245], v154, s[98:99] offset:32
	global_load_dwordx4 v[246:249], v154, s[98:99] offset:64
	global_load_dwordx4 v[250:253], v154, s[98:99] offset:96
	global_load_dwordx4 a[224:227], v154, s[98:99] offset:128
	global_load_dwordx4 a[228:231], v154, s[98:99] offset:160
	global_load_dwordx4 a[232:235], v154, s[98:99] offset:192
	global_load_dwordx4 a[236:239], v154, s[98:99] offset:224
	v_lshlrev_b32_e32 v130, 2, v130
	s_nop 0
	v_lshl_add_u64 v[132:133], s[78:79], 0, v[130:131]
	v_add_lshl_u32 v130, v206, 0, 12
	v_lshl_add_u64 v[134:135], v[130:131], 0, v[132:133]
	global_load_dword a0, v[134:135], off
	global_load_dword a1, v[134:135], off offset:128
	v_add_lshl_u32 v130, v206, 1, 12
	v_lshl_add_u64 v[134:135], v[130:131], 0, v[132:133]
	global_load_dword a2, v[134:135], off
	global_load_dword a3, v[134:135], off offset:128
	v_add_lshl_u32 v130, v206, 2, 12
	v_lshl_add_u64 v[134:135], v[130:131], 0, v[132:133]
	global_load_dword a4, v[134:135], off
	global_load_dword a5, v[134:135], off offset:128
	v_add_lshl_u32 v130, v206, 3, 12
	v_lshl_add_u64 v[134:135], v[130:131], 0, v[132:133]
	global_load_dword a6, v[134:135], off
	global_load_dword a7, v[134:135], off offset:128
	v_add_lshl_u32 v130, v206, 8, 12
	v_lshl_add_u64 v[134:135], v[130:131], 0, v[132:133]
	global_load_dword a8, v[134:135], off
	global_load_dword a9, v[134:135], off offset:128
	v_add_lshl_u32 v130, v206, 9, 12
	v_lshl_add_u64 v[134:135], v[130:131], 0, v[132:133]
	global_load_dword a10, v[134:135], off
	global_load_dword a11, v[134:135], off offset:128
	v_add_lshl_u32 v130, v206, 10, 12
	v_lshl_add_u64 v[134:135], v[130:131], 0, v[132:133]
	global_load_dword a12, v[134:135], off
	global_load_dword a13, v[134:135], off offset:128
	v_add_lshl_u32 v130, v206, 11, 12
	v_lshl_add_u64 v[134:135], v[130:131], 0, v[132:133]
	global_load_dword a14, v[134:135], off
	global_load_dword a15, v[134:135], off offset:128
	v_add_lshl_u32 v130, v206, 16, 12
	v_lshl_add_u64 v[134:135], v[130:131], 0, v[132:133]
	global_load_dword a16, v[134:135], off
	global_load_dword a17, v[134:135], off offset:128
	v_add_lshl_u32 v130, v206, 17, 12
	v_lshl_add_u64 v[134:135], v[130:131], 0, v[132:133]
	global_load_dword a18, v[134:135], off
	global_load_dword a19, v[134:135], off offset:128
	v_add_lshl_u32 v130, v206, 18, 12
	v_lshl_add_u64 v[134:135], v[130:131], 0, v[132:133]
	global_load_dword a20, v[134:135], off
	global_load_dword a21, v[134:135], off offset:128
	v_add_lshl_u32 v130, v206, 19, 12
	v_lshl_add_u64 v[134:135], v[130:131], 0, v[132:133]
	global_load_dword a22, v[134:135], off
	global_load_dword a23, v[134:135], off offset:128
	v_add_lshl_u32 v130, v206, 24, 12
	v_lshl_add_u64 v[134:135], v[130:131], 0, v[132:133]
	global_load_dword a24, v[134:135], off
	global_load_dword a25, v[134:135], off offset:128
	v_add_lshl_u32 v130, v206, 25, 12
	v_lshl_add_u64 v[134:135], v[130:131], 0, v[132:133]
	global_load_dword a26, v[134:135], off
	global_load_dword a27, v[134:135], off offset:128
	v_add_lshl_u32 v130, v206, 26, 12
	v_lshl_add_u64 v[134:135], v[130:131], 0, v[132:133]
	global_load_dword a28, v[134:135], off
	global_load_dword a29, v[134:135], off offset:128
	v_add_lshl_u32 v130, v206, 27, 12
	v_lshl_add_u64 v[134:135], v[130:131], 0, v[132:133]
	global_load_dword a30, v[134:135], off
	global_load_dword a31, v[134:135], off offset:128
	v_add_lshl_u32 v130, v206, 32, 12
	v_lshl_add_u64 v[134:135], v[130:131], 0, v[132:133]
	global_load_dword a32, v[134:135], off
; __device__ __forceinline__ float bflo(unsigned u) { return __uint_as_float(u << 16); }
; __device__ __forceinline__ float bfhi(unsigned u) { return __uint_as_float(u & 0xffff0000u); }
; __device__ __forceinline__ float sigmoidf_(float x) { return __builtin_amdgcn_rcpf(1.f + __expf(-x)); }
; __device__ __forceinline__ int rowmap(int e, int lane) { return (e & 3) + 8 * (e >> 2) + 4 * (lane >> 5); }
; __device__ __forceinline__ void phase6(const Params& p, char* smem) {
;     ...
; #pragma unroll
;     for (int i = 0; i < 2; i++)
; #pragma unroll
;       for (int e = 0; e < 16; e++) {
;         const int row = m0 + wm * 64 + i * 32 + rowmap(e, lane);
;         float sq = 0.f;
; #pragma unroll
;         for (int j = 0; j < 2; j++) {
;           const int col = n0 + wn * 64 + j * 32 + (lane & 31);
;           float* xp = X + (size_t)row * 1024 + col;
;           float v = *xp + ((e & 1) ? bfhi(pe[i][j][e >> 1]) : bflo(pe[i][j][e >> 1])) * sigmoidf_(acc1[i][j][e]);
	global_load_dword a33, v[134:135], off offset:128
	v_add_lshl_u32 v130, v206, 33, 12
	v_lshl_add_u64 v[134:135], v[130:131], 0, v[132:133]
	global_load_dword a34, v[134:135], off
	global_load_dword a35, v[134:135], off offset:128
	v_add_lshl_u32 v130, v206, 34, 12
	v_lshl_add_u64 v[134:135], v[130:131], 0, v[132:133]
	global_load_dword a36, v[134:135], off
	global_load_dword a37, v[134:135], off offset:128
	v_add_lshl_u32 v130, v206, 35, 12
	v_lshl_add_u64 v[134:135], v[130:131], 0, v[132:133]
	global_load_dword a38, v[134:135], off
	global_load_dword a39, v[134:135], off offset:128
	v_add_lshl_u32 v130, v206, 40, 12
	v_lshl_add_u64 v[134:135], v[130:131], 0, v[132:133]
	global_load_dword a40, v[134:135], off
	global_load_dword a41, v[134:135], off offset:128
	v_add_lshl_u32 v130, v206, 41, 12
	v_lshl_add_u64 v[134:135], v[130:131], 0, v[132:133]
	global_load_dword a42, v[134:135], off
	global_load_dword a43, v[134:135], off offset:128
	v_add_lshl_u32 v130, v206, 42, 12
	v_lshl_add_u64 v[134:135], v[130:131], 0, v[132:133]
	global_load_dword a44, v[134:135], off
	global_load_dword a45, v[134:135], off offset:128
	v_add_lshl_u32 v130, v206, 43, 12
	v_lshl_add_u64 v[134:135], v[130:131], 0, v[132:133]
	global_load_dword a46, v[134:135], off
	global_load_dword a47, v[134:135], off offset:128
	v_add_lshl_u32 v130, v206, 48, 12
	v_lshl_add_u64 v[134:135], v[130:131], 0, v[132:133]
	global_load_dword a48, v[134:135], off
	global_load_dword a49, v[134:135], off offset:128
	v_add_lshl_u32 v130, v206, 49, 12
	v_lshl_add_u64 v[134:135], v[130:131], 0, v[132:133]
	global_load_dword a50, v[134:135], off
	global_load_dword a51, v[134:135], off offset:128
	v_add_lshl_u32 v130, v206, 50, 12
	v_lshl_add_u64 v[134:135], v[130:131], 0, v[132:133]
	global_load_dword a52, v[134:135], off
	global_load_dword a53, v[134:135], off offset:128
	v_add_lshl_u32 v130, v206, 51, 12
	v_lshl_add_u64 v[134:135], v[130:131], 0, v[132:133]
	global_load_dword a54, v[134:135], off
	global_load_dword a55, v[134:135], off offset:128
	v_add_lshl_u32 v130, v206, 56, 12
	v_lshl_add_u64 v[134:135], v[130:131], 0, v[132:133]
	global_load_dword a56, v[134:135], off
	global_load_dword a57, v[134:135], off offset:128
	v_add_lshl_u32 v130, v206, 57, 12
	v_lshl_add_u64 v[134:135], v[130:131], 0, v[132:133]
	global_load_dword a58, v[134:135], off
	global_load_dword a59, v[134:135], off offset:128
	v_add_lshl_u32 v130, v206, 58, 12
	v_lshl_add_u64 v[134:135], v[130:131], 0, v[132:133]
	global_load_dword a60, v[134:135], off
	global_load_dword a61, v[134:135], off offset:128
	v_add_lshl_u32 v130, v206, 59, 12
	v_lshl_add_u64 v[134:135], v[130:131], 0, v[132:133]
	global_load_dword a62, v[134:135], off
	global_load_dword a63, v[134:135], off offset:128
	s_waitcnt vmcnt(0)
	v_mul_f32_e32 v154, 0x3a800000, v238
	v_add_f32_e32 v154, 0x358637bd, v154
	v_rsq_f32_e32 v154, v154
	s_nop 0
	v_mul_f32_e32 v154, 0xbfb8aa3b, v154
	v_accvgpr_write_b32 a192, v154
	v_mul_f32_e32 v155, 0x3a800000, v239
	v_add_f32_e32 v155, 0x358637bd, v155
	v_rsq_f32_e32 v155, v155
	s_nop 0
	v_mul_f32_e32 v155, 0xbfb8aa3b, v155
	v_accvgpr_write_b32 a193, v155
	v_mul_f32_e32 v154, 0x3a800000, v240
	v_add_f32_e32 v154, 0x358637bd, v154
	v_rsq_f32_e32 v154, v154
	s_nop 0
	v_mul_f32_e32 v154, 0xbfb8aa3b, v154
	v_accvgpr_write_b32 a194, v154
	v_mul_f32_e32 v155, 0x3a800000, v241
	v_add_f32_e32 v155, 0x358637bd, v155
	v_rsq_f32_e32 v155, v155
	s_nop 0
	v_mul_f32_e32 v155, 0xbfb8aa3b, v155
	v_accvgpr_write_b32 a195, v155
	v_mul_f32_e32 v154, 0x3a800000, v242
	v_add_f32_e32 v154, 0x358637bd, v154
	v_rsq_f32_e32 v154, v154
	s_nop 0
	v_mul_f32_e32 v154, 0xbfb8aa3b, v154
	v_accvgpr_write_b32 a196, v154
	v_mul_f32_e32 v155, 0x3a800000, v243
	v_add_f32_e32 v155, 0x358637bd, v155
	v_rsq_f32_e32 v155, v155
	s_nop 0
	v_mul_f32_e32 v155, 0xbfb8aa3b, v155
	v_accvgpr_write_b32 a197, v155
	v_mul_f32_e32 v154, 0x3a800000, v244
	v_add_f32_e32 v154, 0x358637bd, v154
	v_rsq_f32_e32 v154, v154
	s_nop 0
	v_mul_f32_e32 v154, 0xbfb8aa3b, v154
	v_accvgpr_write_b32 a198, v154
	v_mul_f32_e32 v155, 0x3a800000, v245
	v_add_f32_e32 v155, 0x358637bd, v155
	v_rsq_f32_e32 v155, v155
	s_nop 0
	v_mul_f32_e32 v155, 0xbfb8aa3b, v155
	v_accvgpr_write_b32 a199, v155
	v_mul_f32_e32 v154, 0x3a800000, v246
	v_add_f32_e32 v154, 0x358637bd, v154
	v_rsq_f32_e32 v154, v154
	s_nop 0
	v_mul_f32_e32 v154, 0xbfb8aa3b, v154
	v_accvgpr_write_b32 a200, v154
	v_mul_f32_e32 v155, 0x3a800000, v247
	v_add_f32_e32 v155, 0x358637bd, v155
	v_rsq_f32_e32 v155, v155
	s_nop 0
	v_mul_f32_e32 v155, 0xbfb8aa3b, v155
	v_accvgpr_write_b32 a201, v155
	v_mul_f32_e32 v154, 0x3a800000, v248
	v_add_f32_e32 v154, 0x358637bd, v154
	v_rsq_f32_e32 v154, v154
	s_nop 0
	v_mul_f32_e32 v154, 0xbfb8aa3b, v154
	v_accvgpr_write_b32 a202, v154
	v_mul_f32_e32 v155, 0x3a800000, v249
	v_add_f32_e32 v155, 0x358637bd, v155
	v_rsq_f32_e32 v155, v155
	s_nop 0
	v_mul_f32_e32 v155, 0xbfb8aa3b, v155
	v_accvgpr_write_b32 a203, v155
	v_mul_f32_e32 v154, 0x3a800000, v250
	v_add_f32_e32 v154, 0x358637bd, v154
	v_rsq_f32_e32 v154, v154
	s_nop 0
	v_mul_f32_e32 v154, 0xbfb8aa3b, v154
	v_accvgpr_write_b32 a204, v154
	v_mul_f32_e32 v155, 0x3a800000, v251
	v_add_f32_e32 v155, 0x358637bd, v155
	v_rsq_f32_e32 v155, v155
	s_nop 0
	v_mul_f32_e32 v155, 0xbfb8aa3b, v155
	v_accvgpr_write_b32 a205, v155
	v_mul_f32_e32 v154, 0x3a800000, v252
	v_add_f32_e32 v154, 0x358637bd, v154
	v_rsq_f32_e32 v154, v154
	s_nop 0
	v_mul_f32_e32 v154, 0xbfb8aa3b, v154
	v_accvgpr_write_b32 a206, v154
	v_mul_f32_e32 v155, 0x3a800000, v253
	v_add_f32_e32 v155, 0x358637bd, v155
	v_rsq_f32_e32 v155, v155
	s_nop 0
	v_mul_f32_e32 v155, 0xbfb8aa3b, v155
; __device__ __forceinline__ float bflo(unsigned u) { return __uint_as_float(u << 16); }
; __device__ __forceinline__ float bfhi(unsigned u) { return __uint_as_float(u & 0xffff0000u); }
; __device__ __forceinline__ float sum32(float v) { v = dpp_row_sum16(v); v += __shfl_xor(v, 16); return v; }
; __device__ __forceinline__ float sigmoidf_(float x) { return __builtin_amdgcn_rcpf(1.f + __expf(-x)); }
; __device__ __forceinline__ int rowmap(int e, int lane) { return (e & 3) + 8 * (e >> 2) + 4 * (lane >> 5); }
; __device__ __forceinline__ void phase6(const Params& p, char* smem) {
;     ...
; #pragma unroll
;     for (int i = 0; i < 2; i++)
; #pragma unroll
;       for (int e = 0; e < 16; e++) {
;         const int row = m0 + wm * 64 + i * 32 + rowmap(e, lane);
;         float sq = 0.f;
; #pragma unroll
;         for (int j = 0; j < 2; j++) {
;           const int col = n0 + wn * 64 + j * 32 + (lane & 31);
;           float* xp = X + (size_t)row * 1024 + col;
;           float v = *xp + ((e & 1) ? bfhi(pe[i][j][e >> 1]) : bflo(pe[i][j][e >> 1])) * sigmoidf_(acc1[i][j][e]);
;           *xp = v;
;           sq += v * v;
;         }
;         sq = sum32(sq);
;         if ((lane & 31) == 0) atomicAdd(&SSQ3[row], sq);
;       }
	v_accvgpr_write_b32 a207, v155
	v_accvgpr_read_b32 v154, a224
	v_mul_f32_e32 v154, 0x3a800000, v154
	v_add_f32_e32 v154, 0x358637bd, v154
	v_rsq_f32_e32 v154, v154
	s_nop 0
	v_mul_f32_e32 v154, 0xbfb8aa3b, v154
	v_accvgpr_write_b32 a208, v154
	v_accvgpr_read_b32 v155, a225
	v_mul_f32_e32 v155, 0x3a800000, v155
	v_add_f32_e32 v155, 0x358637bd, v155
	v_rsq_f32_e32 v155, v155
	s_nop 0
	v_mul_f32_e32 v155, 0xbfb8aa3b, v155
	v_accvgpr_write_b32 a209, v155
	v_accvgpr_read_b32 v154, a226
	v_mul_f32_e32 v154, 0x3a800000, v154
	v_add_f32_e32 v154, 0x358637bd, v154
	v_rsq_f32_e32 v154, v154
	s_nop 0
	v_mul_f32_e32 v154, 0xbfb8aa3b, v154
	v_accvgpr_write_b32 a210, v154
	v_accvgpr_read_b32 v155, a227
	v_mul_f32_e32 v155, 0x3a800000, v155
	v_add_f32_e32 v155, 0x358637bd, v155
	v_rsq_f32_e32 v155, v155
	s_nop 0
	v_mul_f32_e32 v155, 0xbfb8aa3b, v155
	v_accvgpr_write_b32 a211, v155
	v_accvgpr_read_b32 v154, a228
	v_mul_f32_e32 v154, 0x3a800000, v154
	v_add_f32_e32 v154, 0x358637bd, v154
	v_rsq_f32_e32 v154, v154
	s_nop 0
	v_mul_f32_e32 v154, 0xbfb8aa3b, v154
	v_accvgpr_write_b32 a212, v154
	v_accvgpr_read_b32 v155, a229
	v_mul_f32_e32 v155, 0x3a800000, v155
	v_add_f32_e32 v155, 0x358637bd, v155
	v_rsq_f32_e32 v155, v155
	s_nop 0
	v_mul_f32_e32 v155, 0xbfb8aa3b, v155
	v_accvgpr_write_b32 a213, v155
	v_accvgpr_read_b32 v154, a230
	v_mul_f32_e32 v154, 0x3a800000, v154
	v_add_f32_e32 v154, 0x358637bd, v154
	v_rsq_f32_e32 v154, v154
	s_nop 0
	v_mul_f32_e32 v154, 0xbfb8aa3b, v154
	v_accvgpr_write_b32 a214, v154
	v_accvgpr_read_b32 v155, a231
	v_mul_f32_e32 v155, 0x3a800000, v155
	v_add_f32_e32 v155, 0x358637bd, v155
	v_rsq_f32_e32 v155, v155
	s_nop 0
	v_mul_f32_e32 v155, 0xbfb8aa3b, v155
	v_accvgpr_write_b32 a215, v155
	v_accvgpr_read_b32 v154, a232
	v_mul_f32_e32 v154, 0x3a800000, v154
	v_add_f32_e32 v154, 0x358637bd, v154
	v_rsq_f32_e32 v154, v154
	s_nop 0
	v_mul_f32_e32 v154, 0xbfb8aa3b, v154
	v_accvgpr_write_b32 a216, v154
	v_accvgpr_read_b32 v155, a233
	v_mul_f32_e32 v155, 0x3a800000, v155
	v_add_f32_e32 v155, 0x358637bd, v155
	v_rsq_f32_e32 v155, v155
	s_nop 0
	v_mul_f32_e32 v155, 0xbfb8aa3b, v155
	v_accvgpr_write_b32 a217, v155
	v_accvgpr_read_b32 v154, a234
	v_mul_f32_e32 v154, 0x3a800000, v154
	v_add_f32_e32 v154, 0x358637bd, v154
	v_rsq_f32_e32 v154, v154
	s_nop 0
	v_mul_f32_e32 v154, 0xbfb8aa3b, v154
	v_accvgpr_write_b32 a218, v154
	v_accvgpr_read_b32 v155, a235
	v_mul_f32_e32 v155, 0x3a800000, v155
	v_add_f32_e32 v155, 0x358637bd, v155
	v_rsq_f32_e32 v155, v155
	s_nop 0
	v_mul_f32_e32 v155, 0xbfb8aa3b, v155
	v_accvgpr_write_b32 a219, v155
	v_accvgpr_read_b32 v154, a236
	v_mul_f32_e32 v154, 0x3a800000, v154
	v_add_f32_e32 v154, 0x358637bd, v154
	v_rsq_f32_e32 v154, v154
	s_nop 0
	v_mul_f32_e32 v154, 0xbfb8aa3b, v154
	v_accvgpr_write_b32 a220, v154
	v_accvgpr_read_b32 v155, a237
	v_mul_f32_e32 v155, 0x3a800000, v155
	v_add_f32_e32 v155, 0x358637bd, v155
	v_rsq_f32_e32 v155, v155
	s_nop 0
	v_mul_f32_e32 v155, 0xbfb8aa3b, v155
	v_accvgpr_write_b32 a221, v155
	v_accvgpr_read_b32 v154, a238
	v_mul_f32_e32 v154, 0x3a800000, v154
	v_add_f32_e32 v154, 0x358637bd, v154
	v_rsq_f32_e32 v154, v154
	s_nop 0
	v_mul_f32_e32 v154, 0xbfb8aa3b, v154
	v_accvgpr_write_b32 a222, v154
	v_accvgpr_read_b32 v155, a239
	v_mul_f32_e32 v155, 0x3a800000, v155
	v_add_f32_e32 v155, 0x358637bd, v155
	v_rsq_f32_e32 v155, v155
	s_nop 0
	v_mul_f32_e32 v155, 0xbfb8aa3b, v155
	v_accvgpr_write_b32 a223, v155
	v_cvt_pk_bf16_f32 v49, v48, v49
	v_add_u32_e32 v48, s8, v215
	v_cvt_pk_bf16_f32 v206, v32, v33
	v_or_b32_e32 v32, v48, v236
	v_ashrrev_i32_e32 v33, 31, v32
	v_or_b32_e32 v130, s38, v217
	v_lshlrev_b64 v[132:133], 12, v[32:33]
	v_lshl_add_u64 v[132:133], s[78:79], 0, v[132:133]
	v_lshlrev_b32_e32 v130, 2, v130
	v_lshl_add_u64 v[132:133], v[132:133], 0, v[130:131]
	v_accvgpr_read_b32 v134, a0
	v_accvgpr_read_b32 v155, a192
	v_mul_f32_e32 v112, v155, v112
	v_exp_f32_e32 v112, v112
	v_lshlrev_b32_e32 v135, 16, v206
	v_add_f32_e32 v112, 1.0, v112
	v_rcp_f32_e32 v112, v112
	v_accvgpr_read_b32 v155, a192
	v_mul_f32_e32 v96, v155, v96
	v_exp_f32_e32 v96, v96
	s_nop 0
	v_add_f32_e32 v96, 1.0, v96
	v_rcp_f32_e32 v96, v96
	v_fmac_f32_e32 v134, v112, v135
	v_accvgpr_read_b32 v112, a1
	v_lshlrev_b32_e32 v135, 16, v49
	global_store_dword v[132:133], v134, off
	v_fmac_f32_e32 v112, v96, v135
	v_mul_f32_e32 v96, v112, v112
	v_fmac_f32_e32 v96, v134, v134
	global_store_dword v[132:133], v112, off offset:128
	s_nop 0
	v_add_f32_dpp v96, v96, v96 quad_perm:[1,0,3,2] row_mask:0xf bank_mask:0xf bound_ctrl:1
	s_nop 1
	v_add_f32_dpp v96, v96, v96 quad_perm:[2,3,0,1] row_mask:0xf bank_mask:0xf bound_ctrl:1
	s_nop 1
	v_add_f32_dpp v96, v96, v96 row_half_mirror row_mask:0xf bank_mask:0xf bound_ctrl:1
	s_nop 1
	v_add_f32_dpp v96, v96, v96 row_mirror row_mask:0xf bank_mask:0xf bound_ctrl:1
	ds_bpermute_b32 v112, v237, v96
	s_and_saveexec_b64 s[8:9], s[4:5]
	s_cbranch_execz .LBB0_1590
	s_waitcnt lgkmcnt(0)
	v_add_f32_e32 v96, v96, v112
	v_lshl_add_u64 v[32:33], v[32:33], 2, s[92:93]
	global_atomic_add_f32 v[32:33], v96, off
; __device__ __forceinline__ float bflo(unsigned u) { return __uint_as_float(u << 16); }
; __device__ __forceinline__ float bfhi(unsigned u) { return __uint_as_float(u & 0xffff0000u); }
; __device__ __forceinline__ float sum32(float v) { v = dpp_row_sum16(v); v += __shfl_xor(v, 16); return v; }
; __device__ __forceinline__ float sigmoidf_(float x) { return __builtin_amdgcn_rcpf(1.f + __expf(-x)); }
; __device__ __forceinline__ int rowmap(int e, int lane) { return (e & 3) + 8 * (e >> 2) + 4 * (lane >> 5); }
; __device__ __forceinline__ void phase6(const Params& p, char* smem) {
;     ...
; #pragma unroll
;     for (int i = 0; i < 2; i++)
; #pragma unroll
;       for (int e = 0; e < 16; e++) {
;         const int row = m0 + wm * 64 + i * 32 + rowmap(e, lane);
;         float sq = 0.f;
; #pragma unroll
;         for (int j = 0; j < 2; j++) {
;           const int col = n0 + wn * 64 + j * 32 + (lane & 31);
;           float* xp = X + (size_t)row * 1024 + col;
;           float v = *xp + ((e & 1) ? bfhi(pe[i][j][e >> 1]) : bflo(pe[i][j][e >> 1])) * sigmoidf_(acc1[i][j][e]);
;           *xp = v;
;           sq += v * v;
;         }
;         sq = sum32(sq);
;         if ((lane & 31) == 0) atomicAdd(&SSQ3[row], sq);
;       }
.LBB0_1590:
	s_or_b64 exec, exec, s[8:9]
	v_accvgpr_read_b32 v135, a84
	v_or_b32_e32 v32, v48, v135
	v_ashrrev_i32_e32 v33, 31, v32
	v_lshlrev_b64 v[132:133], 12, v[32:33]
	v_lshl_add_u64 v[132:133], s[78:79], 0, v[132:133]
	v_lshl_add_u64 v[132:133], v[132:133], 0, v[130:131]
	s_waitcnt lgkmcnt(0)
	v_accvgpr_read_b32 v112, a2
	v_accvgpr_read_b32 v134, a3
	v_accvgpr_read_b32 v155, a193
	v_mul_f32_e32 v97, v155, v97
	v_accvgpr_read_b32 v155, a193
	v_mul_f32_e32 v96, v155, v113
	v_exp_f32_e32 v97, v97
	v_exp_f32_e32 v96, v96
	v_and_b32_e32 v49, 0xffff0000, v49
	v_and_b32_e32 v113, 0xffff0000, v206
	v_add_f32_e32 v97, 1.0, v97
	v_add_f32_e32 v96, 1.0, v96
	v_rcp_f32_e32 v97, v97
	v_rcp_f32_e32 v96, v96
	v_fmac_f32_e32 v134, v97, v49
	v_fmac_f32_e32 v112, v96, v113
	v_mul_f32_e32 v49, v134, v134
	v_fmac_f32_e32 v49, v112, v112
	global_store_dword v[132:133], v112, off
	global_store_dword v[132:133], v134, off offset:128
	v_add_f32_dpp v49, v49, v49 quad_perm:[1,0,3,2] row_mask:0xf bank_mask:0xf bound_ctrl:1
	s_nop 1
	v_add_f32_dpp v49, v49, v49 quad_perm:[2,3,0,1] row_mask:0xf bank_mask:0xf bound_ctrl:1
	s_nop 1
	v_add_f32_dpp v49, v49, v49 row_half_mirror row_mask:0xf bank_mask:0xf bound_ctrl:1
	s_nop 1
	v_add_f32_dpp v49, v49, v49 row_mirror row_mask:0xf bank_mask:0xf bound_ctrl:1
	ds_bpermute_b32 v96, v237, v49
	s_mov_b64 s[8:9], exec
	s_and_b64 s[10:11], s[8:9], s[4:5]
	v_accvgpr_read_b32 v132, a85
	v_accvgpr_read_b32 v133, a86
	v_accvgpr_read_b32 v134, a87
	v_accvgpr_read_b32 v148, a88
	v_accvgpr_read_b32 v149, a89
	v_accvgpr_read_b32 v150, a90
	v_accvgpr_read_b32 v151, a91
	v_accvgpr_read_b32 v152, a92
	s_mov_b64 exec, s[10:11]
	s_cbranch_execz .LBB0_1592
	s_waitcnt lgkmcnt(0)
	v_add_f32_e32 v49, v49, v96
	v_lshl_add_u64 v[32:33], v[32:33], 2, s[92:93]
	global_atomic_add_f32 v[32:33], v49, off
.LBB0_1592:
	s_or_b64 exec, exec, s[8:9]
	v_or_b32_e32 v32, v48, v132
	v_ashrrev_i32_e32 v33, 31, v32
	s_waitcnt lgkmcnt(0)
	v_lshlrev_b64 v[96:97], 12, v[32:33]
	v_lshl_add_u64 v[96:97], s[78:79], 0, v[96:97]
	v_lshl_add_u64 v[96:97], v[96:97], 0, v[130:131]
	v_accvgpr_read_b32 v112, a4
	v_accvgpr_read_b32 v113, a5
	v_accvgpr_read_b32 v155, a194
	v_mul_f32_e32 v98, v155, v98
	v_accvgpr_read_b32 v155, a194
	v_mul_f32_e32 v49, v155, v114
	v_exp_f32_e32 v98, v98
	v_exp_f32_e32 v49, v49
	v_cvt_pk_bf16_f32 v34, v34, v35
	v_cvt_pk_bf16_f32 v35, v50, v51
	v_add_f32_e32 v50, 1.0, v98
	v_add_f32_e32 v49, 1.0, v49
	v_rcp_f32_e32 v50, v50
	v_rcp_f32_e32 v49, v49
	v_lshlrev_b32_e32 v98, 16, v35
	v_lshlrev_b32_e32 v51, 16, v34
	v_fmac_f32_e32 v112, v49, v51
	v_fmac_f32_e32 v113, v50, v98
	v_mul_f32_e32 v49, v113, v113
	v_fmac_f32_e32 v49, v112, v112
	global_store_dword v[96:97], v112, off
	global_store_dword v[96:97], v113, off offset:128
	v_add_f32_dpp v49, v49, v49 quad_perm:[1,0,3,2] row_mask:0xf bank_mask:0xf bound_ctrl:1
	s_nop 1
	v_add_f32_dpp v49, v49, v49 quad_perm:[2,3,0,1] row_mask:0xf bank_mask:0xf bound_ctrl:1
	s_nop 1
	v_add_f32_dpp v49, v49, v49 row_half_mirror row_mask:0xf bank_mask:0xf bound_ctrl:1
	s_nop 1
	v_add_f32_dpp v49, v49, v49 row_mirror row_mask:0xf bank_mask:0xf bound_ctrl:1
	ds_bpermute_b32 v50, v237, v49
	s_and_saveexec_b64 s[8:9], s[4:5]
	s_cbranch_execz .LBB0_1594
	s_waitcnt lgkmcnt(0)
	v_add_f32_e32 v49, v49, v50
	v_lshl_add_u64 v[32:33], v[32:33], 2, s[92:93]
	global_atomic_add_f32 v[32:33], v49, off
.LBB0_1594:
	s_or_b64 exec, exec, s[8:9]
	v_or_b32_e32 v32, v48, v133
	v_ashrrev_i32_e32 v33, 31, v32
	s_waitcnt lgkmcnt(0)
	v_lshlrev_b64 v[50:51], 12, v[32:33]
	v_lshl_add_u64 v[50:51], s[78:79], 0, v[50:51]
	v_lshl_add_u64 v[50:51], v[50:51], 0, v[130:131]
	v_accvgpr_read_b32 v49, a6
	v_accvgpr_read_b32 v96, a7
	v_accvgpr_read_b32 v155, a195
	v_mul_f32_e32 v98, v155, v99
	v_accvgpr_read_b32 v155, a195
	v_mul_f32_e32 v97, v155, v115
	v_exp_f32_e32 v98, v98
	v_exp_f32_e32 v97, v97
	v_and_b32_e32 v35, 0xffff0000, v35
	v_and_b32_e32 v34, 0xffff0000, v34
	v_add_f32_e32 v98, 1.0, v98
	v_add_f32_e32 v97, 1.0, v97
	v_rcp_f32_e32 v98, v98
	v_rcp_f32_e32 v97, v97
	v_fmac_f32_e32 v96, v98, v35
	v_fmac_f32_e32 v49, v97, v34
	v_mul_f32_e32 v34, v96, v96
	v_fmac_f32_e32 v34, v49, v49
	global_store_dword v[50:51], v49, off
	global_store_dword v[50:51], v96, off offset:128
	v_add_f32_dpp v34, v34, v34 quad_perm:[1,0,3,2] row_mask:0xf bank_mask:0xf bound_ctrl:1
	s_nop 1
	v_add_f32_dpp v34, v34, v34 quad_perm:[2,3,0,1] row_mask:0xf bank_mask:0xf bound_ctrl:1
	s_nop 1
	v_add_f32_dpp v34, v34, v34 row_half_mirror row_mask:0xf bank_mask:0xf bound_ctrl:1
	s_nop 1
	v_add_f32_dpp v34, v34, v34 row_mirror row_mask:0xf bank_mask:0xf bound_ctrl:1
	ds_bpermute_b32 v35, v237, v34
	s_mov_b64 s[8:9], exec
	s_and_b64 s[10:11], s[8:9], s[4:5]
	v_accvgpr_read_b32 v99, a93
	v_accvgpr_read_b32 v112, a94
	v_accvgpr_read_b32 v113, a95
	v_accvgpr_read_b32 v114, a96
	v_accvgpr_read_b32 v115, a97
	v_accvgpr_read_b32 v153, a98
	s_mov_b64 exec, s[10:11]
	s_cbranch_execz .LBB0_1596
	s_waitcnt lgkmcnt(0)
	v_add_f32_e32 v34, v34, v35
	v_lshl_add_u64 v[32:33], v[32:33], 2, s[92:93]
	global_atomic_add_f32 v[32:33], v34, off
; __device__ __forceinline__ float bflo(unsigned u) { return __uint_as_float(u << 16); }
; __device__ __forceinline__ float bfhi(unsigned u) { return __uint_as_float(u & 0xffff0000u); }
; __device__ __forceinline__ float sum32(float v) { v = dpp_row_sum16(v); v += __shfl_xor(v, 16); return v; }
; __device__ __forceinline__ float sigmoidf_(float x) { return __builtin_amdgcn_rcpf(1.f + __expf(-x)); }
; __device__ __forceinline__ int rowmap(int e, int lane) { return (e & 3) + 8 * (e >> 2) + 4 * (lane >> 5); }
; __device__ __forceinline__ void phase6(const Params& p, char* smem) {
;     ...
;     for (int i = 0; i < 2; i++)
; #pragma unroll
;       for (int e = 0; e < 16; e++) {
;         const int row = m0 + wm * 64 + i * 32 + rowmap(e, lane);
;         float sq = 0.f;
; #pragma unroll
;         for (int j = 0; j < 2; j++) {
;           const int col = n0 + wn * 64 + j * 32 + (lane & 31);
;           float* xp = X + (size_t)row * 1024 + col;
;           float v = *xp + ((e & 1) ? bfhi(pe[i][j][e >> 1]) : bflo(pe[i][j][e >> 1])) * sigmoidf_(acc1[i][j][e]);
;           *xp = v;
;           sq += v * v;
;         }
;         sq = sum32(sq);
;         if ((lane & 31) == 0) atomicAdd(&SSQ3[row], sq);
;       }
.LBB0_1596:
	s_or_b64 exec, exec, s[8:9]
	v_or_b32_e32 v32, v48, v134
	v_ashrrev_i32_e32 v33, 31, v32
	s_waitcnt lgkmcnt(0)
	v_lshlrev_b64 v[34:35], 12, v[32:33]
	v_lshl_add_u64 v[34:35], s[78:79], 0, v[34:35]
	v_lshl_add_u64 v[50:51], v[34:35], 0, v[130:131]
	v_accvgpr_read_b32 v49, a8
	v_accvgpr_read_b32 v96, a9
	v_accvgpr_read_b32 v155, a196
	v_mul_f32_e32 v35, v155, v100
	v_accvgpr_read_b32 v155, a196
	v_mul_f32_e32 v34, v155, v116
	v_exp_f32_e32 v98, v35
	v_exp_f32_e32 v97, v34
	v_cvt_pk_bf16_f32 v34, v36, v37
	v_cvt_pk_bf16_f32 v35, v52, v53
	v_add_f32_e32 v37, 1.0, v98
	v_add_f32_e32 v36, 1.0, v97
	v_rcp_f32_e32 v37, v37
	v_rcp_f32_e32 v36, v36
	v_lshlrev_b32_e32 v53, 16, v35
	v_lshlrev_b32_e32 v52, 16, v34
	v_fmac_f32_e32 v49, v36, v52
	v_fmac_f32_e32 v96, v37, v53
	v_mul_f32_e32 v36, v96, v96
	v_fmac_f32_e32 v36, v49, v49
	global_store_dword v[50:51], v49, off
	global_store_dword v[50:51], v96, off offset:128
	v_add_f32_dpp v36, v36, v36 quad_perm:[1,0,3,2] row_mask:0xf bank_mask:0xf bound_ctrl:1
	s_nop 1
	v_add_f32_dpp v36, v36, v36 quad_perm:[2,3,0,1] row_mask:0xf bank_mask:0xf bound_ctrl:1
	s_nop 1
	v_add_f32_dpp v36, v36, v36 row_half_mirror row_mask:0xf bank_mask:0xf bound_ctrl:1
	s_nop 1
	v_add_f32_dpp v36, v36, v36 row_mirror row_mask:0xf bank_mask:0xf bound_ctrl:1
	ds_bpermute_b32 v37, v237, v36
	s_and_saveexec_b64 s[8:9], s[4:5]
	s_cbranch_execz .LBB0_1598
	s_waitcnt lgkmcnt(0)
	v_add_f32_e32 v36, v36, v37
	v_lshl_add_u64 v[32:33], v[32:33], 2, s[92:93]
	global_atomic_add_f32 v[32:33], v36, off
.LBB0_1598:
	s_or_b64 exec, exec, s[8:9]
	v_or_b32_e32 v32, v48, v148
	v_ashrrev_i32_e32 v33, 31, v32
	s_waitcnt lgkmcnt(0)
	v_lshlrev_b64 v[36:37], 12, v[32:33]
	v_lshl_add_u64 v[36:37], s[78:79], 0, v[36:37]
	v_lshl_add_u64 v[36:37], v[36:37], 0, v[130:131]
	v_accvgpr_read_b32 v49, a10
	v_accvgpr_read_b32 v50, a11
	v_accvgpr_read_b32 v155, a197
	v_mul_f32_e32 v52, v155, v101
	v_accvgpr_read_b32 v155, a197
	v_mul_f32_e32 v51, v155, v117
	v_exp_f32_e32 v52, v52
	v_exp_f32_e32 v51, v51
	v_and_b32_e32 v35, 0xffff0000, v35
	v_and_b32_e32 v34, 0xffff0000, v34
	v_add_f32_e32 v52, 1.0, v52
	v_add_f32_e32 v51, 1.0, v51
	v_rcp_f32_e32 v52, v52
	v_rcp_f32_e32 v51, v51
	v_fmac_f32_e32 v50, v52, v35
	v_fmac_f32_e32 v49, v51, v34
	v_mul_f32_e32 v34, v50, v50
	v_fmac_f32_e32 v34, v49, v49
	global_store_dword v[36:37], v49, off
	global_store_dword v[36:37], v50, off offset:128
	v_add_f32_dpp v34, v34, v34 quad_perm:[1,0,3,2] row_mask:0xf bank_mask:0xf bound_ctrl:1
	s_nop 1
	v_add_f32_dpp v34, v34, v34 quad_perm:[2,3,0,1] row_mask:0xf bank_mask:0xf bound_ctrl:1
	s_nop 1
	v_add_f32_dpp v34, v34, v34 row_half_mirror row_mask:0xf bank_mask:0xf bound_ctrl:1
	s_nop 1
	v_add_f32_dpp v34, v34, v34 row_mirror row_mask:0xf bank_mask:0xf bound_ctrl:1
	ds_bpermute_b32 v35, v237, v34
	s_and_saveexec_b64 s[8:9], s[4:5]
	s_cbranch_execz .LBB0_1600
	s_waitcnt lgkmcnt(0)
	v_add_f32_e32 v34, v34, v35
	v_lshl_add_u64 v[32:33], v[32:33], 2, s[92:93]
	global_atomic_add_f32 v[32:33], v34, off
.LBB0_1600:
	s_or_b64 exec, exec, s[8:9]
	v_or_b32_e32 v32, v48, v149
	v_ashrrev_i32_e32 v33, 31, v32
	s_waitcnt lgkmcnt(0)
	v_lshlrev_b64 v[34:35], 12, v[32:33]
	v_lshl_add_u64 v[34:35], s[78:79], 0, v[34:35]
	v_lshl_add_u64 v[50:51], v[34:35], 0, v[130:131]
	v_accvgpr_read_b32 v49, a12
	v_accvgpr_read_b32 v52, a13
	v_accvgpr_read_b32 v155, a198
	v_mul_f32_e32 v35, v155, v102
	v_accvgpr_read_b32 v155, a198
	v_mul_f32_e32 v34, v155, v118
	v_exp_f32_e32 v37, v35
	v_exp_f32_e32 v36, v34
	v_cvt_pk_bf16_f32 v35, v54, v55
	v_cvt_pk_bf16_f32 v34, v38, v39
	v_add_f32_e32 v37, 1.0, v37
	v_add_f32_e32 v36, 1.0, v36
	v_rcp_f32_e32 v37, v37
	v_rcp_f32_e32 v36, v36
	v_lshlrev_b32_e32 v39, 16, v35
	v_lshlrev_b32_e32 v38, 16, v34
	v_fmac_f32_e32 v49, v36, v38
	v_fmac_f32_e32 v52, v37, v39
	v_mul_f32_e32 v36, v52, v52
	v_fmac_f32_e32 v36, v49, v49
	global_store_dword v[50:51], v49, off
	global_store_dword v[50:51], v52, off offset:128
	v_add_f32_dpp v36, v36, v36 quad_perm:[1,0,3,2] row_mask:0xf bank_mask:0xf bound_ctrl:1
	s_nop 1
	v_add_f32_dpp v36, v36, v36 quad_perm:[2,3,0,1] row_mask:0xf bank_mask:0xf bound_ctrl:1
	s_nop 1
	v_add_f32_dpp v36, v36, v36 row_half_mirror row_mask:0xf bank_mask:0xf bound_ctrl:1
	s_nop 1
	v_add_f32_dpp v36, v36, v36 row_mirror row_mask:0xf bank_mask:0xf bound_ctrl:1
	ds_bpermute_b32 v37, v237, v36
	s_and_saveexec_b64 s[8:9], s[4:5]
	s_cbranch_execz .LBB0_1602
	s_waitcnt lgkmcnt(0)
	v_add_f32_e32 v36, v36, v37
	v_lshl_add_u64 v[32:33], v[32:33], 2, s[92:93]
	global_atomic_add_f32 v[32:33], v36, off
.LBB0_1602:
	s_or_b64 exec, exec, s[8:9]
	v_or_b32_e32 v32, v48, v150
	v_ashrrev_i32_e32 v33, 31, v32
	s_waitcnt lgkmcnt(0)
	v_lshlrev_b64 v[36:37], 12, v[32:33]
	v_lshl_add_u64 v[36:37], s[78:79], 0, v[36:37]
	v_lshl_add_u64 v[36:37], v[36:37], 0, v[130:131]
	v_accvgpr_read_b32 v38, a14
	v_accvgpr_read_b32 v39, a15
	v_accvgpr_read_b32 v155, a199
	v_mul_f32_e32 v50, v155, v103
	v_accvgpr_read_b32 v155, a199
	v_mul_f32_e32 v49, v155, v119
	v_exp_f32_e32 v50, v50
	v_exp_f32_e32 v49, v49
	v_and_b32_e32 v35, 0xffff0000, v35
	v_and_b32_e32 v34, 0xffff0000, v34
	v_add_f32_e32 v50, 1.0, v50
	v_add_f32_e32 v49, 1.0, v49
	v_rcp_f32_e32 v50, v50
	v_rcp_f32_e32 v49, v49
	v_fmac_f32_e32 v39, v50, v35
	v_fmac_f32_e32 v38, v49, v34
	v_mul_f32_e32 v34, v39, v39
	v_fmac_f32_e32 v34, v38, v38
	global_store_dword v[36:37], v38, off
	global_store_dword v[36:37], v39, off offset:128
	v_add_f32_dpp v34, v34, v34 quad_perm:[1,0,3,2] row_mask:0xf bank_mask:0xf bound_ctrl:1
	s_nop 1
	v_add_f32_dpp v34, v34, v34 quad_perm:[2,3,0,1] row_mask:0xf bank_mask:0xf bound_ctrl:1
	s_nop 1
	v_add_f32_dpp v34, v34, v34 row_half_mirror row_mask:0xf bank_mask:0xf bound_ctrl:1
	s_nop 1
	v_add_f32_dpp v34, v34, v34 row_mirror row_mask:0xf bank_mask:0xf bound_ctrl:1
	ds_bpermute_b32 v35, v237, v34
	s_and_saveexec_b64 s[8:9], s[4:5]
	s_cbranch_execz .LBB0_1604
	s_waitcnt lgkmcnt(0)
	v_add_f32_e32 v34, v34, v35
	v_lshl_add_u64 v[32:33], v[32:33], 2, s[92:93]
	global_atomic_add_f32 v[32:33], v34, off
; __device__ __forceinline__ float bflo(unsigned u) { return __uint_as_float(u << 16); }
; __device__ __forceinline__ float bfhi(unsigned u) { return __uint_as_float(u & 0xffff0000u); }
; __device__ __forceinline__ float sum32(float v) { v = dpp_row_sum16(v); v += __shfl_xor(v, 16); return v; }
; __device__ __forceinline__ float sigmoidf_(float x) { return __builtin_amdgcn_rcpf(1.f + __expf(-x)); }
; __device__ __forceinline__ int rowmap(int e, int lane) { return (e & 3) + 8 * (e >> 2) + 4 * (lane >> 5); }
; __device__ __forceinline__ void phase6(const Params& p, char* smem) {
;     ...
;     for (int i = 0; i < 2; i++)
; #pragma unroll
;       for (int e = 0; e < 16; e++) {
;         const int row = m0 + wm * 64 + i * 32 + rowmap(e, lane);
;         float sq = 0.f;
; #pragma unroll
;         for (int j = 0; j < 2; j++) {
;           const int col = n0 + wn * 64 + j * 32 + (lane & 31);
;           float* xp = X + (size_t)row * 1024 + col;
;           float v = *xp + ((e & 1) ? bfhi(pe[i][j][e >> 1]) : bflo(pe[i][j][e >> 1])) * sigmoidf_(acc1[i][j][e]);
;           *xp = v;
;           sq += v * v;
;         }
;         sq = sum32(sq);
;         if ((lane & 31) == 0) atomicAdd(&SSQ3[row], sq);
;       }
.LBB0_1604:
	s_or_b64 exec, exec, s[8:9]
	v_or_b32_e32 v32, v48, v151
	v_ashrrev_i32_e32 v33, 31, v32
	s_waitcnt lgkmcnt(0)
	v_lshlrev_b64 v[34:35], 12, v[32:33]
	v_lshl_add_u64 v[34:35], s[78:79], 0, v[34:35]
	v_lshl_add_u64 v[38:39], v[34:35], 0, v[130:131]
	v_accvgpr_read_b32 v49, a16
	v_accvgpr_read_b32 v50, a17
	v_accvgpr_read_b32 v155, a200
	v_mul_f32_e32 v35, v155, v104
	v_accvgpr_read_b32 v155, a200
	v_mul_f32_e32 v34, v155, v120
	v_exp_f32_e32 v37, v35
	v_exp_f32_e32 v36, v34
	v_cvt_pk_bf16_f32 v35, v56, v57
	v_cvt_pk_bf16_f32 v34, v40, v41
	v_add_f32_e32 v37, 1.0, v37
	v_add_f32_e32 v36, 1.0, v36
	v_rcp_f32_e32 v37, v37
	v_rcp_f32_e32 v36, v36
	v_lshlrev_b32_e32 v41, 16, v35
	v_lshlrev_b32_e32 v40, 16, v34
	v_fmac_f32_e32 v49, v36, v40
	v_fmac_f32_e32 v50, v37, v41
	v_mul_f32_e32 v36, v50, v50
	v_fmac_f32_e32 v36, v49, v49
	global_store_dword v[38:39], v49, off
	global_store_dword v[38:39], v50, off offset:128
	v_add_f32_dpp v36, v36, v36 quad_perm:[1,0,3,2] row_mask:0xf bank_mask:0xf bound_ctrl:1
	s_nop 1
	v_add_f32_dpp v36, v36, v36 quad_perm:[2,3,0,1] row_mask:0xf bank_mask:0xf bound_ctrl:1
	s_nop 1
	v_add_f32_dpp v36, v36, v36 row_half_mirror row_mask:0xf bank_mask:0xf bound_ctrl:1
	s_nop 1
	v_add_f32_dpp v36, v36, v36 row_mirror row_mask:0xf bank_mask:0xf bound_ctrl:1
	ds_bpermute_b32 v37, v237, v36
	s_and_saveexec_b64 s[8:9], s[4:5]
	s_cbranch_execz .LBB0_1606
	s_waitcnt lgkmcnt(0)
	v_add_f32_e32 v36, v36, v37
	v_lshl_add_u64 v[32:33], v[32:33], 2, s[92:93]
	global_atomic_add_f32 v[32:33], v36, off
.LBB0_1606:
	s_or_b64 exec, exec, s[8:9]
	v_or_b32_e32 v32, v48, v152
	v_ashrrev_i32_e32 v33, 31, v32
	s_waitcnt lgkmcnt(0)
	v_lshlrev_b64 v[36:37], 12, v[32:33]
	v_lshl_add_u64 v[36:37], s[78:79], 0, v[36:37]
	v_lshl_add_u64 v[36:37], v[36:37], 0, v[130:131]
	v_accvgpr_read_b32 v38, a18
	v_accvgpr_read_b32 v39, a19
	v_accvgpr_read_b32 v155, a201
	v_mul_f32_e32 v41, v155, v105
	v_accvgpr_read_b32 v155, a201
	v_mul_f32_e32 v40, v155, v121
	v_exp_f32_e32 v41, v41
	v_exp_f32_e32 v40, v40
	v_and_b32_e32 v35, 0xffff0000, v35
	v_and_b32_e32 v34, 0xffff0000, v34
	v_add_f32_e32 v41, 1.0, v41
	v_add_f32_e32 v40, 1.0, v40
	v_rcp_f32_e32 v41, v41
	v_rcp_f32_e32 v40, v40
	v_fmac_f32_e32 v39, v41, v35
	v_fmac_f32_e32 v38, v40, v34
	v_mul_f32_e32 v34, v39, v39
	v_fmac_f32_e32 v34, v38, v38
	global_store_dword v[36:37], v38, off
	global_store_dword v[36:37], v39, off offset:128
	v_add_f32_dpp v34, v34, v34 quad_perm:[1,0,3,2] row_mask:0xf bank_mask:0xf bound_ctrl:1
	s_nop 1
	v_add_f32_dpp v34, v34, v34 quad_perm:[2,3,0,1] row_mask:0xf bank_mask:0xf bound_ctrl:1
	s_nop 1
	v_add_f32_dpp v34, v34, v34 row_half_mirror row_mask:0xf bank_mask:0xf bound_ctrl:1
	s_nop 1
	v_add_f32_dpp v34, v34, v34 row_mirror row_mask:0xf bank_mask:0xf bound_ctrl:1
	ds_bpermute_b32 v35, v237, v34
	s_and_saveexec_b64 s[8:9], s[4:5]
	s_cbranch_execz .LBB0_1608
	s_waitcnt lgkmcnt(0)
	v_add_f32_e32 v34, v34, v35
	v_lshl_add_u64 v[32:33], v[32:33], 2, s[92:93]
	global_atomic_add_f32 v[32:33], v34, off
.LBB0_1608:
	s_or_b64 exec, exec, s[8:9]
	v_or_b32_e32 v32, v48, v99
	v_ashrrev_i32_e32 v33, 31, v32
	s_waitcnt lgkmcnt(0)
	v_lshlrev_b64 v[34:35], 12, v[32:33]
	v_lshl_add_u64 v[34:35], s[78:79], 0, v[34:35]
	v_lshl_add_u64 v[38:39], v[34:35], 0, v[130:131]
	v_accvgpr_read_b32 v40, a20
	v_accvgpr_read_b32 v41, a21
	v_accvgpr_read_b32 v155, a202
	v_mul_f32_e32 v35, v155, v106
	v_accvgpr_read_b32 v155, a202
	v_mul_f32_e32 v34, v155, v122
	v_exp_f32_e32 v37, v35
	v_exp_f32_e32 v36, v34
	v_cvt_pk_bf16_f32 v35, v58, v59
	v_cvt_pk_bf16_f32 v34, v42, v43
	v_add_f32_e32 v37, 1.0, v37
	v_add_f32_e32 v36, 1.0, v36
	v_rcp_f32_e32 v37, v37
	v_rcp_f32_e32 v36, v36
	v_lshlrev_b32_e32 v43, 16, v35
	v_lshlrev_b32_e32 v42, 16, v34
	v_fmac_f32_e32 v40, v36, v42
	v_fmac_f32_e32 v41, v37, v43
	v_mul_f32_e32 v36, v41, v41
	v_fmac_f32_e32 v36, v40, v40
	global_store_dword v[38:39], v40, off
	global_store_dword v[38:39], v41, off offset:128
	v_add_f32_dpp v36, v36, v36 quad_perm:[1,0,3,2] row_mask:0xf bank_mask:0xf bound_ctrl:1
	s_nop 1
	v_add_f32_dpp v36, v36, v36 quad_perm:[2,3,0,1] row_mask:0xf bank_mask:0xf bound_ctrl:1
	s_nop 1
	v_add_f32_dpp v36, v36, v36 row_half_mirror row_mask:0xf bank_mask:0xf bound_ctrl:1
	s_nop 1
	v_add_f32_dpp v36, v36, v36 row_mirror row_mask:0xf bank_mask:0xf bound_ctrl:1
	ds_bpermute_b32 v37, v237, v36
	s_and_saveexec_b64 s[8:9], s[4:5]
	s_cbranch_execz .LBB0_1610
	s_waitcnt lgkmcnt(0)
	v_add_f32_e32 v36, v36, v37
	v_lshl_add_u64 v[32:33], v[32:33], 2, s[92:93]
	global_atomic_add_f32 v[32:33], v36, off
.LBB0_1610:
	s_or_b64 exec, exec, s[8:9]
	v_or_b32_e32 v32, v48, v112
	v_ashrrev_i32_e32 v33, 31, v32
	s_waitcnt lgkmcnt(0)
	v_lshlrev_b64 v[36:37], 12, v[32:33]
	v_lshl_add_u64 v[36:37], s[78:79], 0, v[36:37]
	v_lshl_add_u64 v[36:37], v[36:37], 0, v[130:131]
	v_accvgpr_read_b32 v38, a22
	v_accvgpr_read_b32 v39, a23
	v_accvgpr_read_b32 v155, a203
	v_mul_f32_e32 v41, v155, v107
	v_accvgpr_read_b32 v155, a203
	v_mul_f32_e32 v40, v155, v123
	v_exp_f32_e32 v41, v41
	v_exp_f32_e32 v40, v40
	v_and_b32_e32 v35, 0xffff0000, v35
	v_and_b32_e32 v34, 0xffff0000, v34
	v_add_f32_e32 v41, 1.0, v41
	v_add_f32_e32 v40, 1.0, v40
	v_rcp_f32_e32 v41, v41
	v_rcp_f32_e32 v40, v40
	v_fmac_f32_e32 v39, v41, v35
	v_fmac_f32_e32 v38, v40, v34
	v_mul_f32_e32 v34, v39, v39
	v_fmac_f32_e32 v34, v38, v38
	global_store_dword v[36:37], v38, off
	global_store_dword v[36:37], v39, off offset:128
	v_add_f32_dpp v34, v34, v34 quad_perm:[1,0,3,2] row_mask:0xf bank_mask:0xf bound_ctrl:1
	s_nop 1
	v_add_f32_dpp v34, v34, v34 quad_perm:[2,3,0,1] row_mask:0xf bank_mask:0xf bound_ctrl:1
	s_nop 1
	v_add_f32_dpp v34, v34, v34 row_half_mirror row_mask:0xf bank_mask:0xf bound_ctrl:1
	s_nop 1
	v_add_f32_dpp v34, v34, v34 row_mirror row_mask:0xf bank_mask:0xf bound_ctrl:1
	ds_bpermute_b32 v35, v237, v34
	s_and_saveexec_b64 s[8:9], s[4:5]
	s_cbranch_execz .LBB0_1612
	s_waitcnt lgkmcnt(0)
	v_add_f32_e32 v34, v34, v35
	v_lshl_add_u64 v[32:33], v[32:33], 2, s[92:93]
	global_atomic_add_f32 v[32:33], v34, off
; __device__ __forceinline__ float bflo(unsigned u) { return __uint_as_float(u << 16); }
; __device__ __forceinline__ float bfhi(unsigned u) { return __uint_as_float(u & 0xffff0000u); }
; __device__ __forceinline__ float sum32(float v) { v = dpp_row_sum16(v); v += __shfl_xor(v, 16); return v; }
; __device__ __forceinline__ float sigmoidf_(float x) { return __builtin_amdgcn_rcpf(1.f + __expf(-x)); }
; __device__ __forceinline__ int rowmap(int e, int lane) { return (e & 3) + 8 * (e >> 2) + 4 * (lane >> 5); }
; __device__ __forceinline__ void phase6(const Params& p, char* smem) {
;     ...
;     for (int i = 0; i < 2; i++)
; #pragma unroll
;       for (int e = 0; e < 16; e++) {
;         const int row = m0 + wm * 64 + i * 32 + rowmap(e, lane);
;         float sq = 0.f;
; #pragma unroll
;         for (int j = 0; j < 2; j++) {
;           const int col = n0 + wn * 64 + j * 32 + (lane & 31);
;           float* xp = X + (size_t)row * 1024 + col;
;           float v = *xp + ((e & 1) ? bfhi(pe[i][j][e >> 1]) : bflo(pe[i][j][e >> 1])) * sigmoidf_(acc1[i][j][e]);
;           *xp = v;
;           sq += v * v;
;         }
;         sq = sum32(sq);
;         if ((lane & 31) == 0) atomicAdd(&SSQ3[row], sq);
;       }
.LBB0_1612:
	s_or_b64 exec, exec, s[8:9]
	v_or_b32_e32 v32, v48, v113
	v_ashrrev_i32_e32 v33, 31, v32
	s_waitcnt lgkmcnt(0)
	v_lshlrev_b64 v[34:35], 12, v[32:33]
	v_lshl_add_u64 v[34:35], s[78:79], 0, v[34:35]
	v_lshl_add_u64 v[38:39], v[34:35], 0, v[130:131]
	v_accvgpr_read_b32 v40, a24
	v_accvgpr_read_b32 v41, a25
	v_accvgpr_read_b32 v155, a204
	v_mul_f32_e32 v35, v155, v108
	v_accvgpr_read_b32 v155, a204
	v_mul_f32_e32 v34, v155, v124
	v_exp_f32_e32 v37, v35
	v_exp_f32_e32 v36, v34
	v_cvt_pk_bf16_f32 v35, v60, v61
	v_cvt_pk_bf16_f32 v34, v44, v45
	v_add_f32_e32 v37, 1.0, v37
	v_add_f32_e32 v36, 1.0, v36
	v_rcp_f32_e32 v37, v37
	v_rcp_f32_e32 v36, v36
	v_lshlrev_b32_e32 v43, 16, v35
	v_lshlrev_b32_e32 v42, 16, v34
	v_fmac_f32_e32 v40, v36, v42
	v_fmac_f32_e32 v41, v37, v43
	v_mul_f32_e32 v36, v41, v41
	v_fmac_f32_e32 v36, v40, v40
	global_store_dword v[38:39], v40, off
	global_store_dword v[38:39], v41, off offset:128
	v_add_f32_dpp v36, v36, v36 quad_perm:[1,0,3,2] row_mask:0xf bank_mask:0xf bound_ctrl:1
	s_nop 1
	v_add_f32_dpp v36, v36, v36 quad_perm:[2,3,0,1] row_mask:0xf bank_mask:0xf bound_ctrl:1
	s_nop 1
	v_add_f32_dpp v36, v36, v36 row_half_mirror row_mask:0xf bank_mask:0xf bound_ctrl:1
	s_nop 1
	v_add_f32_dpp v36, v36, v36 row_mirror row_mask:0xf bank_mask:0xf bound_ctrl:1
	ds_bpermute_b32 v37, v237, v36
	s_and_saveexec_b64 s[8:9], s[4:5]
	s_cbranch_execz .LBB0_1614
	s_waitcnt lgkmcnt(0)
	v_add_f32_e32 v36, v36, v37
	v_lshl_add_u64 v[32:33], v[32:33], 2, s[92:93]
	global_atomic_add_f32 v[32:33], v36, off
.LBB0_1614:
	s_or_b64 exec, exec, s[8:9]
	v_or_b32_e32 v32, v48, v114
	v_ashrrev_i32_e32 v33, 31, v32
	s_waitcnt lgkmcnt(0)
	v_lshlrev_b64 v[36:37], 12, v[32:33]
	v_lshl_add_u64 v[36:37], s[78:79], 0, v[36:37]
	v_lshl_add_u64 v[36:37], v[36:37], 0, v[130:131]
	v_accvgpr_read_b32 v38, a26
	v_accvgpr_read_b32 v39, a27
	v_accvgpr_read_b32 v155, a205
	v_mul_f32_e32 v41, v155, v109
	v_accvgpr_read_b32 v155, a205
	v_mul_f32_e32 v40, v155, v125
	v_exp_f32_e32 v41, v41
	v_exp_f32_e32 v40, v40
	v_and_b32_e32 v35, 0xffff0000, v35
	v_and_b32_e32 v34, 0xffff0000, v34
	v_add_f32_e32 v41, 1.0, v41
	v_add_f32_e32 v40, 1.0, v40
	v_rcp_f32_e32 v41, v41
	v_rcp_f32_e32 v40, v40
	v_fmac_f32_e32 v39, v41, v35
	v_fmac_f32_e32 v38, v40, v34
	v_mul_f32_e32 v34, v39, v39
	v_fmac_f32_e32 v34, v38, v38
	global_store_dword v[36:37], v38, off
	global_store_dword v[36:37], v39, off offset:128
	v_add_f32_dpp v34, v34, v34 quad_perm:[1,0,3,2] row_mask:0xf bank_mask:0xf bound_ctrl:1
	s_nop 1
	v_add_f32_dpp v34, v34, v34 quad_perm:[2,3,0,1] row_mask:0xf bank_mask:0xf bound_ctrl:1
	s_nop 1
	v_add_f32_dpp v34, v34, v34 row_half_mirror row_mask:0xf bank_mask:0xf bound_ctrl:1
	s_nop 1
	v_add_f32_dpp v34, v34, v34 row_mirror row_mask:0xf bank_mask:0xf bound_ctrl:1
	ds_bpermute_b32 v35, v237, v34
	s_and_saveexec_b64 s[8:9], s[4:5]
	s_cbranch_execz .LBB0_1616
	s_waitcnt lgkmcnt(0)
	v_add_f32_e32 v34, v34, v35
	v_lshl_add_u64 v[32:33], v[32:33], 2, s[92:93]
	global_atomic_add_f32 v[32:33], v34, off
.LBB0_1616:
	s_or_b64 exec, exec, s[8:9]
	v_or_b32_e32 v32, v48, v115
	v_ashrrev_i32_e32 v33, 31, v32
	s_waitcnt lgkmcnt(0)
	v_lshlrev_b64 v[34:35], 12, v[32:33]
	v_lshl_add_u64 v[34:35], s[78:79], 0, v[34:35]
	v_lshl_add_u64 v[38:39], v[34:35], 0, v[130:131]
	v_accvgpr_read_b32 v40, a28
	v_accvgpr_read_b32 v41, a29
	v_accvgpr_read_b32 v155, a206
	v_mul_f32_e32 v35, v155, v110
	v_accvgpr_read_b32 v155, a206
	v_mul_f32_e32 v34, v155, v126
	v_exp_f32_e32 v37, v35
	v_exp_f32_e32 v36, v34
	v_cvt_pk_bf16_f32 v35, v62, v63
	v_cvt_pk_bf16_f32 v34, v46, v47
	v_add_f32_e32 v37, 1.0, v37
	v_add_f32_e32 v36, 1.0, v36
	v_rcp_f32_e32 v37, v37
	v_rcp_f32_e32 v36, v36
	v_lshlrev_b32_e32 v43, 16, v35
	v_lshlrev_b32_e32 v42, 16, v34
	v_fmac_f32_e32 v40, v36, v42
	v_fmac_f32_e32 v41, v37, v43
	v_mul_f32_e32 v36, v41, v41
	v_fmac_f32_e32 v36, v40, v40
	global_store_dword v[38:39], v40, off
	global_store_dword v[38:39], v41, off offset:128
	v_add_f32_dpp v36, v36, v36 quad_perm:[1,0,3,2] row_mask:0xf bank_mask:0xf bound_ctrl:1
	s_nop 1
	v_add_f32_dpp v36, v36, v36 quad_perm:[2,3,0,1] row_mask:0xf bank_mask:0xf bound_ctrl:1
	s_nop 1
	v_add_f32_dpp v36, v36, v36 row_half_mirror row_mask:0xf bank_mask:0xf bound_ctrl:1
	s_nop 1
	v_add_f32_dpp v36, v36, v36 row_mirror row_mask:0xf bank_mask:0xf bound_ctrl:1
	ds_bpermute_b32 v37, v237, v36
	s_and_saveexec_b64 s[8:9], s[4:5]
	s_cbranch_execz .LBB0_1618
	s_waitcnt lgkmcnt(0)
	v_add_f32_e32 v36, v36, v37
	v_lshl_add_u64 v[32:33], v[32:33], 2, s[92:93]
	global_atomic_add_f32 v[32:33], v36, off
.LBB0_1618:
	s_or_b64 exec, exec, s[8:9]
	v_or_b32_e32 v32, v48, v153
	v_ashrrev_i32_e32 v33, 31, v32
	s_waitcnt lgkmcnt(0)
	v_lshlrev_b64 v[36:37], 12, v[32:33]
	v_lshl_add_u64 v[36:37], s[78:79], 0, v[36:37]
	v_lshl_add_u64 v[36:37], v[36:37], 0, v[130:131]
	v_accvgpr_read_b32 v38, a30
	v_accvgpr_read_b32 v39, a31
	v_accvgpr_read_b32 v155, a207
	v_mul_f32_e32 v41, v155, v111
	v_accvgpr_read_b32 v155, a207
	v_mul_f32_e32 v40, v155, v127
	v_exp_f32_e32 v41, v41
	v_exp_f32_e32 v40, v40
	v_and_b32_e32 v35, 0xffff0000, v35
	v_and_b32_e32 v34, 0xffff0000, v34
	v_add_f32_e32 v41, 1.0, v41
	v_add_f32_e32 v40, 1.0, v40
	v_rcp_f32_e32 v41, v41
	v_rcp_f32_e32 v40, v40
	v_fmac_f32_e32 v39, v41, v35
	v_fmac_f32_e32 v38, v40, v34
	v_mul_f32_e32 v34, v39, v39
	v_fmac_f32_e32 v34, v38, v38
	global_store_dword v[36:37], v38, off
	global_store_dword v[36:37], v39, off offset:128
	v_add_f32_dpp v34, v34, v34 quad_perm:[1,0,3,2] row_mask:0xf bank_mask:0xf bound_ctrl:1
	s_nop 1
	v_add_f32_dpp v34, v34, v34 quad_perm:[2,3,0,1] row_mask:0xf bank_mask:0xf bound_ctrl:1
	s_nop 1
	v_add_f32_dpp v34, v34, v34 row_half_mirror row_mask:0xf bank_mask:0xf bound_ctrl:1
	s_nop 1
	v_add_f32_dpp v34, v34, v34 row_mirror row_mask:0xf bank_mask:0xf bound_ctrl:1
	ds_bpermute_b32 v35, v237, v34
	s_and_saveexec_b64 s[8:9], s[4:5]
	s_cbranch_execz .LBB0_1620
	s_waitcnt lgkmcnt(0)
	v_add_f32_e32 v34, v34, v35
	v_lshl_add_u64 v[32:33], v[32:33], 2, s[92:93]
	global_atomic_add_f32 v[32:33], v34, off
; __device__ __forceinline__ float bflo(unsigned u) { return __uint_as_float(u << 16); }
; __device__ __forceinline__ float bfhi(unsigned u) { return __uint_as_float(u & 0xffff0000u); }
; __device__ __forceinline__ float sum32(float v) { v = dpp_row_sum16(v); v += __shfl_xor(v, 16); return v; }
; __device__ __forceinline__ float sigmoidf_(float x) { return __builtin_amdgcn_rcpf(1.f + __expf(-x)); }
; __device__ __forceinline__ int rowmap(int e, int lane) { return (e & 3) + 8 * (e >> 2) + 4 * (lane >> 5); }
; __device__ __forceinline__ void phase6(const Params& p, char* smem) {
;     ...
;     for (int i = 0; i < 2; i++)
; #pragma unroll
;       for (int e = 0; e < 16; e++) {
;         const int row = m0 + wm * 64 + i * 32 + rowmap(e, lane);
;         float sq = 0.f;
; #pragma unroll
;         for (int j = 0; j < 2; j++) {
;           const int col = n0 + wn * 64 + j * 32 + (lane & 31);
;           float* xp = X + (size_t)row * 1024 + col;
;           float v = *xp + ((e & 1) ? bfhi(pe[i][j][e >> 1]) : bflo(pe[i][j][e >> 1])) * sigmoidf_(acc1[i][j][e]);
;           *xp = v;
;           sq += v * v;
;         }
;         sq = sum32(sq);
;         if ((lane & 31) == 0) atomicAdd(&SSQ3[row], sq);
;       }
.LBB0_1620:
	s_or_b64 exec, exec, s[8:9]
	v_or_b32_e32 v34, 32, v48
	v_or_b32_e32 v32, v34, v236
	v_ashrrev_i32_e32 v33, 31, v32
	v_lshlrev_b64 v[36:37], 12, v[32:33]
	v_lshl_add_u64 v[36:37], s[78:79], 0, v[36:37]
	v_lshl_add_u64 v[36:37], v[36:37], 0, v[130:131]
	v_accvgpr_read_b32 v38, a32
	v_accvgpr_read_b32 v39, a33
	v_accvgpr_read_b32 v155, a208
	v_mul_f32_e32 v40, v155, v64
	s_waitcnt lgkmcnt(0)
	v_accvgpr_read_b32 v155, a208
	v_mul_f32_e32 v35, v155, v80
	v_exp_f32_e32 v40, v40
	v_exp_f32_e32 v41, v35
	v_cvt_pk_bf16_f32 v35, v0, v1
	v_cvt_pk_bf16_f32 v16, v16, v17
	v_add_f32_e32 v1, 1.0, v40
	v_add_f32_e32 v0, 1.0, v41
	v_rcp_f32_e32 v1, v1
	v_rcp_f32_e32 v0, v0
	v_lshlrev_b32_e32 v40, 16, v16
	v_lshlrev_b32_e32 v17, 16, v35
	v_fmac_f32_e32 v38, v0, v17
	v_fmac_f32_e32 v39, v1, v40
	v_mul_f32_e32 v0, v39, v39
	v_fmac_f32_e32 v0, v38, v38
	global_store_dword v[36:37], v38, off
	global_store_dword v[36:37], v39, off offset:128
	v_add_f32_dpp v0, v0, v0 quad_perm:[1,0,3,2] row_mask:0xf bank_mask:0xf bound_ctrl:1
	s_nop 1
	v_add_f32_dpp v0, v0, v0 quad_perm:[2,3,0,1] row_mask:0xf bank_mask:0xf bound_ctrl:1
	s_nop 1
	v_add_f32_dpp v0, v0, v0 row_half_mirror row_mask:0xf bank_mask:0xf bound_ctrl:1
	s_nop 1
	v_add_f32_dpp v0, v0, v0 row_mirror row_mask:0xf bank_mask:0xf bound_ctrl:1
	ds_bpermute_b32 v1, v237, v0
	s_and_saveexec_b64 s[8:9], s[4:5]
	s_cbranch_execz .LBB0_1622
	s_waitcnt lgkmcnt(0)
	v_add_f32_e32 v17, v0, v1
	v_lshl_add_u64 v[0:1], v[32:33], 2, s[92:93]
	global_atomic_add_f32 v[0:1], v17, off
.LBB0_1622:
	s_or_b64 exec, exec, s[8:9]
	v_or_b32_e32 v0, v34, v135
	s_waitcnt lgkmcnt(0)
	v_ashrrev_i32_e32 v1, 31, v0
	v_lshlrev_b64 v[32:33], 12, v[0:1]
	v_lshl_add_u64 v[32:33], s[78:79], 0, v[32:33]
	v_lshl_add_u64 v[32:33], v[32:33], 0, v[130:131]
	v_accvgpr_read_b32 v36, a34
	v_accvgpr_read_b32 v37, a35
	v_accvgpr_read_b32 v155, a209
	v_mul_f32_e32 v38, v155, v65
	v_accvgpr_read_b32 v155, a209
	v_mul_f32_e32 v17, v155, v81
	v_exp_f32_e32 v38, v38
	v_exp_f32_e32 v17, v17
	v_and_b32_e32 v16, 0xffff0000, v16
	v_and_b32_e32 v35, 0xffff0000, v35
	v_add_f32_e32 v38, 1.0, v38
	v_add_f32_e32 v17, 1.0, v17
	v_rcp_f32_e32 v38, v38
	v_rcp_f32_e32 v17, v17
	v_fmac_f32_e32 v37, v38, v16
	v_fmac_f32_e32 v36, v17, v35
	v_mul_f32_e32 v16, v37, v37
	v_fmac_f32_e32 v16, v36, v36
	global_store_dword v[32:33], v36, off
	global_store_dword v[32:33], v37, off offset:128
	v_add_f32_dpp v16, v16, v16 quad_perm:[1,0,3,2] row_mask:0xf bank_mask:0xf bound_ctrl:1
	s_nop 1
	v_add_f32_dpp v16, v16, v16 quad_perm:[2,3,0,1] row_mask:0xf bank_mask:0xf bound_ctrl:1
	s_nop 1
	v_add_f32_dpp v16, v16, v16 row_half_mirror row_mask:0xf bank_mask:0xf bound_ctrl:1
	s_nop 1
	v_add_f32_dpp v16, v16, v16 row_mirror row_mask:0xf bank_mask:0xf bound_ctrl:1
	ds_bpermute_b32 v17, v237, v16
	s_and_saveexec_b64 s[8:9], s[4:5]
	s_cbranch_execz .LBB0_1624
	s_waitcnt lgkmcnt(0)
	v_add_f32_e32 v16, v16, v17
	v_lshl_add_u64 v[0:1], v[0:1], 2, s[92:93]
	global_atomic_add_f32 v[0:1], v16, off
.LBB0_1624:
	s_or_b64 exec, exec, s[8:9]
	v_or_b32_e32 v0, v34, v132
	v_ashrrev_i32_e32 v1, 31, v0
	s_waitcnt lgkmcnt(0)
	v_lshlrev_b64 v[16:17], 12, v[0:1]
	v_lshl_add_u64 v[16:17], s[78:79], 0, v[16:17]
	v_lshl_add_u64 v[32:33], v[16:17], 0, v[130:131]
	v_accvgpr_read_b32 v35, a36
	v_accvgpr_read_b32 v36, a37
	v_accvgpr_read_b32 v155, a210
	v_mul_f32_e32 v17, v155, v66
	v_accvgpr_read_b32 v155, a210
	v_mul_f32_e32 v16, v155, v82
	v_exp_f32_e32 v17, v17
	v_exp_f32_e32 v16, v16
	v_cvt_pk_bf16_f32 v2, v2, v3
	v_cvt_pk_bf16_f32 v3, v18, v19
	v_add_f32_e32 v17, 1.0, v17
	v_add_f32_e32 v16, 1.0, v16
	v_rcp_f32_e32 v17, v17
	v_rcp_f32_e32 v16, v16
	v_lshlrev_b32_e32 v19, 16, v3
	v_lshlrev_b32_e32 v18, 16, v2
	v_fmac_f32_e32 v35, v16, v18
	v_fmac_f32_e32 v36, v17, v19
	v_mul_f32_e32 v16, v36, v36
	v_fmac_f32_e32 v16, v35, v35
	global_store_dword v[32:33], v35, off
	global_store_dword v[32:33], v36, off offset:128
	v_add_f32_dpp v16, v16, v16 quad_perm:[1,0,3,2] row_mask:0xf bank_mask:0xf bound_ctrl:1
	s_nop 1
	v_add_f32_dpp v16, v16, v16 quad_perm:[2,3,0,1] row_mask:0xf bank_mask:0xf bound_ctrl:1
	s_nop 1
	v_add_f32_dpp v16, v16, v16 row_half_mirror row_mask:0xf bank_mask:0xf bound_ctrl:1
	s_nop 1
	v_add_f32_dpp v16, v16, v16 row_mirror row_mask:0xf bank_mask:0xf bound_ctrl:1
	ds_bpermute_b32 v17, v237, v16
	s_and_saveexec_b64 s[8:9], s[4:5]
	s_cbranch_execz .LBB0_1626
	s_waitcnt lgkmcnt(0)
	v_add_f32_e32 v16, v16, v17
	v_lshl_add_u64 v[0:1], v[0:1], 2, s[92:93]
	global_atomic_add_f32 v[0:1], v16, off
.LBB0_1626:
	s_or_b64 exec, exec, s[8:9]
	v_or_b32_e32 v0, v34, v133
	v_ashrrev_i32_e32 v1, 31, v0
	s_waitcnt lgkmcnt(0)
	v_lshlrev_b64 v[16:17], 12, v[0:1]
	v_lshl_add_u64 v[16:17], s[78:79], 0, v[16:17]
	v_lshl_add_u64 v[16:17], v[16:17], 0, v[130:131]
	v_accvgpr_read_b32 v18, a38
	v_accvgpr_read_b32 v19, a39
	v_accvgpr_read_b32 v155, a211
	v_mul_f32_e32 v33, v155, v67
	v_accvgpr_read_b32 v155, a211
	v_mul_f32_e32 v32, v155, v83
	v_exp_f32_e32 v33, v33
	v_exp_f32_e32 v32, v32
	v_and_b32_e32 v3, 0xffff0000, v3
	v_and_b32_e32 v2, 0xffff0000, v2
	v_add_f32_e32 v33, 1.0, v33
	v_add_f32_e32 v32, 1.0, v32
	v_rcp_f32_e32 v33, v33
	v_rcp_f32_e32 v32, v32
	v_fmac_f32_e32 v19, v33, v3
	v_fmac_f32_e32 v18, v32, v2
	v_mul_f32_e32 v2, v19, v19
	v_fmac_f32_e32 v2, v18, v18
	global_store_dword v[16:17], v18, off
	global_store_dword v[16:17], v19, off offset:128
	v_add_f32_dpp v2, v2, v2 quad_perm:[1,0,3,2] row_mask:0xf bank_mask:0xf bound_ctrl:1
	s_nop 1
	v_add_f32_dpp v2, v2, v2 quad_perm:[2,3,0,1] row_mask:0xf bank_mask:0xf bound_ctrl:1
	s_nop 1
	v_add_f32_dpp v2, v2, v2 row_half_mirror row_mask:0xf bank_mask:0xf bound_ctrl:1
	s_nop 1
	v_add_f32_dpp v2, v2, v2 row_mirror row_mask:0xf bank_mask:0xf bound_ctrl:1
	ds_bpermute_b32 v3, v237, v2
	s_and_saveexec_b64 s[8:9], s[4:5]
	s_cbranch_execz .LBB0_1628
	s_waitcnt lgkmcnt(0)
	v_add_f32_e32 v2, v2, v3
	v_lshl_add_u64 v[0:1], v[0:1], 2, s[92:93]
	global_atomic_add_f32 v[0:1], v2, off
; __device__ __forceinline__ float bflo(unsigned u) { return __uint_as_float(u << 16); }
; __device__ __forceinline__ float bfhi(unsigned u) { return __uint_as_float(u & 0xffff0000u); }
; __device__ __forceinline__ float sum32(float v) { v = dpp_row_sum16(v); v += __shfl_xor(v, 16); return v; }
; __device__ __forceinline__ float sigmoidf_(float x) { return __builtin_amdgcn_rcpf(1.f + __expf(-x)); }
; __device__ __forceinline__ int rowmap(int e, int lane) { return (e & 3) + 8 * (e >> 2) + 4 * (lane >> 5); }
; __device__ __forceinline__ void phase6(const Params& p, char* smem) {
;     ...
;     for (int i = 0; i < 2; i++)
; #pragma unroll
;       for (int e = 0; e < 16; e++) {
;         const int row = m0 + wm * 64 + i * 32 + rowmap(e, lane);
;         float sq = 0.f;
; #pragma unroll
;         for (int j = 0; j < 2; j++) {
;           const int col = n0 + wn * 64 + j * 32 + (lane & 31);
;           float* xp = X + (size_t)row * 1024 + col;
;           float v = *xp + ((e & 1) ? bfhi(pe[i][j][e >> 1]) : bflo(pe[i][j][e >> 1])) * sigmoidf_(acc1[i][j][e]);
;           *xp = v;
;           sq += v * v;
;         }
;         sq = sum32(sq);
;         if ((lane & 31) == 0) atomicAdd(&SSQ3[row], sq);
;       }
.LBB0_1628:
	s_or_b64 exec, exec, s[8:9]
	v_or_b32_e32 v0, v34, v134
	v_ashrrev_i32_e32 v1, 31, v0
	s_waitcnt lgkmcnt(0)
	v_lshlrev_b64 v[2:3], 12, v[0:1]
	v_lshl_add_u64 v[2:3], s[78:79], 0, v[2:3]
	v_lshl_add_u64 v[16:17], v[2:3], 0, v[130:131]
	v_accvgpr_read_b32 v18, a40
	v_accvgpr_read_b32 v19, a41
	v_accvgpr_read_b32 v155, a212
	v_mul_f32_e32 v3, v155, v68
	v_accvgpr_read_b32 v155, a212
	v_mul_f32_e32 v2, v155, v84
	v_exp_f32_e32 v33, v3
	v_exp_f32_e32 v32, v2
	v_cvt_pk_bf16_f32 v2, v4, v5
	v_cvt_pk_bf16_f32 v3, v20, v21
	v_add_f32_e32 v5, 1.0, v33
	v_add_f32_e32 v4, 1.0, v32
	v_rcp_f32_e32 v5, v5
	v_rcp_f32_e32 v4, v4
	v_lshlrev_b32_e32 v21, 16, v3
	v_lshlrev_b32_e32 v20, 16, v2
	v_fmac_f32_e32 v18, v4, v20
	v_fmac_f32_e32 v19, v5, v21
	v_mul_f32_e32 v4, v19, v19
	v_fmac_f32_e32 v4, v18, v18
	global_store_dword v[16:17], v18, off
	global_store_dword v[16:17], v19, off offset:128
	v_add_f32_dpp v4, v4, v4 quad_perm:[1,0,3,2] row_mask:0xf bank_mask:0xf bound_ctrl:1
	s_nop 1
	v_add_f32_dpp v4, v4, v4 quad_perm:[2,3,0,1] row_mask:0xf bank_mask:0xf bound_ctrl:1
	s_nop 1
	v_add_f32_dpp v4, v4, v4 row_half_mirror row_mask:0xf bank_mask:0xf bound_ctrl:1
	s_nop 1
	v_add_f32_dpp v4, v4, v4 row_mirror row_mask:0xf bank_mask:0xf bound_ctrl:1
	ds_bpermute_b32 v5, v237, v4
	s_and_saveexec_b64 s[8:9], s[4:5]
	s_cbranch_execz .LBB0_1630
	s_waitcnt lgkmcnt(0)
	v_add_f32_e32 v4, v4, v5
	v_lshl_add_u64 v[0:1], v[0:1], 2, s[92:93]
	global_atomic_add_f32 v[0:1], v4, off
.LBB0_1630:
	s_or_b64 exec, exec, s[8:9]
	v_or_b32_e32 v0, v34, v148
	v_ashrrev_i32_e32 v1, 31, v0
	s_waitcnt lgkmcnt(0)
	v_lshlrev_b64 v[4:5], 12, v[0:1]
	v_lshl_add_u64 v[4:5], s[78:79], 0, v[4:5]
	v_lshl_add_u64 v[4:5], v[4:5], 0, v[130:131]
	v_accvgpr_read_b32 v16, a42
	v_accvgpr_read_b32 v17, a43
	v_accvgpr_read_b32 v155, a213
	v_mul_f32_e32 v19, v155, v69
	v_accvgpr_read_b32 v155, a213
	v_mul_f32_e32 v18, v155, v85
	v_exp_f32_e32 v19, v19
	v_exp_f32_e32 v18, v18
	v_and_b32_e32 v3, 0xffff0000, v3
	v_and_b32_e32 v2, 0xffff0000, v2
	v_add_f32_e32 v19, 1.0, v19
	v_add_f32_e32 v18, 1.0, v18
	v_rcp_f32_e32 v19, v19
	v_rcp_f32_e32 v18, v18
	v_fmac_f32_e32 v17, v19, v3
	v_fmac_f32_e32 v16, v18, v2
	v_mul_f32_e32 v2, v17, v17
	v_fmac_f32_e32 v2, v16, v16
	global_store_dword v[4:5], v16, off
	global_store_dword v[4:5], v17, off offset:128
	v_add_f32_dpp v2, v2, v2 quad_perm:[1,0,3,2] row_mask:0xf bank_mask:0xf bound_ctrl:1
	s_nop 1
	v_add_f32_dpp v2, v2, v2 quad_perm:[2,3,0,1] row_mask:0xf bank_mask:0xf bound_ctrl:1
	s_nop 1
	v_add_f32_dpp v2, v2, v2 row_half_mirror row_mask:0xf bank_mask:0xf bound_ctrl:1
	s_nop 1
	v_add_f32_dpp v2, v2, v2 row_mirror row_mask:0xf bank_mask:0xf bound_ctrl:1
	ds_bpermute_b32 v3, v237, v2
	s_and_saveexec_b64 s[8:9], s[4:5]
	s_cbranch_execz .LBB0_1632
	s_waitcnt lgkmcnt(0)
	v_add_f32_e32 v2, v2, v3
	v_lshl_add_u64 v[0:1], v[0:1], 2, s[92:93]
	global_atomic_add_f32 v[0:1], v2, off
.LBB0_1632:
	s_or_b64 exec, exec, s[8:9]
	v_or_b32_e32 v0, v34, v149
	v_ashrrev_i32_e32 v1, 31, v0
	s_waitcnt lgkmcnt(0)
	v_lshlrev_b64 v[2:3], 12, v[0:1]
	v_lshl_add_u64 v[2:3], s[78:79], 0, v[2:3]
	v_lshl_add_u64 v[16:17], v[2:3], 0, v[130:131]
	v_accvgpr_read_b32 v18, a44
	v_accvgpr_read_b32 v19, a45
	v_accvgpr_read_b32 v155, a214
	v_mul_f32_e32 v3, v155, v70
	v_accvgpr_read_b32 v155, a214
	v_mul_f32_e32 v2, v155, v86
	v_exp_f32_e32 v5, v3
	v_exp_f32_e32 v4, v2
	v_cvt_pk_bf16_f32 v3, v22, v23
	v_cvt_pk_bf16_f32 v2, v6, v7
	v_add_f32_e32 v5, 1.0, v5
	v_add_f32_e32 v4, 1.0, v4
	v_rcp_f32_e32 v5, v5
	v_rcp_f32_e32 v4, v4
	v_lshlrev_b32_e32 v7, 16, v3
	v_lshlrev_b32_e32 v6, 16, v2
	v_fmac_f32_e32 v18, v4, v6
	v_fmac_f32_e32 v19, v5, v7
	v_mul_f32_e32 v4, v19, v19
	v_fmac_f32_e32 v4, v18, v18
	global_store_dword v[16:17], v18, off
	global_store_dword v[16:17], v19, off offset:128
	v_add_f32_dpp v4, v4, v4 quad_perm:[1,0,3,2] row_mask:0xf bank_mask:0xf bound_ctrl:1
	s_nop 1
	v_add_f32_dpp v4, v4, v4 quad_perm:[2,3,0,1] row_mask:0xf bank_mask:0xf bound_ctrl:1
	s_nop 1
	v_add_f32_dpp v4, v4, v4 row_half_mirror row_mask:0xf bank_mask:0xf bound_ctrl:1
	s_nop 1
	v_add_f32_dpp v4, v4, v4 row_mirror row_mask:0xf bank_mask:0xf bound_ctrl:1
	ds_bpermute_b32 v5, v237, v4
	s_and_saveexec_b64 s[8:9], s[4:5]
	s_cbranch_execz .LBB0_1634
	s_waitcnt lgkmcnt(0)
	v_add_f32_e32 v4, v4, v5
	v_lshl_add_u64 v[0:1], v[0:1], 2, s[92:93]
	global_atomic_add_f32 v[0:1], v4, off
.LBB0_1634:
	s_or_b64 exec, exec, s[8:9]
	v_or_b32_e32 v0, v34, v150
	v_ashrrev_i32_e32 v1, 31, v0
	s_waitcnt lgkmcnt(0)
	v_lshlrev_b64 v[4:5], 12, v[0:1]
	v_lshl_add_u64 v[4:5], s[78:79], 0, v[4:5]
	v_lshl_add_u64 v[4:5], v[4:5], 0, v[130:131]
	v_accvgpr_read_b32 v6, a46
	v_accvgpr_read_b32 v7, a47
	v_accvgpr_read_b32 v155, a215
	v_mul_f32_e32 v17, v155, v71
	v_accvgpr_read_b32 v155, a215
	v_mul_f32_e32 v16, v155, v87
	v_exp_f32_e32 v17, v17
	v_exp_f32_e32 v16, v16
	v_and_b32_e32 v3, 0xffff0000, v3
	v_and_b32_e32 v2, 0xffff0000, v2
	v_add_f32_e32 v17, 1.0, v17
	v_add_f32_e32 v16, 1.0, v16
	v_rcp_f32_e32 v17, v17
	v_rcp_f32_e32 v16, v16
	v_fmac_f32_e32 v7, v17, v3
	v_fmac_f32_e32 v6, v16, v2
	v_mul_f32_e32 v2, v7, v7
	v_fmac_f32_e32 v2, v6, v6
	global_store_dword v[4:5], v6, off
	global_store_dword v[4:5], v7, off offset:128
	v_add_f32_dpp v2, v2, v2 quad_perm:[1,0,3,2] row_mask:0xf bank_mask:0xf bound_ctrl:1
	s_nop 1
	v_add_f32_dpp v2, v2, v2 quad_perm:[2,3,0,1] row_mask:0xf bank_mask:0xf bound_ctrl:1
	s_nop 1
	v_add_f32_dpp v2, v2, v2 row_half_mirror row_mask:0xf bank_mask:0xf bound_ctrl:1
	s_nop 1
	v_add_f32_dpp v2, v2, v2 row_mirror row_mask:0xf bank_mask:0xf bound_ctrl:1
	ds_bpermute_b32 v3, v237, v2
	s_and_saveexec_b64 s[8:9], s[4:5]
	s_cbranch_execz .LBB0_1636
	s_waitcnt lgkmcnt(0)
	v_add_f32_e32 v2, v2, v3
	v_lshl_add_u64 v[0:1], v[0:1], 2, s[92:93]
	global_atomic_add_f32 v[0:1], v2, off
; __device__ __forceinline__ float bflo(unsigned u) { return __uint_as_float(u << 16); }
; __device__ __forceinline__ float bfhi(unsigned u) { return __uint_as_float(u & 0xffff0000u); }
; __device__ __forceinline__ float sum32(float v) { v = dpp_row_sum16(v); v += __shfl_xor(v, 16); return v; }
; __device__ __forceinline__ float sigmoidf_(float x) { return __builtin_amdgcn_rcpf(1.f + __expf(-x)); }
; __device__ __forceinline__ int rowmap(int e, int lane) { return (e & 3) + 8 * (e >> 2) + 4 * (lane >> 5); }
; __device__ __forceinline__ void phase6(const Params& p, char* smem) {
;     ...
;     for (int i = 0; i < 2; i++)
; #pragma unroll
;       for (int e = 0; e < 16; e++) {
;         const int row = m0 + wm * 64 + i * 32 + rowmap(e, lane);
;         float sq = 0.f;
; #pragma unroll
;         for (int j = 0; j < 2; j++) {
;           const int col = n0 + wn * 64 + j * 32 + (lane & 31);
;           float* xp = X + (size_t)row * 1024 + col;
;           float v = *xp + ((e & 1) ? bfhi(pe[i][j][e >> 1]) : bflo(pe[i][j][e >> 1])) * sigmoidf_(acc1[i][j][e]);
;           *xp = v;
;           sq += v * v;
;         }
;         sq = sum32(sq);
;         if ((lane & 31) == 0) atomicAdd(&SSQ3[row], sq);
;       }
.LBB0_1636:
	s_or_b64 exec, exec, s[8:9]
	v_or_b32_e32 v0, v34, v151
	v_ashrrev_i32_e32 v1, 31, v0
	s_waitcnt lgkmcnt(0)
	v_lshlrev_b64 v[2:3], 12, v[0:1]
	v_lshl_add_u64 v[2:3], s[78:79], 0, v[2:3]
	v_lshl_add_u64 v[6:7], v[2:3], 0, v[130:131]
	v_accvgpr_read_b32 v16, a48
	v_accvgpr_read_b32 v17, a49
	v_accvgpr_read_b32 v155, a216
	v_mul_f32_e32 v3, v155, v72
	v_accvgpr_read_b32 v155, a216
	v_mul_f32_e32 v2, v155, v88
	v_exp_f32_e32 v5, v3
	v_exp_f32_e32 v4, v2
	v_cvt_pk_bf16_f32 v3, v24, v25
	v_cvt_pk_bf16_f32 v2, v8, v9
	v_add_f32_e32 v5, 1.0, v5
	v_add_f32_e32 v4, 1.0, v4
	v_rcp_f32_e32 v5, v5
	v_rcp_f32_e32 v4, v4
	v_lshlrev_b32_e32 v9, 16, v3
	v_lshlrev_b32_e32 v8, 16, v2
	v_fmac_f32_e32 v16, v4, v8
	v_fmac_f32_e32 v17, v5, v9
	v_mul_f32_e32 v4, v17, v17
	v_fmac_f32_e32 v4, v16, v16
	global_store_dword v[6:7], v16, off
	global_store_dword v[6:7], v17, off offset:128
	v_add_f32_dpp v4, v4, v4 quad_perm:[1,0,3,2] row_mask:0xf bank_mask:0xf bound_ctrl:1
	s_nop 1
	v_add_f32_dpp v4, v4, v4 quad_perm:[2,3,0,1] row_mask:0xf bank_mask:0xf bound_ctrl:1
	s_nop 1
	v_add_f32_dpp v4, v4, v4 row_half_mirror row_mask:0xf bank_mask:0xf bound_ctrl:1
	s_nop 1
	v_add_f32_dpp v4, v4, v4 row_mirror row_mask:0xf bank_mask:0xf bound_ctrl:1
	ds_bpermute_b32 v5, v237, v4
	s_and_saveexec_b64 s[8:9], s[4:5]
	s_cbranch_execz .LBB0_1638
	s_waitcnt lgkmcnt(0)
	v_add_f32_e32 v4, v4, v5
	v_lshl_add_u64 v[0:1], v[0:1], 2, s[92:93]
	global_atomic_add_f32 v[0:1], v4, off
.LBB0_1638:
	s_or_b64 exec, exec, s[8:9]
	v_or_b32_e32 v0, v34, v152
	v_ashrrev_i32_e32 v1, 31, v0
	s_waitcnt lgkmcnt(0)
	v_lshlrev_b64 v[4:5], 12, v[0:1]
	v_lshl_add_u64 v[4:5], s[78:79], 0, v[4:5]
	v_lshl_add_u64 v[4:5], v[4:5], 0, v[130:131]
	v_accvgpr_read_b32 v6, a50
	v_accvgpr_read_b32 v7, a51
	v_accvgpr_read_b32 v155, a217
	v_mul_f32_e32 v9, v155, v73
	v_accvgpr_read_b32 v155, a217
	v_mul_f32_e32 v8, v155, v89
	v_exp_f32_e32 v9, v9
	v_exp_f32_e32 v8, v8
	v_and_b32_e32 v3, 0xffff0000, v3
	v_and_b32_e32 v2, 0xffff0000, v2
	v_add_f32_e32 v9, 1.0, v9
	v_add_f32_e32 v8, 1.0, v8
	v_rcp_f32_e32 v9, v9
	v_rcp_f32_e32 v8, v8
	v_fmac_f32_e32 v7, v9, v3
	v_fmac_f32_e32 v6, v8, v2
	v_mul_f32_e32 v2, v7, v7
	v_fmac_f32_e32 v2, v6, v6
	global_store_dword v[4:5], v6, off
	global_store_dword v[4:5], v7, off offset:128
	v_add_f32_dpp v2, v2, v2 quad_perm:[1,0,3,2] row_mask:0xf bank_mask:0xf bound_ctrl:1
	s_nop 1
	v_add_f32_dpp v2, v2, v2 quad_perm:[2,3,0,1] row_mask:0xf bank_mask:0xf bound_ctrl:1
	s_nop 1
	v_add_f32_dpp v2, v2, v2 row_half_mirror row_mask:0xf bank_mask:0xf bound_ctrl:1
	s_nop 1
	v_add_f32_dpp v2, v2, v2 row_mirror row_mask:0xf bank_mask:0xf bound_ctrl:1
	ds_bpermute_b32 v3, v237, v2
	s_and_saveexec_b64 s[8:9], s[4:5]
	s_cbranch_execz .LBB0_1640
	s_waitcnt lgkmcnt(0)
	v_add_f32_e32 v2, v2, v3
	v_lshl_add_u64 v[0:1], v[0:1], 2, s[92:93]
	global_atomic_add_f32 v[0:1], v2, off
.LBB0_1640:
	s_or_b64 exec, exec, s[8:9]
	v_or_b32_e32 v0, v34, v99
	v_ashrrev_i32_e32 v1, 31, v0
	s_waitcnt lgkmcnt(0)
	v_lshlrev_b64 v[2:3], 12, v[0:1]
	v_lshl_add_u64 v[2:3], s[78:79], 0, v[2:3]
	v_lshl_add_u64 v[6:7], v[2:3], 0, v[130:131]
	v_accvgpr_read_b32 v8, a52
	v_accvgpr_read_b32 v9, a53
	v_accvgpr_read_b32 v155, a218
	v_mul_f32_e32 v3, v155, v74
	v_accvgpr_read_b32 v155, a218
	v_mul_f32_e32 v2, v155, v90
	v_exp_f32_e32 v5, v3
	v_exp_f32_e32 v4, v2
	v_cvt_pk_bf16_f32 v3, v26, v27
	v_cvt_pk_bf16_f32 v2, v10, v11
	v_add_f32_e32 v5, 1.0, v5
	v_add_f32_e32 v4, 1.0, v4
	v_rcp_f32_e32 v5, v5
	v_rcp_f32_e32 v4, v4
	v_lshlrev_b32_e32 v11, 16, v3
	v_lshlrev_b32_e32 v10, 16, v2
	v_fmac_f32_e32 v8, v4, v10
	v_fmac_f32_e32 v9, v5, v11
	v_mul_f32_e32 v4, v9, v9
	v_fmac_f32_e32 v4, v8, v8
	global_store_dword v[6:7], v8, off
	global_store_dword v[6:7], v9, off offset:128
	v_add_f32_dpp v4, v4, v4 quad_perm:[1,0,3,2] row_mask:0xf bank_mask:0xf bound_ctrl:1
	s_nop 1
	v_add_f32_dpp v4, v4, v4 quad_perm:[2,3,0,1] row_mask:0xf bank_mask:0xf bound_ctrl:1
	s_nop 1
	v_add_f32_dpp v4, v4, v4 row_half_mirror row_mask:0xf bank_mask:0xf bound_ctrl:1
	s_nop 1
	v_add_f32_dpp v4, v4, v4 row_mirror row_mask:0xf bank_mask:0xf bound_ctrl:1
	ds_bpermute_b32 v5, v237, v4
	s_and_saveexec_b64 s[8:9], s[4:5]
	s_cbranch_execz .LBB0_1642
	s_waitcnt lgkmcnt(0)
	v_add_f32_e32 v4, v4, v5
	v_lshl_add_u64 v[0:1], v[0:1], 2, s[92:93]
	global_atomic_add_f32 v[0:1], v4, off
.LBB0_1642:
	s_or_b64 exec, exec, s[8:9]
	v_or_b32_e32 v0, v34, v112
	v_ashrrev_i32_e32 v1, 31, v0
	s_waitcnt lgkmcnt(0)
	v_lshlrev_b64 v[4:5], 12, v[0:1]
	v_lshl_add_u64 v[4:5], s[78:79], 0, v[4:5]
	v_lshl_add_u64 v[4:5], v[4:5], 0, v[130:131]
	v_accvgpr_read_b32 v6, a54
	v_accvgpr_read_b32 v7, a55
	v_accvgpr_read_b32 v155, a219
	v_mul_f32_e32 v9, v155, v75
	v_accvgpr_read_b32 v155, a219
	v_mul_f32_e32 v8, v155, v91
	v_exp_f32_e32 v9, v9
	v_exp_f32_e32 v8, v8
	v_and_b32_e32 v3, 0xffff0000, v3
	v_and_b32_e32 v2, 0xffff0000, v2
	v_add_f32_e32 v9, 1.0, v9
	v_add_f32_e32 v8, 1.0, v8
	v_rcp_f32_e32 v9, v9
	v_rcp_f32_e32 v8, v8
	v_fmac_f32_e32 v7, v9, v3
	v_fmac_f32_e32 v6, v8, v2
	v_mul_f32_e32 v2, v7, v7
	v_fmac_f32_e32 v2, v6, v6
	global_store_dword v[4:5], v6, off
	global_store_dword v[4:5], v7, off offset:128
	v_add_f32_dpp v2, v2, v2 quad_perm:[1,0,3,2] row_mask:0xf bank_mask:0xf bound_ctrl:1
	s_nop 1
	v_add_f32_dpp v2, v2, v2 quad_perm:[2,3,0,1] row_mask:0xf bank_mask:0xf bound_ctrl:1
	s_nop 1
	v_add_f32_dpp v2, v2, v2 row_half_mirror row_mask:0xf bank_mask:0xf bound_ctrl:1
	s_nop 1
	v_add_f32_dpp v2, v2, v2 row_mirror row_mask:0xf bank_mask:0xf bound_ctrl:1
	ds_bpermute_b32 v3, v237, v2
	s_and_saveexec_b64 s[8:9], s[4:5]
	s_cbranch_execz .LBB0_1644
	s_waitcnt lgkmcnt(0)
	v_add_f32_e32 v2, v2, v3
	v_lshl_add_u64 v[0:1], v[0:1], 2, s[92:93]
	global_atomic_add_f32 v[0:1], v2, off
; __device__ __forceinline__ float bflo(unsigned u) { return __uint_as_float(u << 16); }
; __device__ __forceinline__ float bfhi(unsigned u) { return __uint_as_float(u & 0xffff0000u); }
; __device__ __forceinline__ float sum32(float v) { v = dpp_row_sum16(v); v += __shfl_xor(v, 16); return v; }
; __device__ __forceinline__ float sigmoidf_(float x) { return __builtin_amdgcn_rcpf(1.f + __expf(-x)); }
; __device__ __forceinline__ int rowmap(int e, int lane) { return (e & 3) + 8 * (e >> 2) + 4 * (lane >> 5); }
; __device__ __forceinline__ void phase6(const Params& p, char* smem) {
;     ...
;     for (int i = 0; i < 2; i++)
; #pragma unroll
;       for (int e = 0; e < 16; e++) {
;         const int row = m0 + wm * 64 + i * 32 + rowmap(e, lane);
;         float sq = 0.f;
; #pragma unroll
;         for (int j = 0; j < 2; j++) {
;           const int col = n0 + wn * 64 + j * 32 + (lane & 31);
;           float* xp = X + (size_t)row * 1024 + col;
;           float v = *xp + ((e & 1) ? bfhi(pe[i][j][e >> 1]) : bflo(pe[i][j][e >> 1])) * sigmoidf_(acc1[i][j][e]);
;           *xp = v;
;           sq += v * v;
;         }
;         sq = sum32(sq);
;         if ((lane & 31) == 0) atomicAdd(&SSQ3[row], sq);
;       }
.LBB0_1644:
	s_or_b64 exec, exec, s[8:9]
	v_or_b32_e32 v0, v34, v113
	v_ashrrev_i32_e32 v1, 31, v0
	s_waitcnt lgkmcnt(0)
	v_lshlrev_b64 v[2:3], 12, v[0:1]
	v_lshl_add_u64 v[2:3], s[78:79], 0, v[2:3]
	v_lshl_add_u64 v[6:7], v[2:3], 0, v[130:131]
	v_accvgpr_read_b32 v8, a56
	v_accvgpr_read_b32 v9, a57
	v_accvgpr_read_b32 v155, a220
	v_mul_f32_e32 v3, v155, v76
	v_accvgpr_read_b32 v155, a220
	v_mul_f32_e32 v2, v155, v92
	v_exp_f32_e32 v5, v3
	v_exp_f32_e32 v4, v2
	v_cvt_pk_bf16_f32 v3, v28, v29
	v_cvt_pk_bf16_f32 v2, v12, v13
	v_add_f32_e32 v5, 1.0, v5
	v_add_f32_e32 v4, 1.0, v4
	v_rcp_f32_e32 v5, v5
	v_rcp_f32_e32 v4, v4
	v_lshlrev_b32_e32 v11, 16, v3
	v_lshlrev_b32_e32 v10, 16, v2
	v_fmac_f32_e32 v8, v4, v10
	v_fmac_f32_e32 v9, v5, v11
	v_mul_f32_e32 v4, v9, v9
	v_fmac_f32_e32 v4, v8, v8
	global_store_dword v[6:7], v8, off
	global_store_dword v[6:7], v9, off offset:128
	v_add_f32_dpp v4, v4, v4 quad_perm:[1,0,3,2] row_mask:0xf bank_mask:0xf bound_ctrl:1
	s_nop 1
	v_add_f32_dpp v4, v4, v4 quad_perm:[2,3,0,1] row_mask:0xf bank_mask:0xf bound_ctrl:1
	s_nop 1
	v_add_f32_dpp v4, v4, v4 row_half_mirror row_mask:0xf bank_mask:0xf bound_ctrl:1
	s_nop 1
	v_add_f32_dpp v4, v4, v4 row_mirror row_mask:0xf bank_mask:0xf bound_ctrl:1
	ds_bpermute_b32 v5, v237, v4
	s_and_saveexec_b64 s[8:9], s[4:5]
	s_cbranch_execz .LBB0_1646
	s_waitcnt lgkmcnt(0)
	v_add_f32_e32 v4, v4, v5
	v_lshl_add_u64 v[0:1], v[0:1], 2, s[92:93]
	global_atomic_add_f32 v[0:1], v4, off
.LBB0_1646:
	s_or_b64 exec, exec, s[8:9]
	v_or_b32_e32 v0, v34, v114
	v_ashrrev_i32_e32 v1, 31, v0
	s_waitcnt lgkmcnt(0)
	v_lshlrev_b64 v[4:5], 12, v[0:1]
	v_lshl_add_u64 v[4:5], s[78:79], 0, v[4:5]
	v_lshl_add_u64 v[4:5], v[4:5], 0, v[130:131]
	v_accvgpr_read_b32 v6, a58
	v_accvgpr_read_b32 v7, a59
	v_accvgpr_read_b32 v155, a221
	v_mul_f32_e32 v9, v155, v77
	v_accvgpr_read_b32 v155, a221
	v_mul_f32_e32 v8, v155, v93
	v_exp_f32_e32 v9, v9
	v_exp_f32_e32 v8, v8
	v_and_b32_e32 v3, 0xffff0000, v3
	v_and_b32_e32 v2, 0xffff0000, v2
	v_add_f32_e32 v9, 1.0, v9
	v_add_f32_e32 v8, 1.0, v8
	v_rcp_f32_e32 v9, v9
	v_rcp_f32_e32 v8, v8
	v_fmac_f32_e32 v7, v9, v3
	v_fmac_f32_e32 v6, v8, v2
	v_mul_f32_e32 v2, v7, v7
	v_fmac_f32_e32 v2, v6, v6
	global_store_dword v[4:5], v6, off
	global_store_dword v[4:5], v7, off offset:128
	v_add_f32_dpp v2, v2, v2 quad_perm:[1,0,3,2] row_mask:0xf bank_mask:0xf bound_ctrl:1
	s_nop 1
	v_add_f32_dpp v2, v2, v2 quad_perm:[2,3,0,1] row_mask:0xf bank_mask:0xf bound_ctrl:1
	s_nop 1
	v_add_f32_dpp v2, v2, v2 row_half_mirror row_mask:0xf bank_mask:0xf bound_ctrl:1
	s_nop 1
	v_add_f32_dpp v2, v2, v2 row_mirror row_mask:0xf bank_mask:0xf bound_ctrl:1
	ds_bpermute_b32 v3, v237, v2
	s_and_saveexec_b64 s[8:9], s[4:5]
	s_cbranch_execz .LBB0_1648
	s_waitcnt lgkmcnt(0)
	v_add_f32_e32 v2, v2, v3
	v_lshl_add_u64 v[0:1], v[0:1], 2, s[92:93]
	global_atomic_add_f32 v[0:1], v2, off
.LBB0_1648:
	s_or_b64 exec, exec, s[8:9]
	v_or_b32_e32 v0, v34, v115
	v_ashrrev_i32_e32 v1, 31, v0
	s_waitcnt lgkmcnt(0)
	v_lshlrev_b64 v[2:3], 12, v[0:1]
	v_lshl_add_u64 v[2:3], s[78:79], 0, v[2:3]
	v_lshl_add_u64 v[6:7], v[2:3], 0, v[130:131]
	v_accvgpr_read_b32 v8, a60
	v_accvgpr_read_b32 v9, a61
	v_accvgpr_read_b32 v155, a222
	v_mul_f32_e32 v3, v155, v78
	v_accvgpr_read_b32 v155, a222
	v_mul_f32_e32 v2, v155, v94
	v_exp_f32_e32 v5, v3
	v_exp_f32_e32 v4, v2
	v_cvt_pk_bf16_f32 v3, v30, v31
	v_cvt_pk_bf16_f32 v2, v14, v15
	v_add_f32_e32 v5, 1.0, v5
	v_add_f32_e32 v4, 1.0, v4
	v_rcp_f32_e32 v5, v5
	v_rcp_f32_e32 v4, v4
	v_lshlrev_b32_e32 v11, 16, v3
	v_lshlrev_b32_e32 v10, 16, v2
	v_fmac_f32_e32 v8, v4, v10
	v_fmac_f32_e32 v9, v5, v11
	v_mul_f32_e32 v4, v9, v9
	v_fmac_f32_e32 v4, v8, v8
	global_store_dword v[6:7], v8, off
	global_store_dword v[6:7], v9, off offset:128
	v_add_f32_dpp v4, v4, v4 quad_perm:[1,0,3,2] row_mask:0xf bank_mask:0xf bound_ctrl:1
	s_nop 1
	v_add_f32_dpp v4, v4, v4 quad_perm:[2,3,0,1] row_mask:0xf bank_mask:0xf bound_ctrl:1
	s_nop 1
	v_add_f32_dpp v4, v4, v4 row_half_mirror row_mask:0xf bank_mask:0xf bound_ctrl:1
	s_nop 1
	v_add_f32_dpp v4, v4, v4 row_mirror row_mask:0xf bank_mask:0xf bound_ctrl:1
	ds_bpermute_b32 v5, v237, v4
	s_and_saveexec_b64 s[8:9], s[4:5]
	s_cbranch_execz .LBB0_1650
	s_waitcnt lgkmcnt(0)
	v_add_f32_e32 v4, v4, v5
	v_lshl_add_u64 v[0:1], v[0:1], 2, s[92:93]
	global_atomic_add_f32 v[0:1], v4, off
.LBB0_1650:
	s_or_b64 exec, exec, s[8:9]
	v_or_b32_e32 v0, v34, v153
	v_ashrrev_i32_e32 v1, 31, v0
	s_waitcnt lgkmcnt(0)
	v_lshlrev_b64 v[4:5], 12, v[0:1]
	v_lshl_add_u64 v[4:5], s[78:79], 0, v[4:5]
	v_lshl_add_u64 v[4:5], v[4:5], 0, v[130:131]
	v_accvgpr_read_b32 v6, a62
	v_accvgpr_read_b32 v7, a63
	v_accvgpr_read_b32 v155, a223
	v_mul_f32_e32 v9, v155, v79
	v_accvgpr_read_b32 v155, a223
	v_mul_f32_e32 v8, v155, v95
	v_exp_f32_e32 v9, v9
	v_exp_f32_e32 v8, v8
	v_and_b32_e32 v3, 0xffff0000, v3
	v_and_b32_e32 v2, 0xffff0000, v2
	v_add_f32_e32 v9, 1.0, v9
	v_add_f32_e32 v8, 1.0, v8
	v_rcp_f32_e32 v9, v9
	v_rcp_f32_e32 v8, v8
	v_fmac_f32_e32 v7, v9, v3
	v_fmac_f32_e32 v6, v8, v2
	v_mul_f32_e32 v2, v7, v7
	v_fmac_f32_e32 v2, v6, v6
	global_store_dword v[4:5], v6, off
	global_store_dword v[4:5], v7, off offset:128
	v_add_f32_dpp v2, v2, v2 quad_perm:[1,0,3,2] row_mask:0xf bank_mask:0xf bound_ctrl:1
	s_nop 1
	v_add_f32_dpp v2, v2, v2 quad_perm:[2,3,0,1] row_mask:0xf bank_mask:0xf bound_ctrl:1
	s_nop 1
	v_add_f32_dpp v2, v2, v2 row_half_mirror row_mask:0xf bank_mask:0xf bound_ctrl:1
	s_nop 1
	v_add_f32_dpp v2, v2, v2 row_mirror row_mask:0xf bank_mask:0xf bound_ctrl:1
	ds_bpermute_b32 v3, v237, v2
	s_and_saveexec_b64 s[8:9], s[4:5]
	s_cbranch_execz .LBB0_1577
	s_waitcnt lgkmcnt(0)
	v_add_f32_e32 v2, v2, v3
	v_lshl_add_u64 v[0:1], v[0:1], 2, s[92:93]
	global_atomic_add_f32 v[0:1], v2, off
	s_branch .LBB0_1577
